# GEMM K-loops: MFMA-block priority raised to 3 instead of 1 at the after-load barrier (priority-level variant of the static raise), on top of v15b
# baseline (speedup 1.0000x reference)
; #define PG8_STAGE(bufoff, gbase, voff) do { _Pragma("unroll") for (int _i = 0; _i < 2; ++_i) \
;         __builtin_amdgcn_global_load_lds((const unsigned*)((const char*)(gbase) + (voff)[_i]), (PG8_LAS unsigned*)(lds + (bufoff) + ldsw + _i * 8192), 16, 0, 0); } while (0)
; #define PG8_LDA(dst, b, h) do { _Pragma("unroll") for (int m = 0; m < 4; ++m) _Pragma("unroll") for (int k = 0; k < 2; ++k) dst[m][k] = *(const PG8_LAS bf16x8*)(lds + PG8_SA(b, h) + aoff + m * 2048 + k * 1024); } while (0)
; #define PG8_LDB(dst, b, h) do { _Pragma("unroll") for (int n = 0; n < 2; ++n) _Pragma("unroll") for (int k = 0; k < 2; ++k) dst[n][k] = *(const PG8_LAS bf16x8*)(lds + PG8_SB(b, h) + boff + n * 2048 + k * 1024); } while (0)
; #define PG8_WAIT_V(n) asm volatile("s_waitcnt vmcnt(" #n ")" ::: "memory")
; #define PG8_WAIT_L(n) asm volatile("s_waitcnt lgkmcnt(" #n ")" ::: "memory")
; #define PG8_BAR __builtin_amdgcn_s_barrier()
; #define PG8_SCHED __builtin_amdgcn_sched_barrier(0)
; template <class Epi, class Sched, bool ALIGN_EPI = false, bool SP2 = false>
; __device__ __forceinline__ void gemm_phase(PG8_LAS unsigned char* lds, const Gemm g, const Sched& S, const Epi& E) {
;     ...
;         const char* nA = has_next ? (const char*)g.A + (size_t)nxt.pm * tstep : cA; const char* nB = has_next ? (const char*)g.Bt + (size_t)nxt.pn * tstep : cB;
;         for (int t = 0; t < nt; t += 2) {
;             const bool last = (t == nt - 2);
;             const char* a1 = cA + (size_t)(t + 1) * kstep;
;             const char* a2 = last ? nA : cA + (size_t)(t + 2) * kstep; const char* b2 = last ? nB : cB + (size_t)(t + 2) * kstep;
;             const char* a3 = a2 + kstep; const char* b3 = b2 + kstep;
;             if (last && has_next) S.a_ready(nxt);
;             if constexpr (SP2) {
;             PG8_LDB(B0, 0, 0); PG8_LDB(B1, 0, 1); PG8_SCHED; PG8_LDA(At, 0, 0); PG8_STAGE(PG8_SA(1, 1), a1 + hstep, voffA);
;             PG8_WAIT_V(8); PG8_WAIT_L(0); PG8_BAR; PG8_MMA(0, 0, At, B0); PG8_MMA(0, 1, At, B1); PG8_BAR; PG8_SCHED;
;             PG8_LDA(At, 0, 1); PG8_STAGE(PG8_SB(0, 0), b2, voffB); PG8_STAGE(PG8_SB(0, 1), b2 + hstep, voffB); PG8_STAGE(PG8_SA(0, 0), a2, voffA);
;             PG8_WAIT_V(8); PG8_WAIT_L(0); PG8_BAR; PG8_MMA(1, 0, At, B0); PG8_MMA(1, 1, At, B1); PG8_BAR; PG8_SCHED;
.LBB0_1166:
	s_ashr_i32 s17, s16, 31
	s_lshl_b64 s[20:21], s[16:17], 20
	s_add_u32 s20, s3, s20
	s_addc_u32 s21, s2, s21
	s_and_b64 s[34:35], s[4:5], exec
	s_cselect_b32 s17, s21, s37
	s_cselect_b32 s30, s20, s36
	s_ashr_i32 s15, s14, 31
	s_lshl_b64 s[34:35], s[14:15], 20
	s_add_u32 s34, s29, s34
	s_addc_u32 s35, s40, s35
	s_and_b64 s[42:43], s[4:5], exec
	s_cselect_b32 s15, s35, s39
	s_cselect_b32 s55, s34, s38
	s_add_u32 s36, s36, 0x80080
	s_addc_u32 s37, s37, 0
	s_add_u32 s56, s38, 0x100
	s_addc_u32 s57, s39, 0
	s_mov_b32 s62, -2
	s_add_u32 s26, s36, 0xfff80080
	s_addc_u32 s38, s37, -1
	s_add_i32 s63, 0, 0x10000
	s_cmp_eq_u32 s62, 28
	s_cselect_b32 s43, s17, s38
	s_cselect_b32 s42, s30, s26
	v_add_u32_e32 v144, s63, v145
	s_cselect_b32 s39, s15, s57
	s_cselect_b32 s38, s55, s56
	s_add_i32 s26, 0, 0x14000
	ds_read_b128 v[154:157], v144
	ds_read_b128 v[158:161], v144 offset:1024
	ds_read_b128 v[162:165], v144 offset:2048
	ds_read_b128 v[166:169], v144 offset:3072
	v_add_u32_e32 v144, s26, v145
	ds_read_b128 v[170:173], v144
	ds_read_b128 v[174:177], v144 offset:1024
	ds_read_b128 v[182:185], v144 offset:2048
	ds_read_b128 v[186:189], v144 offset:3072
	v_lshl_add_u64 v[146:147], s[36:37], 0, v[140:141]
	s_add_i32 m0, s45, 0xc000
	ds_read_b128 v[190:193], v153
	ds_read_b128 v[194:197], v153 offset:1024
	ds_read_b128 v[198:201], v153 offset:2048
	ds_read_b128 v[202:205], v153 offset:3072
	ds_read_b128 v[206:209], v153 offset:4096
	ds_read_b128 v[210:213], v153 offset:5120
	ds_read_b128 v[214:217], v153 offset:6144
	ds_read_b128 v[218:221], v153 offset:7168
	global_load_lds_dwordx4 v[146:147], off
	v_lshl_add_u64 v[146:147], s[36:37], 0, v[142:143]
	s_add_i32 m0, s45, 0xe000
	s_nop 0
	global_load_lds_dwordx4 v[146:147], off
	s_waitcnt vmcnt(8)
	s_waitcnt lgkmcnt(0)
	s_setprio 3
	s_barrier
	v_mfma_f32_16x16x32_bf16 v[80:83], v[154:157], v[190:193], 0
	v_mfma_f32_16x16x32_bf16 v[76:79], v[162:165], v[190:193], 0
	v_mfma_f32_16x16x32_bf16 v[64:67], v[154:157], v[198:201], 0
	v_mfma_f32_16x16x32_bf16 v[60:63], v[162:165], v[198:201], 0
	v_mfma_f32_16x16x32_bf16 v[56:59], v[154:157], v[206:209], 0
	v_mfma_f32_16x16x32_bf16 v[52:55], v[162:165], v[206:209], 0
	v_mfma_f32_16x16x32_bf16 v[44:47], v[154:157], v[214:217], 0
	v_mfma_f32_16x16x32_bf16 v[36:39], v[162:165], v[214:217], 0
	v_mfma_f32_16x16x32_bf16 v[80:83], v[158:161], v[194:197], v[80:83]
	v_mfma_f32_16x16x32_bf16 v[76:79], v[166:169], v[194:197], v[76:79]
	v_mfma_f32_16x16x32_bf16 v[64:67], v[158:161], v[202:205], v[64:67]
	v_mfma_f32_16x16x32_bf16 v[60:63], v[166:169], v[202:205], v[60:63]
	v_mfma_f32_16x16x32_bf16 v[56:59], v[158:161], v[210:213], v[56:59]
	v_mfma_f32_16x16x32_bf16 v[52:55], v[166:169], v[210:213], v[52:55]
	v_mfma_f32_16x16x32_bf16 v[44:47], v[158:161], v[218:221], v[44:47]
	v_mfma_f32_16x16x32_bf16 v[36:39], v[166:169], v[218:221], v[36:39]
	s_setprio 0
	s_setprio 1
	v_mfma_f32_16x16x32_bf16 v[128:131], v[170:173], v[190:193], 0
	v_mfma_f32_16x16x32_bf16 v[124:127], v[182:185], v[190:193], 0
	v_mfma_f32_16x16x32_bf16 v[120:123], v[170:173], v[198:201], 0
	v_mfma_f32_16x16x32_bf16 v[116:119], v[182:185], v[198:201], 0
	v_mfma_f32_16x16x32_bf16 v[112:115], v[170:173], v[206:209], 0
	v_mfma_f32_16x16x32_bf16 v[108:111], v[182:185], v[206:209], 0
	v_mfma_f32_16x16x32_bf16 v[104:107], v[170:173], v[214:217], 0
	v_mfma_f32_16x16x32_bf16 v[100:103], v[182:185], v[214:217], 0
	v_mfma_f32_16x16x32_bf16 v[128:131], v[174:177], v[194:197], v[128:131]
	v_mfma_f32_16x16x32_bf16 v[124:127], v[186:189], v[194:197], v[124:127]
	v_mfma_f32_16x16x32_bf16 v[120:123], v[174:177], v[202:205], v[120:123]
	v_mfma_f32_16x16x32_bf16 v[116:119], v[186:189], v[202:205], v[116:119]
	v_mfma_f32_16x16x32_bf16 v[112:115], v[174:177], v[210:213], v[112:115]
	v_mfma_f32_16x16x32_bf16 v[108:111], v[186:189], v[210:213], v[108:111]
	v_mfma_f32_16x16x32_bf16 v[104:107], v[174:177], v[218:221], v[104:107]
	v_mfma_f32_16x16x32_bf16 v[100:103], v[186:189], v[218:221], v[100:103]
	s_barrier
	s_setprio 0
	s_add_i32 s63, s63, s44
	v_lshl_add_u64 v[146:147], s[38:39], 0, v[2:3]
	s_mov_b32 m0, s63
	ds_read_b128 v[190:193], v153 offset:16384
	ds_read_b128 v[194:197], v153 offset:17408
	ds_read_b128 v[198:201], v153 offset:18432
	ds_read_b128 v[202:205], v153 offset:19456
	ds_read_b128 v[206:209], v153 offset:20480
	ds_read_b128 v[210:213], v153 offset:21504
	ds_read_b128 v[214:217], v153 offset:22528
	ds_read_b128 v[218:221], v153 offset:23552
	global_load_lds_dwordx4 v[146:147], off
	s_add_i32 m0, s63, 0x2000
	s_add_u32 s66, s38, 0x80000
	v_lshl_add_u64 v[150:151], s[38:39], 0, v[132:133]
	s_addc_u32 s67, s39, 0
	s_add_i32 s26, s26, s44
	global_load_lds_dwordx4 v[150:151], off
	v_lshl_add_u64 v[178:179], s[66:67], 0, v[2:3]
	s_mov_b32 m0, s26
	v_lshl_add_u64 v[222:223], s[42:43], 0, v[134:135]
	global_load_lds_dwordx4 v[178:179], off
	v_lshl_add_u64 v[178:179], s[66:67], 0, v[132:133]
	s_add_i32 m0, s26, 0x2000
	s_nop 0
	global_load_lds_dwordx4 v[178:179], off
	v_lshl_add_u64 v[178:179], s[42:43], 0, v[136:137]
	s_mov_b32 m0, s45
	s_nop 0
	global_load_lds_dwordx4 v[178:179], off
	s_mov_b32 m0, s46
	s_nop 0
	global_load_lds_dwordx4 v[222:223], off
	s_waitcnt vmcnt(8)
	s_waitcnt lgkmcnt(0)
	s_setprio 3
	s_barrier
; #define PG8_STAGE(bufoff, gbase, voff) do { _Pragma("unroll") for (int _i = 0; _i < 2; ++_i) \
;         __builtin_amdgcn_global_load_lds((const unsigned*)((const char*)(gbase) + (voff)[_i]), (PG8_LAS unsigned*)(lds + (bufoff) + ldsw + _i * 8192), 16, 0, 0); } while (0)
; #define PG8_LDA(dst, b, h) do { _Pragma("unroll") for (int m = 0; m < 4; ++m) _Pragma("unroll") for (int k = 0; k < 2; ++k) dst[m][k] = *(const PG8_LAS bf16x8*)(lds + PG8_SA(b, h) + aoff + m * 2048 + k * 1024); } while (0)
; #define PG8_LDB(dst, b, h) do { _Pragma("unroll") for (int n = 0; n < 2; ++n) _Pragma("unroll") for (int k = 0; k < 2; ++k) dst[n][k] = *(const PG8_LAS bf16x8*)(lds + PG8_SB(b, h) + boff + n * 2048 + k * 1024); } while (0)
; #define PG8_MMA(ai, bj, At, Bt) do { __builtin_amdgcn_s_setprio(1); _Pragma("unroll") for (int m = 0; m < 4; ++m) _Pragma("unroll") for (int n = 0; n < 2; ++n) _Pragma("unroll") for (int k = 0; k < 2; ++k) \
;         acc[ai][bj][m][n] = __builtin_amdgcn_mfma_f32_16x16x32_bf16(Bt[n][k], At[m][k], acc[ai][bj][m][n], 0, 0, 0); __builtin_amdgcn_s_setprio(0); } while (0)
; #define PG8_WAIT_V(n) asm volatile("s_waitcnt vmcnt(" #n ")" ::: "memory")
; #define PG8_WAIT_L(n) asm volatile("s_waitcnt lgkmcnt(" #n ")" ::: "memory")
; #define PG8_BAR __builtin_amdgcn_s_barrier()
; #define PG8_SCHED __builtin_amdgcn_sched_barrier(0)
; template <class Epi, class Sched, bool ALIGN_EPI = false, bool SP2 = false>
; __device__ __forceinline__ void gemm_phase(PG8_LAS unsigned char* lds, const Gemm g, const Sched& S, const Epi& E) {
;     ...
;             PG8_WAIT_V(8); PG8_WAIT_L(0); PG8_BAR; PG8_MMA(1, 0, At, B0); PG8_MMA(1, 1, At, B1); PG8_BAR; PG8_SCHED;
;             PG8_LDB(B0, 1, 0); PG8_LDB(B1, 1, 1); PG8_SCHED; PG8_LDA(At, 1, 0); PG8_STAGE(PG8_SA(0, 1), a2 + hstep, voffA);
;             PG8_WAIT_V(8); PG8_WAIT_L(0); PG8_BAR; PG8_MMA(0, 0, At, B0); PG8_MMA(0, 1, At, B1); PG8_BAR; PG8_SCHED;
	v_mfma_f32_16x16x32_bf16 v[32:35], v[154:157], v[190:193], 0
	v_mfma_f32_16x16x32_bf16 v[28:31], v[162:165], v[190:193], 0
	v_mfma_f32_16x16x32_bf16 v[24:27], v[154:157], v[198:201], 0
	v_mfma_f32_16x16x32_bf16 v[20:23], v[162:165], v[198:201], 0
	v_mfma_f32_16x16x32_bf16 v[16:19], v[154:157], v[206:209], 0
	v_mfma_f32_16x16x32_bf16 v[12:15], v[162:165], v[206:209], 0
	v_mfma_f32_16x16x32_bf16 v[8:11], v[154:157], v[214:217], 0
	v_mfma_f32_16x16x32_bf16 v[4:7], v[162:165], v[214:217], 0
	v_mfma_f32_16x16x32_bf16 v[32:35], v[158:161], v[194:197], v[32:35]
	v_mfma_f32_16x16x32_bf16 v[28:31], v[166:169], v[194:197], v[28:31]
	v_mfma_f32_16x16x32_bf16 v[24:27], v[158:161], v[202:205], v[24:27]
	v_mfma_f32_16x16x32_bf16 v[20:23], v[166:169], v[202:205], v[20:23]
	v_mfma_f32_16x16x32_bf16 v[16:19], v[158:161], v[210:213], v[16:19]
	v_mfma_f32_16x16x32_bf16 v[12:15], v[166:169], v[210:213], v[12:15]
	v_mfma_f32_16x16x32_bf16 v[8:11], v[158:161], v[218:221], v[8:11]
	v_mfma_f32_16x16x32_bf16 v[4:7], v[166:169], v[218:221], v[4:7]
	s_setprio 0
	s_setprio 1
	v_mfma_f32_16x16x32_bf16 v[96:99], v[170:173], v[190:193], 0
	v_mfma_f32_16x16x32_bf16 v[92:95], v[182:185], v[190:193], 0
	v_mfma_f32_16x16x32_bf16 v[88:91], v[170:173], v[198:201], 0
	v_mfma_f32_16x16x32_bf16 v[84:87], v[182:185], v[198:201], 0
	v_mfma_f32_16x16x32_bf16 v[72:75], v[170:173], v[206:209], 0
	v_mfma_f32_16x16x32_bf16 v[68:71], v[182:185], v[206:209], 0
	v_mfma_f32_16x16x32_bf16 v[48:51], v[170:173], v[214:217], 0
	v_mfma_f32_16x16x32_bf16 v[40:43], v[182:185], v[214:217], 0
	v_mfma_f32_16x16x32_bf16 v[96:99], v[174:177], v[194:197], v[96:99]
	v_mfma_f32_16x16x32_bf16 v[92:95], v[186:189], v[194:197], v[92:95]
	v_mfma_f32_16x16x32_bf16 v[88:91], v[174:177], v[202:205], v[88:91]
	v_mfma_f32_16x16x32_bf16 v[84:87], v[186:189], v[202:205], v[84:87]
	v_mfma_f32_16x16x32_bf16 v[72:75], v[174:177], v[210:213], v[72:75]
	v_mfma_f32_16x16x32_bf16 v[68:71], v[186:189], v[210:213], v[68:71]
	v_mfma_f32_16x16x32_bf16 v[48:51], v[174:177], v[218:221], v[48:51]
	v_mfma_f32_16x16x32_bf16 v[40:43], v[186:189], v[218:221], v[40:43]
	s_barrier
	s_setprio 0
	s_add_i32 s26, 0, 0x18000
	v_add_u32_e32 v144, s26, v145
	s_add_i32 s63, 0, 0x1c000
	ds_read_b128 v[154:157], v144
	ds_read_b128 v[158:161], v144 offset:1024
	ds_read_b128 v[162:165], v144 offset:2048
	ds_read_b128 v[166:169], v144 offset:3072
	v_add_u32_e32 v144, s63, v145
	ds_read_b128 v[170:173], v144
	ds_read_b128 v[174:177], v144 offset:1024
	ds_read_b128 v[182:185], v144 offset:2048
	ds_read_b128 v[186:189], v144 offset:3072
	s_add_u32 s42, s42, 0x80000
	s_addc_u32 s43, s43, 0
	s_mov_b32 m0, s47
	v_lshl_add_u64 v[224:225], s[42:43], 0, v[136:137]
	ds_read_b128 v[190:193], v153 offset:32768
	ds_read_b128 v[194:197], v153 offset:33792
	ds_read_b128 v[198:201], v153 offset:34816
	ds_read_b128 v[202:205], v153 offset:35840
	ds_read_b128 v[206:209], v153 offset:36864
	ds_read_b128 v[210:213], v153 offset:37888
	ds_read_b128 v[214:217], v153 offset:38912
	ds_read_b128 v[218:221], v153 offset:39936
	global_load_lds_dwordx4 v[224:225], off
	v_lshl_add_u64 v[224:225], s[42:43], 0, v[134:135]
	s_mov_b32 m0, s50
	s_nop 0
	global_load_lds_dwordx4 v[224:225], off
	s_waitcnt vmcnt(8)
	s_waitcnt lgkmcnt(0)
	s_setprio 3
	s_barrier
	v_mfma_f32_16x16x32_bf16 v[80:83], v[154:157], v[190:193], v[80:83]
	v_mfma_f32_16x16x32_bf16 v[76:79], v[162:165], v[190:193], v[76:79]
	v_mfma_f32_16x16x32_bf16 v[64:67], v[154:157], v[198:201], v[64:67]
	v_mfma_f32_16x16x32_bf16 v[60:63], v[162:165], v[198:201], v[60:63]
	v_mfma_f32_16x16x32_bf16 v[56:59], v[154:157], v[206:209], v[56:59]
	v_mfma_f32_16x16x32_bf16 v[52:55], v[162:165], v[206:209], v[52:55]
	v_mfma_f32_16x16x32_bf16 v[44:47], v[154:157], v[214:217], v[44:47]
	v_mfma_f32_16x16x32_bf16 v[36:39], v[162:165], v[214:217], v[36:39]
	v_mfma_f32_16x16x32_bf16 v[80:83], v[158:161], v[194:197], v[80:83]
	v_mfma_f32_16x16x32_bf16 v[76:79], v[166:169], v[194:197], v[76:79]
	v_mfma_f32_16x16x32_bf16 v[64:67], v[158:161], v[202:205], v[64:67]
	v_mfma_f32_16x16x32_bf16 v[60:63], v[166:169], v[202:205], v[60:63]
	v_mfma_f32_16x16x32_bf16 v[56:59], v[158:161], v[210:213], v[56:59]
	v_mfma_f32_16x16x32_bf16 v[52:55], v[166:169], v[210:213], v[52:55]
	v_mfma_f32_16x16x32_bf16 v[44:47], v[158:161], v[218:221], v[44:47]
	v_mfma_f32_16x16x32_bf16 v[36:39], v[166:169], v[218:221], v[36:39]
	s_setprio 0
	s_setprio 1
	v_mfma_f32_16x16x32_bf16 v[128:131], v[170:173], v[190:193], v[128:131]
	v_mfma_f32_16x16x32_bf16 v[124:127], v[182:185], v[190:193], v[124:127]
	v_mfma_f32_16x16x32_bf16 v[120:123], v[170:173], v[198:201], v[120:123]
	v_mfma_f32_16x16x32_bf16 v[116:119], v[182:185], v[198:201], v[116:119]
	v_mfma_f32_16x16x32_bf16 v[112:115], v[170:173], v[206:209], v[112:115]
	v_mfma_f32_16x16x32_bf16 v[108:111], v[182:185], v[206:209], v[108:111]
	v_mfma_f32_16x16x32_bf16 v[104:107], v[170:173], v[214:217], v[104:107]
	v_mfma_f32_16x16x32_bf16 v[100:103], v[182:185], v[214:217], v[100:103]
	v_mfma_f32_16x16x32_bf16 v[128:131], v[174:177], v[194:197], v[128:131]
	v_mfma_f32_16x16x32_bf16 v[124:127], v[186:189], v[194:197], v[124:127]
	v_mfma_f32_16x16x32_bf16 v[120:123], v[174:177], v[202:205], v[120:123]
	v_mfma_f32_16x16x32_bf16 v[116:119], v[186:189], v[202:205], v[116:119]
	v_mfma_f32_16x16x32_bf16 v[112:115], v[174:177], v[210:213], v[112:115]
	v_mfma_f32_16x16x32_bf16 v[108:111], v[186:189], v[210:213], v[108:111]
	v_mfma_f32_16x16x32_bf16 v[104:107], v[174:177], v[218:221], v[104:107]
	v_mfma_f32_16x16x32_bf16 v[100:103], v[186:189], v[218:221], v[100:103]
	s_barrier
; #define PG8_STAGE(bufoff, gbase, voff) do { _Pragma("unroll") for (int _i = 0; _i < 2; ++_i) \
;         __builtin_amdgcn_global_load_lds((const unsigned*)((const char*)(gbase) + (voff)[_i]), (PG8_LAS unsigned*)(lds + (bufoff) + ldsw + _i * 8192), 16, 0, 0); } while (0)
; #define PG8_LDA(dst, b, h) do { _Pragma("unroll") for (int m = 0; m < 4; ++m) _Pragma("unroll") for (int k = 0; k < 2; ++k) dst[m][k] = *(const PG8_LAS bf16x8*)(lds + PG8_SA(b, h) + aoff + m * 2048 + k * 1024); } while (0)
; #define PG8_LDB(dst, b, h) do { _Pragma("unroll") for (int n = 0; n < 2; ++n) _Pragma("unroll") for (int k = 0; k < 2; ++k) dst[n][k] = *(const PG8_LAS bf16x8*)(lds + PG8_SB(b, h) + boff + n * 2048 + k * 1024); } while (0)
; #define PG8_MMA(ai, bj, At, Bt) do { __builtin_amdgcn_s_setprio(1); _Pragma("unroll") for (int m = 0; m < 4; ++m) _Pragma("unroll") for (int n = 0; n < 2; ++n) _Pragma("unroll") for (int k = 0; k < 2; ++k) \
;         acc[ai][bj][m][n] = __builtin_amdgcn_mfma_f32_16x16x32_bf16(Bt[n][k], At[m][k], acc[ai][bj][m][n], 0, 0, 0); __builtin_amdgcn_s_setprio(0); } while (0)
; #define PG8_WAIT_V(n) asm volatile("s_waitcnt vmcnt(" #n ")" ::: "memory")
; template <class Epi, class Sched, bool ALIGN_EPI = false, bool SP2 = false>
; __device__ __forceinline__ void gemm_phase(PG8_LAS unsigned char* lds, const Gemm g, const Sched& S, const Epi& E) {
;     ...
;             PG8_LDB(B0, 0, 0); PG8_LDB(B1, 0, 1); PG8_SCHED; PG8_LDA(At, 0, 0); PG8_STAGE(PG8_SA(1, 1), a1 + hstep, voffA);
;             PG8_WAIT_V(8); PG8_WAIT_L(0); PG8_BAR; PG8_MMA(0, 0, At, B0); PG8_MMA(0, 1, At, B1); PG8_BAR; PG8_SCHED;
;             PG8_LDA(At, 0, 1); PG8_STAGE(PG8_SB(0, 0), b2, voffB); PG8_STAGE(PG8_SB(0, 1), b2 + hstep, voffB); PG8_STAGE(PG8_SA(0, 0), a2, voffA);
;             PG8_WAIT_V(8); PG8_WAIT_L(0); PG8_BAR; PG8_MMA(1, 0, At, B0); PG8_MMA(1, 1, At, B1); PG8_BAR; PG8_SCHED;
;             PG8_LDB(B0, 1, 0); PG8_LDB(B1, 1, 1); PG8_SCHED; PG8_LDA(At, 1, 0); PG8_STAGE(PG8_SA(0, 1), a2 + hstep, voffA);
;             PG8_WAIT_V(8); PG8_WAIT_L(0); PG8_BAR; PG8_MMA(0, 0, At, B0); PG8_MMA(0, 1, At, B1); PG8_BAR; PG8_SCHED;
;             PG8_LDA(At, 1, 1); PG8_STAGE(PG8_SB(1, 0), b3, voffB); PG8_STAGE(PG8_SB(1, 1), b3 + hstep, voffB); PG8_STAGE(PG8_SA(1, 0), a3, voffA);
;             PG8_WAIT_V(8); PG8_WAIT_L(0); PG8_BAR; PG8_MMA(1, 0, At, B0); PG8_MMA(1, 1, At, B1); PG8_BAR; PG8_SCHED;
	s_setprio 0
	s_add_i32 s26, s26, s44
	v_lshl_add_u64 v[146:147], v[146:147], 0, s[60:61]
	s_mov_b32 m0, s26
	ds_read_b128 v[190:193], v153 offset:49152
	ds_read_b128 v[194:197], v153 offset:50176
	ds_read_b128 v[198:201], v153 offset:51200
	ds_read_b128 v[202:205], v153 offset:52224
	ds_read_b128 v[206:209], v153 offset:53248
	ds_read_b128 v[210:213], v153 offset:54272
	ds_read_b128 v[214:217], v153 offset:55296
	ds_read_b128 v[218:221], v153 offset:56320
	global_load_lds_dwordx4 v[146:147], off
	s_add_i32 m0, s26, 0x2000
	s_add_u32 s38, s38, 0x80080
	v_lshl_add_u64 v[146:147], v[150:151], 0, s[60:61]
	s_addc_u32 s39, s39, 0
	s_add_i32 s26, s63, s44
	global_load_lds_dwordx4 v[146:147], off
	v_lshl_add_u64 v[146:147], s[38:39], 0, v[2:3]
	s_mov_b32 m0, s26
	s_nop 0
	global_load_lds_dwordx4 v[146:147], off
	v_lshl_add_u64 v[146:147], s[38:39], 0, v[132:133]
	s_add_i32 m0, s26, 0x2000
	s_nop 0
	global_load_lds_dwordx4 v[146:147], off
	v_lshl_add_u64 v[146:147], v[178:179], 0, s[60:61]
	s_mov_b32 m0, s51
	s_nop 0
	global_load_lds_dwordx4 v[146:147], off
	v_lshl_add_u64 v[146:147], v[222:223], 0, s[60:61]
	s_mov_b32 m0, s52
	s_nop 0
	global_load_lds_dwordx4 v[146:147], off
	s_waitcnt vmcnt(8)
	s_waitcnt lgkmcnt(0)
	s_setprio 3
	s_barrier
	v_mfma_f32_16x16x32_bf16 v[32:35], v[154:157], v[190:193], v[32:35]
	v_mfma_f32_16x16x32_bf16 v[28:31], v[162:165], v[190:193], v[28:31]
	v_mfma_f32_16x16x32_bf16 v[24:27], v[154:157], v[198:201], v[24:27]
	v_mfma_f32_16x16x32_bf16 v[20:23], v[162:165], v[198:201], v[20:23]
	v_mfma_f32_16x16x32_bf16 v[16:19], v[154:157], v[206:209], v[16:19]
	v_mfma_f32_16x16x32_bf16 v[12:15], v[162:165], v[206:209], v[12:15]
	v_mfma_f32_16x16x32_bf16 v[8:11], v[154:157], v[214:217], v[8:11]
	v_mfma_f32_16x16x32_bf16 v[4:7], v[162:165], v[214:217], v[4:7]
	v_mfma_f32_16x16x32_bf16 v[32:35], v[158:161], v[194:197], v[32:35]
	v_mfma_f32_16x16x32_bf16 v[28:31], v[166:169], v[194:197], v[28:31]
	v_mfma_f32_16x16x32_bf16 v[24:27], v[158:161], v[202:205], v[24:27]
	v_mfma_f32_16x16x32_bf16 v[20:23], v[166:169], v[202:205], v[20:23]
	v_mfma_f32_16x16x32_bf16 v[16:19], v[158:161], v[210:213], v[16:19]
	v_mfma_f32_16x16x32_bf16 v[12:15], v[166:169], v[210:213], v[12:15]
	v_mfma_f32_16x16x32_bf16 v[8:11], v[158:161], v[218:221], v[8:11]
	v_mfma_f32_16x16x32_bf16 v[4:7], v[166:169], v[218:221], v[4:7]
	s_setprio 0
	s_setprio 1
	v_mfma_f32_16x16x32_bf16 v[96:99], v[170:173], v[190:193], v[96:99]
	v_mfma_f32_16x16x32_bf16 v[92:95], v[182:185], v[190:193], v[92:95]
	v_mfma_f32_16x16x32_bf16 v[88:91], v[170:173], v[198:201], v[88:91]
	v_mfma_f32_16x16x32_bf16 v[84:87], v[182:185], v[198:201], v[84:87]
	v_mfma_f32_16x16x32_bf16 v[72:75], v[170:173], v[206:209], v[72:75]
	v_mfma_f32_16x16x32_bf16 v[68:71], v[182:185], v[206:209], v[68:71]
	v_mfma_f32_16x16x32_bf16 v[48:51], v[170:173], v[214:217], v[48:51]
	v_mfma_f32_16x16x32_bf16 v[40:43], v[182:185], v[214:217], v[40:43]
	v_mfma_f32_16x16x32_bf16 v[96:99], v[174:177], v[194:197], v[96:99]
	v_mfma_f32_16x16x32_bf16 v[92:95], v[186:189], v[194:197], v[92:95]
	v_mfma_f32_16x16x32_bf16 v[88:91], v[174:177], v[202:205], v[88:91]
	v_mfma_f32_16x16x32_bf16 v[84:87], v[186:189], v[202:205], v[84:87]
	v_mfma_f32_16x16x32_bf16 v[72:75], v[174:177], v[210:213], v[72:75]
	v_mfma_f32_16x16x32_bf16 v[68:71], v[186:189], v[210:213], v[68:71]
	v_mfma_f32_16x16x32_bf16 v[48:51], v[174:177], v[218:221], v[48:51]
	v_mfma_f32_16x16x32_bf16 v[40:43], v[186:189], v[218:221], v[40:43]
	s_barrier
	s_setprio 0
	s_add_i32 s62, s62, 2
	s_add_u32 s36, s36, 0x100
	s_addc_u32 s37, s37, 0
	s_add_u32 s56, s56, 0x100
	s_addc_u32 s57, s57, 0
	s_cmp_gt_u32 s62, 29
	s_cbranch_scc0 .LBB0_1167
	s_branch .Lpeel_post_p1
.LBB0_1167:
	s_add_u32 s26, s36, 0xfff80080
	s_addc_u32 s38, s37, -1
	s_add_i32 s63, 0, 0x10000
	s_cmp_eq_u32 s62, 28
	s_cselect_b32 s43, s17, s38
	s_cselect_b32 s42, s30, s26
	v_add_u32_e32 v144, s63, v145
	s_cselect_b32 s39, s15, s57
	s_cselect_b32 s38, s55, s56
	s_add_i32 s26, 0, 0x14000
	ds_read_b128 v[154:157], v144
	ds_read_b128 v[158:161], v144 offset:1024
	ds_read_b128 v[162:165], v144 offset:2048
	ds_read_b128 v[166:169], v144 offset:3072
	v_add_u32_e32 v144, s26, v145
	ds_read_b128 v[170:173], v144
	ds_read_b128 v[174:177], v144 offset:1024
	ds_read_b128 v[182:185], v144 offset:2048
	ds_read_b128 v[186:189], v144 offset:3072
	v_lshl_add_u64 v[146:147], s[36:37], 0, v[140:141]
	s_add_i32 m0, s45, 0xc000
	ds_read_b128 v[190:193], v153
	ds_read_b128 v[194:197], v153 offset:1024
	ds_read_b128 v[198:201], v153 offset:2048
	ds_read_b128 v[202:205], v153 offset:3072
	ds_read_b128 v[206:209], v153 offset:4096
	ds_read_b128 v[210:213], v153 offset:5120
	ds_read_b128 v[214:217], v153 offset:6144
	ds_read_b128 v[218:221], v153 offset:7168
	global_load_lds_dwordx4 v[146:147], off
	v_lshl_add_u64 v[146:147], s[36:37], 0, v[142:143]
	s_add_i32 m0, s45, 0xe000
	s_nop 0
	global_load_lds_dwordx4 v[146:147], off
	s_waitcnt vmcnt(8)
	s_waitcnt lgkmcnt(0)
	s_setprio 3
	s_barrier
; #define PG8_STAGE(bufoff, gbase, voff) do { _Pragma("unroll") for (int _i = 0; _i < 2; ++_i) \
;         __builtin_amdgcn_global_load_lds((const unsigned*)((const char*)(gbase) + (voff)[_i]), (PG8_LAS unsigned*)(lds + (bufoff) + ldsw + _i * 8192), 16, 0, 0); } while (0)
; #define PG8_LDA(dst, b, h) do { _Pragma("unroll") for (int m = 0; m < 4; ++m) _Pragma("unroll") for (int k = 0; k < 2; ++k) dst[m][k] = *(const PG8_LAS bf16x8*)(lds + PG8_SA(b, h) + aoff + m * 2048 + k * 1024); } while (0)
; #define PG8_MMA(ai, bj, At, Bt) do { __builtin_amdgcn_s_setprio(1); _Pragma("unroll") for (int m = 0; m < 4; ++m) _Pragma("unroll") for (int n = 0; n < 2; ++n) _Pragma("unroll") for (int k = 0; k < 2; ++k) \
;         acc[ai][bj][m][n] = __builtin_amdgcn_mfma_f32_16x16x32_bf16(Bt[n][k], At[m][k], acc[ai][bj][m][n], 0, 0, 0); __builtin_amdgcn_s_setprio(0); } while (0)
; #define PG8_WAIT_V(n) asm volatile("s_waitcnt vmcnt(" #n ")" ::: "memory")
; #define PG8_WAIT_L(n) asm volatile("s_waitcnt lgkmcnt(" #n ")" ::: "memory")
; #define PG8_BAR __builtin_amdgcn_s_barrier()
; #define PG8_SCHED __builtin_amdgcn_sched_barrier(0)
; template <class Epi, class Sched, bool ALIGN_EPI = false, bool SP2 = false>
; __device__ __forceinline__ void gemm_phase(PG8_LAS unsigned char* lds, const Gemm g, const Sched& S, const Epi& E) {
;     ...
;             PG8_WAIT_V(8); PG8_WAIT_L(0); PG8_BAR; PG8_MMA(0, 0, At, B0); PG8_MMA(0, 1, At, B1); PG8_BAR; PG8_SCHED;
;             PG8_LDA(At, 0, 1); PG8_STAGE(PG8_SB(0, 0), b2, voffB); PG8_STAGE(PG8_SB(0, 1), b2 + hstep, voffB); PG8_STAGE(PG8_SA(0, 0), a2, voffA);
;             PG8_WAIT_V(8); PG8_WAIT_L(0); PG8_BAR; PG8_MMA(1, 0, At, B0); PG8_MMA(1, 1, At, B1); PG8_BAR; PG8_SCHED;
	v_mfma_f32_16x16x32_bf16 v[80:83], v[154:157], v[190:193], v[80:83]
	v_mfma_f32_16x16x32_bf16 v[76:79], v[162:165], v[190:193], v[76:79]
	v_mfma_f32_16x16x32_bf16 v[64:67], v[154:157], v[198:201], v[64:67]
	v_mfma_f32_16x16x32_bf16 v[60:63], v[162:165], v[198:201], v[60:63]
	v_mfma_f32_16x16x32_bf16 v[56:59], v[154:157], v[206:209], v[56:59]
	v_mfma_f32_16x16x32_bf16 v[52:55], v[162:165], v[206:209], v[52:55]
	v_mfma_f32_16x16x32_bf16 v[44:47], v[154:157], v[214:217], v[44:47]
	v_mfma_f32_16x16x32_bf16 v[36:39], v[162:165], v[214:217], v[36:39]
	v_mfma_f32_16x16x32_bf16 v[80:83], v[158:161], v[194:197], v[80:83]
	v_mfma_f32_16x16x32_bf16 v[76:79], v[166:169], v[194:197], v[76:79]
	v_mfma_f32_16x16x32_bf16 v[64:67], v[158:161], v[202:205], v[64:67]
	v_mfma_f32_16x16x32_bf16 v[60:63], v[166:169], v[202:205], v[60:63]
	v_mfma_f32_16x16x32_bf16 v[56:59], v[158:161], v[210:213], v[56:59]
	v_mfma_f32_16x16x32_bf16 v[52:55], v[166:169], v[210:213], v[52:55]
	v_mfma_f32_16x16x32_bf16 v[44:47], v[158:161], v[218:221], v[44:47]
	v_mfma_f32_16x16x32_bf16 v[36:39], v[166:169], v[218:221], v[36:39]
	s_setprio 0
	s_setprio 1
	v_mfma_f32_16x16x32_bf16 v[128:131], v[170:173], v[190:193], v[128:131]
	v_mfma_f32_16x16x32_bf16 v[124:127], v[182:185], v[190:193], v[124:127]
	v_mfma_f32_16x16x32_bf16 v[120:123], v[170:173], v[198:201], v[120:123]
	v_mfma_f32_16x16x32_bf16 v[116:119], v[182:185], v[198:201], v[116:119]
	v_mfma_f32_16x16x32_bf16 v[112:115], v[170:173], v[206:209], v[112:115]
	v_mfma_f32_16x16x32_bf16 v[108:111], v[182:185], v[206:209], v[108:111]
	v_mfma_f32_16x16x32_bf16 v[104:107], v[170:173], v[214:217], v[104:107]
	v_mfma_f32_16x16x32_bf16 v[100:103], v[182:185], v[214:217], v[100:103]
	v_mfma_f32_16x16x32_bf16 v[128:131], v[174:177], v[194:197], v[128:131]
	v_mfma_f32_16x16x32_bf16 v[124:127], v[186:189], v[194:197], v[124:127]
	v_mfma_f32_16x16x32_bf16 v[120:123], v[174:177], v[202:205], v[120:123]
	v_mfma_f32_16x16x32_bf16 v[116:119], v[186:189], v[202:205], v[116:119]
	v_mfma_f32_16x16x32_bf16 v[112:115], v[174:177], v[210:213], v[112:115]
	v_mfma_f32_16x16x32_bf16 v[108:111], v[186:189], v[210:213], v[108:111]
	v_mfma_f32_16x16x32_bf16 v[104:107], v[174:177], v[218:221], v[104:107]
	v_mfma_f32_16x16x32_bf16 v[100:103], v[186:189], v[218:221], v[100:103]
	s_barrier
	s_setprio 0
	s_add_i32 s63, s63, s44
	v_lshl_add_u64 v[146:147], s[38:39], 0, v[2:3]
	s_mov_b32 m0, s63
	ds_read_b128 v[190:193], v153 offset:16384
	ds_read_b128 v[194:197], v153 offset:17408
	ds_read_b128 v[198:201], v153 offset:18432
	ds_read_b128 v[202:205], v153 offset:19456
	ds_read_b128 v[206:209], v153 offset:20480
	ds_read_b128 v[210:213], v153 offset:21504
	ds_read_b128 v[214:217], v153 offset:22528
	ds_read_b128 v[218:221], v153 offset:23552
	global_load_lds_dwordx4 v[146:147], off
	s_add_i32 m0, s63, 0x2000
	s_add_u32 s66, s38, 0x80000
	v_lshl_add_u64 v[150:151], s[38:39], 0, v[132:133]
	s_addc_u32 s67, s39, 0
	s_add_i32 s26, s26, s44
	global_load_lds_dwordx4 v[150:151], off
	v_lshl_add_u64 v[178:179], s[66:67], 0, v[2:3]
	s_mov_b32 m0, s26
	v_lshl_add_u64 v[222:223], s[42:43], 0, v[134:135]
	global_load_lds_dwordx4 v[178:179], off
	v_lshl_add_u64 v[178:179], s[66:67], 0, v[132:133]
	s_add_i32 m0, s26, 0x2000
	s_nop 0
	global_load_lds_dwordx4 v[178:179], off
	v_lshl_add_u64 v[178:179], s[42:43], 0, v[136:137]
	s_mov_b32 m0, s45
	s_nop 0
	global_load_lds_dwordx4 v[178:179], off
	s_mov_b32 m0, s46
	s_nop 0
	global_load_lds_dwordx4 v[222:223], off
	s_waitcnt vmcnt(8)
	s_waitcnt lgkmcnt(0)
	s_setprio 3
	s_barrier
	v_mfma_f32_16x16x32_bf16 v[32:35], v[154:157], v[190:193], v[32:35]
	v_mfma_f32_16x16x32_bf16 v[28:31], v[162:165], v[190:193], v[28:31]
	v_mfma_f32_16x16x32_bf16 v[24:27], v[154:157], v[198:201], v[24:27]
	v_mfma_f32_16x16x32_bf16 v[20:23], v[162:165], v[198:201], v[20:23]
	v_mfma_f32_16x16x32_bf16 v[16:19], v[154:157], v[206:209], v[16:19]
	v_mfma_f32_16x16x32_bf16 v[12:15], v[162:165], v[206:209], v[12:15]
	v_mfma_f32_16x16x32_bf16 v[8:11], v[154:157], v[214:217], v[8:11]
	v_mfma_f32_16x16x32_bf16 v[4:7], v[162:165], v[214:217], v[4:7]
	v_mfma_f32_16x16x32_bf16 v[32:35], v[158:161], v[194:197], v[32:35]
	v_mfma_f32_16x16x32_bf16 v[28:31], v[166:169], v[194:197], v[28:31]
	v_mfma_f32_16x16x32_bf16 v[24:27], v[158:161], v[202:205], v[24:27]
	v_mfma_f32_16x16x32_bf16 v[20:23], v[166:169], v[202:205], v[20:23]
	v_mfma_f32_16x16x32_bf16 v[16:19], v[158:161], v[210:213], v[16:19]
	v_mfma_f32_16x16x32_bf16 v[12:15], v[166:169], v[210:213], v[12:15]
	v_mfma_f32_16x16x32_bf16 v[8:11], v[158:161], v[218:221], v[8:11]
	v_mfma_f32_16x16x32_bf16 v[4:7], v[166:169], v[218:221], v[4:7]
	s_setprio 0
	s_setprio 1
	v_mfma_f32_16x16x32_bf16 v[96:99], v[170:173], v[190:193], v[96:99]
	v_mfma_f32_16x16x32_bf16 v[92:95], v[182:185], v[190:193], v[92:95]
	v_mfma_f32_16x16x32_bf16 v[88:91], v[170:173], v[198:201], v[88:91]
	v_mfma_f32_16x16x32_bf16 v[84:87], v[182:185], v[198:201], v[84:87]
	v_mfma_f32_16x16x32_bf16 v[72:75], v[170:173], v[206:209], v[72:75]
	v_mfma_f32_16x16x32_bf16 v[68:71], v[182:185], v[206:209], v[68:71]
	v_mfma_f32_16x16x32_bf16 v[48:51], v[170:173], v[214:217], v[48:51]
	v_mfma_f32_16x16x32_bf16 v[40:43], v[182:185], v[214:217], v[40:43]
	v_mfma_f32_16x16x32_bf16 v[96:99], v[174:177], v[194:197], v[96:99]
	v_mfma_f32_16x16x32_bf16 v[92:95], v[186:189], v[194:197], v[92:95]
	v_mfma_f32_16x16x32_bf16 v[88:91], v[174:177], v[202:205], v[88:91]
	v_mfma_f32_16x16x32_bf16 v[84:87], v[186:189], v[202:205], v[84:87]
	v_mfma_f32_16x16x32_bf16 v[72:75], v[174:177], v[210:213], v[72:75]
	v_mfma_f32_16x16x32_bf16 v[68:71], v[186:189], v[210:213], v[68:71]
	v_mfma_f32_16x16x32_bf16 v[48:51], v[174:177], v[218:221], v[48:51]
	v_mfma_f32_16x16x32_bf16 v[40:43], v[186:189], v[218:221], v[40:43]
	s_barrier
; #define PG8_STAGE(bufoff, gbase, voff) do { _Pragma("unroll") for (int _i = 0; _i < 2; ++_i) \
;         __builtin_amdgcn_global_load_lds((const unsigned*)((const char*)(gbase) + (voff)[_i]), (PG8_LAS unsigned*)(lds + (bufoff) + ldsw + _i * 8192), 16, 0, 0); } while (0)
; #define PG8_LDA(dst, b, h) do { _Pragma("unroll") for (int m = 0; m < 4; ++m) _Pragma("unroll") for (int k = 0; k < 2; ++k) dst[m][k] = *(const PG8_LAS bf16x8*)(lds + PG8_SA(b, h) + aoff + m * 2048 + k * 1024); } while (0)
; #define PG8_LDB(dst, b, h) do { _Pragma("unroll") for (int n = 0; n < 2; ++n) _Pragma("unroll") for (int k = 0; k < 2; ++k) dst[n][k] = *(const PG8_LAS bf16x8*)(lds + PG8_SB(b, h) + boff + n * 2048 + k * 1024); } while (0)
; #define PG8_MMA(ai, bj, At, Bt) do { __builtin_amdgcn_s_setprio(1); _Pragma("unroll") for (int m = 0; m < 4; ++m) _Pragma("unroll") for (int n = 0; n < 2; ++n) _Pragma("unroll") for (int k = 0; k < 2; ++k) \
;         acc[ai][bj][m][n] = __builtin_amdgcn_mfma_f32_16x16x32_bf16(Bt[n][k], At[m][k], acc[ai][bj][m][n], 0, 0, 0); __builtin_amdgcn_s_setprio(0); } while (0)
; #define PG8_WAIT_V(n) asm volatile("s_waitcnt vmcnt(" #n ")" ::: "memory")
; #define PG8_WAIT_L(n) asm volatile("s_waitcnt lgkmcnt(" #n ")" ::: "memory")
; #define PG8_BAR __builtin_amdgcn_s_barrier()
; #define PG8_SCHED __builtin_amdgcn_sched_barrier(0)
; template <class Epi, class Sched, bool ALIGN_EPI = false, bool SP2 = false>
; __device__ __forceinline__ void gemm_phase(PG8_LAS unsigned char* lds, const Gemm g, const Sched& S, const Epi& E) {
;     ...
;             PG8_LDB(B0, 1, 0); PG8_LDB(B1, 1, 1); PG8_SCHED; PG8_LDA(At, 1, 0); PG8_STAGE(PG8_SA(0, 1), a2 + hstep, voffA);
;             PG8_WAIT_V(8); PG8_WAIT_L(0); PG8_BAR; PG8_MMA(0, 0, At, B0); PG8_MMA(0, 1, At, B1); PG8_BAR; PG8_SCHED;
	s_setprio 0
	s_add_i32 s26, 0, 0x18000
	v_add_u32_e32 v144, s26, v145
	s_add_i32 s63, 0, 0x1c000
	ds_read_b128 v[154:157], v144
	ds_read_b128 v[158:161], v144 offset:1024
	ds_read_b128 v[162:165], v144 offset:2048
	ds_read_b128 v[166:169], v144 offset:3072
	v_add_u32_e32 v144, s63, v145
	ds_read_b128 v[170:173], v144
	ds_read_b128 v[174:177], v144 offset:1024
	ds_read_b128 v[182:185], v144 offset:2048
	ds_read_b128 v[186:189], v144 offset:3072
	s_add_u32 s42, s42, 0x80000
	s_addc_u32 s43, s43, 0
	s_mov_b32 m0, s47
	v_lshl_add_u64 v[224:225], s[42:43], 0, v[136:137]
	ds_read_b128 v[190:193], v153 offset:32768
	ds_read_b128 v[194:197], v153 offset:33792
	ds_read_b128 v[198:201], v153 offset:34816
	ds_read_b128 v[202:205], v153 offset:35840
	ds_read_b128 v[206:209], v153 offset:36864
	ds_read_b128 v[210:213], v153 offset:37888
	ds_read_b128 v[214:217], v153 offset:38912
	ds_read_b128 v[218:221], v153 offset:39936
	global_load_lds_dwordx4 v[224:225], off
	v_lshl_add_u64 v[224:225], s[42:43], 0, v[134:135]
	s_mov_b32 m0, s50
	s_nop 0
	global_load_lds_dwordx4 v[224:225], off
	s_waitcnt vmcnt(8)
	s_waitcnt lgkmcnt(0)
	s_setprio 3
	s_barrier
	v_mfma_f32_16x16x32_bf16 v[80:83], v[154:157], v[190:193], v[80:83]
	v_mfma_f32_16x16x32_bf16 v[76:79], v[162:165], v[190:193], v[76:79]
	v_mfma_f32_16x16x32_bf16 v[64:67], v[154:157], v[198:201], v[64:67]
	v_mfma_f32_16x16x32_bf16 v[60:63], v[162:165], v[198:201], v[60:63]
	v_mfma_f32_16x16x32_bf16 v[56:59], v[154:157], v[206:209], v[56:59]
	v_mfma_f32_16x16x32_bf16 v[52:55], v[162:165], v[206:209], v[52:55]
	v_mfma_f32_16x16x32_bf16 v[44:47], v[154:157], v[214:217], v[44:47]
	v_mfma_f32_16x16x32_bf16 v[36:39], v[162:165], v[214:217], v[36:39]
	v_mfma_f32_16x16x32_bf16 v[80:83], v[158:161], v[194:197], v[80:83]
	v_mfma_f32_16x16x32_bf16 v[76:79], v[166:169], v[194:197], v[76:79]
	v_mfma_f32_16x16x32_bf16 v[64:67], v[158:161], v[202:205], v[64:67]
	v_mfma_f32_16x16x32_bf16 v[60:63], v[166:169], v[202:205], v[60:63]
	v_mfma_f32_16x16x32_bf16 v[56:59], v[158:161], v[210:213], v[56:59]
	v_mfma_f32_16x16x32_bf16 v[52:55], v[166:169], v[210:213], v[52:55]
	v_mfma_f32_16x16x32_bf16 v[44:47], v[158:161], v[218:221], v[44:47]
	v_mfma_f32_16x16x32_bf16 v[36:39], v[166:169], v[218:221], v[36:39]
	s_setprio 0
	s_setprio 1
	v_mfma_f32_16x16x32_bf16 v[128:131], v[170:173], v[190:193], v[128:131]
	v_mfma_f32_16x16x32_bf16 v[124:127], v[182:185], v[190:193], v[124:127]
	v_mfma_f32_16x16x32_bf16 v[120:123], v[170:173], v[198:201], v[120:123]
	v_mfma_f32_16x16x32_bf16 v[116:119], v[182:185], v[198:201], v[116:119]
	v_mfma_f32_16x16x32_bf16 v[112:115], v[170:173], v[206:209], v[112:115]
	v_mfma_f32_16x16x32_bf16 v[108:111], v[182:185], v[206:209], v[108:111]
	v_mfma_f32_16x16x32_bf16 v[104:107], v[170:173], v[214:217], v[104:107]
	v_mfma_f32_16x16x32_bf16 v[100:103], v[182:185], v[214:217], v[100:103]
	v_mfma_f32_16x16x32_bf16 v[128:131], v[174:177], v[194:197], v[128:131]
	v_mfma_f32_16x16x32_bf16 v[124:127], v[186:189], v[194:197], v[124:127]
	v_mfma_f32_16x16x32_bf16 v[120:123], v[174:177], v[202:205], v[120:123]
	v_mfma_f32_16x16x32_bf16 v[116:119], v[186:189], v[202:205], v[116:119]
	v_mfma_f32_16x16x32_bf16 v[112:115], v[174:177], v[210:213], v[112:115]
	v_mfma_f32_16x16x32_bf16 v[108:111], v[186:189], v[210:213], v[108:111]
	v_mfma_f32_16x16x32_bf16 v[104:107], v[174:177], v[218:221], v[104:107]
	v_mfma_f32_16x16x32_bf16 v[100:103], v[186:189], v[218:221], v[100:103]
	s_barrier
; #define PG8_STAGE(bufoff, gbase, voff) do { _Pragma("unroll") for (int _i = 0; _i < 2; ++_i) \
;         __builtin_amdgcn_global_load_lds((const unsigned*)((const char*)(gbase) + (voff)[_i]), (PG8_LAS unsigned*)(lds + (bufoff) + ldsw + _i * 8192), 16, 0, 0); } while (0)
; #define PG8_LDA(dst, b, h) do { _Pragma("unroll") for (int m = 0; m < 4; ++m) _Pragma("unroll") for (int k = 0; k < 2; ++k) dst[m][k] = *(const PG8_LAS bf16x8*)(lds + PG8_SA(b, h) + aoff + m * 2048 + k * 1024); } while (0)
; #define PG8_MMA(ai, bj, At, Bt) do { __builtin_amdgcn_s_setprio(1); _Pragma("unroll") for (int m = 0; m < 4; ++m) _Pragma("unroll") for (int n = 0; n < 2; ++n) _Pragma("unroll") for (int k = 0; k < 2; ++k) \
;         acc[ai][bj][m][n] = __builtin_amdgcn_mfma_f32_16x16x32_bf16(Bt[n][k], At[m][k], acc[ai][bj][m][n], 0, 0, 0); __builtin_amdgcn_s_setprio(0); } while (0)
; #define PG8_WAIT_V(n) asm volatile("s_waitcnt vmcnt(" #n ")" ::: "memory")
; #define PG8_WAIT_L(n) asm volatile("s_waitcnt lgkmcnt(" #n ")" ::: "memory")
; #define PG8_BAR __builtin_amdgcn_s_barrier()
; #define PG8_SCHED __builtin_amdgcn_sched_barrier(0)
; template <class Epi, class Sched, bool ALIGN_EPI = false, bool SP2 = false>
; __device__ __forceinline__ void gemm_phase(PG8_LAS unsigned char* lds, const Gemm g, const Sched& S, const Epi& E) {
;     ...
;             PG8_LDA(At, 1, 1); PG8_STAGE(PG8_SB(1, 0), b3, voffB); PG8_STAGE(PG8_SB(1, 1), b3 + hstep, voffB); PG8_STAGE(PG8_SA(1, 0), a3, voffA);
;             PG8_WAIT_V(8); PG8_WAIT_L(0); PG8_BAR; PG8_MMA(1, 0, At, B0); PG8_MMA(1, 1, At, B1); PG8_BAR; PG8_SCHED;
	s_setprio 0
	s_add_i32 s26, s26, s44
	v_lshl_add_u64 v[146:147], v[146:147], 0, s[60:61]
	s_mov_b32 m0, s26
	ds_read_b128 v[190:193], v153 offset:49152
	ds_read_b128 v[194:197], v153 offset:50176
	ds_read_b128 v[198:201], v153 offset:51200
	ds_read_b128 v[202:205], v153 offset:52224
	ds_read_b128 v[206:209], v153 offset:53248
	ds_read_b128 v[210:213], v153 offset:54272
	ds_read_b128 v[214:217], v153 offset:55296
	ds_read_b128 v[218:221], v153 offset:56320
	global_load_lds_dwordx4 v[146:147], off
	s_add_i32 m0, s26, 0x2000
	s_add_u32 s38, s38, 0x80080
	v_lshl_add_u64 v[146:147], v[150:151], 0, s[60:61]
	s_addc_u32 s39, s39, 0
	s_add_i32 s26, s63, s44
	global_load_lds_dwordx4 v[146:147], off
	v_lshl_add_u64 v[146:147], s[38:39], 0, v[2:3]
	s_mov_b32 m0, s26
	s_nop 0
	global_load_lds_dwordx4 v[146:147], off
	v_lshl_add_u64 v[146:147], s[38:39], 0, v[132:133]
	s_add_i32 m0, s26, 0x2000
	s_nop 0
	global_load_lds_dwordx4 v[146:147], off
	v_lshl_add_u64 v[146:147], v[178:179], 0, s[60:61]
	s_mov_b32 m0, s51
	s_nop 0
	global_load_lds_dwordx4 v[146:147], off
	v_lshl_add_u64 v[146:147], v[222:223], 0, s[60:61]
	s_mov_b32 m0, s52
	s_nop 0
	global_load_lds_dwordx4 v[146:147], off
	s_waitcnt vmcnt(8)
	s_waitcnt lgkmcnt(0)
	s_setprio 3
	s_barrier
	v_mfma_f32_16x16x32_bf16 v[32:35], v[154:157], v[190:193], v[32:35]
	v_mfma_f32_16x16x32_bf16 v[28:31], v[162:165], v[190:193], v[28:31]
	v_mfma_f32_16x16x32_bf16 v[24:27], v[154:157], v[198:201], v[24:27]
	v_mfma_f32_16x16x32_bf16 v[20:23], v[162:165], v[198:201], v[20:23]
	v_mfma_f32_16x16x32_bf16 v[16:19], v[154:157], v[206:209], v[16:19]
	v_mfma_f32_16x16x32_bf16 v[12:15], v[162:165], v[206:209], v[12:15]
	v_mfma_f32_16x16x32_bf16 v[8:11], v[154:157], v[214:217], v[8:11]
	v_mfma_f32_16x16x32_bf16 v[4:7], v[162:165], v[214:217], v[4:7]
	v_mfma_f32_16x16x32_bf16 v[32:35], v[158:161], v[194:197], v[32:35]
	v_mfma_f32_16x16x32_bf16 v[28:31], v[166:169], v[194:197], v[28:31]
	v_mfma_f32_16x16x32_bf16 v[24:27], v[158:161], v[202:205], v[24:27]
	v_mfma_f32_16x16x32_bf16 v[20:23], v[166:169], v[202:205], v[20:23]
	v_mfma_f32_16x16x32_bf16 v[16:19], v[158:161], v[210:213], v[16:19]
	v_mfma_f32_16x16x32_bf16 v[12:15], v[166:169], v[210:213], v[12:15]
	v_mfma_f32_16x16x32_bf16 v[8:11], v[158:161], v[218:221], v[8:11]
	v_mfma_f32_16x16x32_bf16 v[4:7], v[166:169], v[218:221], v[4:7]
	s_setprio 0
	s_setprio 1
	v_mfma_f32_16x16x32_bf16 v[96:99], v[170:173], v[190:193], v[96:99]
	v_mfma_f32_16x16x32_bf16 v[92:95], v[182:185], v[190:193], v[92:95]
	v_mfma_f32_16x16x32_bf16 v[88:91], v[170:173], v[198:201], v[88:91]
	v_mfma_f32_16x16x32_bf16 v[84:87], v[182:185], v[198:201], v[84:87]
	v_mfma_f32_16x16x32_bf16 v[72:75], v[170:173], v[206:209], v[72:75]
	v_mfma_f32_16x16x32_bf16 v[68:71], v[182:185], v[206:209], v[68:71]
	v_mfma_f32_16x16x32_bf16 v[48:51], v[170:173], v[214:217], v[48:51]
	v_mfma_f32_16x16x32_bf16 v[40:43], v[182:185], v[214:217], v[40:43]
	v_mfma_f32_16x16x32_bf16 v[96:99], v[174:177], v[194:197], v[96:99]
	v_mfma_f32_16x16x32_bf16 v[92:95], v[186:189], v[194:197], v[92:95]
	v_mfma_f32_16x16x32_bf16 v[88:91], v[174:177], v[202:205], v[88:91]
	v_mfma_f32_16x16x32_bf16 v[84:87], v[186:189], v[202:205], v[84:87]
	v_mfma_f32_16x16x32_bf16 v[72:75], v[174:177], v[210:213], v[72:75]
	v_mfma_f32_16x16x32_bf16 v[68:71], v[186:189], v[210:213], v[68:71]
	v_mfma_f32_16x16x32_bf16 v[48:51], v[174:177], v[218:221], v[48:51]
	v_mfma_f32_16x16x32_bf16 v[40:43], v[186:189], v[218:221], v[40:43]
	s_barrier
	s_setprio 0
	s_add_i32 s62, s62, 2
	s_add_u32 s36, s36, 0x100
	s_addc_u32 s37, s37, 0
	s_add_u32 s56, s56, 0x100
	s_addc_u32 s57, s57, 0
	s_cmp_gt_u32 s62, 29
	s_cbranch_scc0 .LBB0_1167

; #define PG8_STAGE(bufoff, gbase, voff) do { _Pragma("unroll") for (int _i = 0; _i < 2; ++_i) \
;         __builtin_amdgcn_global_load_lds((const unsigned*)((const char*)(gbase) + (voff)[_i]), (PG8_LAS unsigned*)(lds + (bufoff) + ldsw + _i * 8192), 16, 0, 0); } while (0)
; #define PG8_LDA(dst, b, h) do { _Pragma("unroll") for (int m = 0; m < 4; ++m) _Pragma("unroll") for (int k = 0; k < 2; ++k) dst[m][k] = *(const PG8_LAS bf16x8*)(lds + PG8_SA(b, h) + aoff + m * 2048 + k * 1024); } while (0)
; #define PG8_LDB(dst, b, h) do { _Pragma("unroll") for (int n = 0; n < 2; ++n) _Pragma("unroll") for (int k = 0; k < 2; ++k) dst[n][k] = *(const PG8_LAS bf16x8*)(lds + PG8_SB(b, h) + boff + n * 2048 + k * 1024); } while (0)
; #define PG8_WAIT_V(n) asm volatile("s_waitcnt vmcnt(" #n ")" ::: "memory")
; #define PG8_WAIT_L(n) asm volatile("s_waitcnt lgkmcnt(" #n ")" ::: "memory")
; #define PG8_BAR __builtin_amdgcn_s_barrier()
; #define PG8_SCHED __builtin_amdgcn_sched_barrier(0)
; template <class Epi, class Sched, bool ALIGN_EPI = false, bool SP2 = false>
; __device__ __forceinline__ void gemm_phase(PG8_LAS unsigned char* lds, const Gemm g, const Sched& S, const Epi& E) {
;     ...
;         const bool has_next = S.next(ui + 1, nxt);
;         const char* nA = has_next ? (const char*)g.A + (size_t)nxt.pm * tstep : cA; const char* nB = has_next ? (const char*)g.Bt + (size_t)nxt.pn * tstep : cB;
;         for (int t = 0; t < nt; t += 2) {
;             const bool last = (t == nt - 2);
;             const char* a1 = cA + (size_t)(t + 1) * kstep;
;             const char* a2 = last ? nA : cA + (size_t)(t + 2) * kstep; const char* b2 = last ? nB : cB + (size_t)(t + 2) * kstep;
;             const char* a3 = a2 + kstep; const char* b3 = b2 + kstep;
;             if (last && has_next) S.a_ready(nxt);
;             if constexpr (SP2) {
;             PG8_LDB(B0, 0, 0); PG8_LDB(B1, 0, 1); PG8_SCHED; PG8_LDA(At, 0, 0); PG8_STAGE(PG8_SA(1, 1), a1 + hstep, voffA);
;             PG8_WAIT_V(8); PG8_WAIT_L(0); PG8_BAR; PG8_MMA(0, 0, At, B0); PG8_MMA(0, 1, At, B1); PG8_BAR; PG8_SCHED;
;             PG8_LDA(At, 0, 1); PG8_STAGE(PG8_SB(0, 0), b2, voffB); PG8_STAGE(PG8_SB(0, 1), b2 + hstep, voffB); PG8_STAGE(PG8_SA(0, 0), a2, voffA);
;             PG8_WAIT_V(8); PG8_WAIT_L(0); PG8_BAR; PG8_MMA(1, 0, At, B0); PG8_MMA(1, 1, At, B1); PG8_BAR; PG8_SCHED;
.LBB0_1960:
	s_ashr_i32 s21, s20, 31
	s_lshl_b64 s[34:35], s[20:21], 20
	s_add_u32 s34, s2, s34
	s_addc_u32 s35, s3, s35
	s_and_b64 s[36:37], s[6:7], exec
	s_cselect_b32 s21, s35, s39
	s_cselect_b32 s57, s34, s38
	s_ashr_i32 s19, s18, 31
	s_lshl_b64 s[36:37], s[18:19], 20
	s_add_u32 s36, s29, s36
	s_addc_u32 s37, s40, s37
	s_and_b64 s[44:45], s[6:7], exec
	s_cselect_b32 s19, s37, s43
	s_cselect_b32 s62, s36, s42
	s_add_u32 s38, s38, 0x80080
	s_addc_u32 s39, s39, 0
	s_add_u32 s63, s42, 0x100
	s_addc_u32 s64, s43, 0
	s_mov_b32 s66, -2
	s_waitcnt lgkmcnt(0)
	s_add_u32 s26, s38, 0xfff80080
	s_addc_u32 s31, s39, -1
	s_add_i32 s67, 0, 0x10000
	s_cmp_eq_u32 s66, 28
	s_cselect_b32 s45, s21, s31
	s_cselect_b32 s44, s57, s26
	s_cselect_b32 s43, s19, s64
	s_cselect_b32 s42, s62, s63
	s_add_i32 s26, 0, 0x14000
	v_add_u32_e32 v128, s67, v178
	v_add_u32_e32 v170, s26, v178
	ds_read_b128 v[116:119], v128
	ds_read_b128 v[120:123], v128 offset:1024
	ds_read_b128 v[124:127], v128 offset:2048
	ds_read_b128 v[128:131], v128 offset:3072
	ds_read_b128 v[132:135], v170
	ds_read_b128 v[136:139], v170 offset:1024
	ds_read_b128 v[166:169], v170 offset:2048
	ds_read_b128 v[170:173], v170 offset:3072
	v_lshl_add_u64 v[210:211], s[38:39], 0, v[162:163]
	s_add_i32 m0, s47, 0xc000
	ds_read_b128 v[174:177], v181
	ds_read_b128 v[182:185], v181 offset:1024
	ds_read_b128 v[186:189], v181 offset:2048
	ds_read_b128 v[190:193], v181 offset:3072
	ds_read_b128 v[194:197], v181 offset:4096
	ds_read_b128 v[198:201], v181 offset:5120
	ds_read_b128 v[202:205], v181 offset:6144
	ds_read_b128 v[206:209], v181 offset:7168
	global_load_lds_dwordx4 v[210:211], off
	v_lshl_add_u64 v[210:211], s[38:39], 0, v[164:165]
	s_add_i32 m0, s47, 0xe000
	s_nop 0
	global_load_lds_dwordx4 v[210:211], off
	s_waitcnt vmcnt(8)
	s_waitcnt lgkmcnt(0)
	s_setprio 3
	s_barrier
	v_mfma_f32_16x16x32_bf16 v[152:155], v[116:119], v[174:177], 0
	v_mfma_f32_16x16x32_bf16 v[148:151], v[124:127], v[174:177], 0
	v_mfma_f32_16x16x32_bf16 v[112:115], v[116:119], v[186:189], 0
	v_mfma_f32_16x16x32_bf16 v[108:111], v[124:127], v[186:189], 0
	v_mfma_f32_16x16x32_bf16 v[96:99], v[116:119], v[194:197], 0
	v_mfma_f32_16x16x32_bf16 v[92:95], v[124:127], v[194:197], 0
	v_mfma_f32_16x16x32_bf16 v[80:83], v[116:119], v[202:205], 0
	v_mfma_f32_16x16x32_bf16 v[76:79], v[124:127], v[202:205], 0
	v_mfma_f32_16x16x32_bf16 v[152:155], v[120:123], v[182:185], v[152:155]
	v_mfma_f32_16x16x32_bf16 v[148:151], v[128:131], v[182:185], v[148:151]
	v_mfma_f32_16x16x32_bf16 v[112:115], v[120:123], v[190:193], v[112:115]
	v_mfma_f32_16x16x32_bf16 v[108:111], v[128:131], v[190:193], v[108:111]
	v_mfma_f32_16x16x32_bf16 v[96:99], v[120:123], v[198:201], v[96:99]
	v_mfma_f32_16x16x32_bf16 v[92:95], v[128:131], v[198:201], v[92:95]
	v_mfma_f32_16x16x32_bf16 v[80:83], v[120:123], v[206:209], v[80:83]
	v_mfma_f32_16x16x32_bf16 v[76:79], v[128:131], v[206:209], v[76:79]
	s_setprio 0
	s_setprio 1
	v_mfma_f32_16x16x32_bf16 v[144:147], v[132:135], v[174:177], 0
	v_mfma_f32_16x16x32_bf16 v[140:143], v[166:169], v[174:177], 0
	v_mfma_f32_16x16x32_bf16 v[104:107], v[132:135], v[186:189], 0
	v_mfma_f32_16x16x32_bf16 v[100:103], v[166:169], v[186:189], 0
	v_mfma_f32_16x16x32_bf16 v[88:91], v[132:135], v[194:197], 0
	v_mfma_f32_16x16x32_bf16 v[84:87], v[166:169], v[194:197], 0
	v_mfma_f32_16x16x32_bf16 v[72:75], v[132:135], v[202:205], 0
	v_mfma_f32_16x16x32_bf16 v[68:71], v[166:169], v[202:205], 0
	v_mfma_f32_16x16x32_bf16 v[144:147], v[136:139], v[182:185], v[144:147]
	v_mfma_f32_16x16x32_bf16 v[140:143], v[170:173], v[182:185], v[140:143]
	v_mfma_f32_16x16x32_bf16 v[104:107], v[136:139], v[190:193], v[104:107]
	v_mfma_f32_16x16x32_bf16 v[100:103], v[170:173], v[190:193], v[100:103]
	v_mfma_f32_16x16x32_bf16 v[88:91], v[136:139], v[198:201], v[88:91]
	v_mfma_f32_16x16x32_bf16 v[84:87], v[170:173], v[198:201], v[84:87]
	v_mfma_f32_16x16x32_bf16 v[72:75], v[136:139], v[206:209], v[72:75]
	v_mfma_f32_16x16x32_bf16 v[68:71], v[170:173], v[206:209], v[68:71]
	s_barrier
	s_setprio 0
	s_add_i32 s31, s67, s46
	v_lshl_add_u64 v[210:211], s[42:43], 0, v[2:3]
	s_mov_b32 m0, s31
	ds_read_b128 v[174:177], v181 offset:16384
	ds_read_b128 v[182:185], v181 offset:17408
	ds_read_b128 v[186:189], v181 offset:18432
	ds_read_b128 v[190:193], v181 offset:19456
	ds_read_b128 v[194:197], v181 offset:20480
	ds_read_b128 v[198:201], v181 offset:21504
	ds_read_b128 v[202:205], v181 offset:22528
	ds_read_b128 v[206:209], v181 offset:23552
	global_load_lds_dwordx4 v[210:211], off
	s_add_i32 m0, s31, 0x2000
	s_add_u32 s68, s42, 0x80000
	v_lshl_add_u64 v[212:213], s[42:43], 0, v[156:157]
	s_addc_u32 s69, s43, 0
	s_add_i32 s26, s26, s46
	global_load_lds_dwordx4 v[212:213], off
	v_lshl_add_u64 v[214:215], s[68:69], 0, v[2:3]
	s_mov_b32 m0, s26
	v_lshl_add_u64 v[216:217], s[44:45], 0, v[158:159]
	global_load_lds_dwordx4 v[214:215], off
	v_lshl_add_u64 v[214:215], s[68:69], 0, v[156:157]
	s_add_i32 m0, s26, 0x2000
	s_nop 0
	global_load_lds_dwordx4 v[214:215], off
	v_lshl_add_u64 v[214:215], s[44:45], 0, v[160:161]
	s_mov_b32 m0, s47
	s_nop 0
	global_load_lds_dwordx4 v[214:215], off
	s_mov_b32 m0, s50
	s_nop 0
	global_load_lds_dwordx4 v[216:217], off
	s_waitcnt vmcnt(8)
	s_waitcnt lgkmcnt(0)
	s_setprio 3
	s_barrier
; #define PG8_STAGE(bufoff, gbase, voff) do { _Pragma("unroll") for (int _i = 0; _i < 2; ++_i) \
;         __builtin_amdgcn_global_load_lds((const unsigned*)((const char*)(gbase) + (voff)[_i]), (PG8_LAS unsigned*)(lds + (bufoff) + ldsw + _i * 8192), 16, 0, 0); } while (0)
; #define PG8_LDA(dst, b, h) do { _Pragma("unroll") for (int m = 0; m < 4; ++m) _Pragma("unroll") for (int k = 0; k < 2; ++k) dst[m][k] = *(const PG8_LAS bf16x8*)(lds + PG8_SA(b, h) + aoff + m * 2048 + k * 1024); } while (0)
; #define PG8_LDB(dst, b, h) do { _Pragma("unroll") for (int n = 0; n < 2; ++n) _Pragma("unroll") for (int k = 0; k < 2; ++k) dst[n][k] = *(const PG8_LAS bf16x8*)(lds + PG8_SB(b, h) + boff + n * 2048 + k * 1024); } while (0)
; #define PG8_MMA(ai, bj, At, Bt) do { __builtin_amdgcn_s_setprio(1); _Pragma("unroll") for (int m = 0; m < 4; ++m) _Pragma("unroll") for (int n = 0; n < 2; ++n) _Pragma("unroll") for (int k = 0; k < 2; ++k) \
;         acc[ai][bj][m][n] = __builtin_amdgcn_mfma_f32_16x16x32_bf16(Bt[n][k], At[m][k], acc[ai][bj][m][n], 0, 0, 0); __builtin_amdgcn_s_setprio(0); } while (0)
; #define PG8_WAIT_V(n) asm volatile("s_waitcnt vmcnt(" #n ")" ::: "memory")
; #define PG8_WAIT_L(n) asm volatile("s_waitcnt lgkmcnt(" #n ")" ::: "memory")
; #define PG8_BAR __builtin_amdgcn_s_barrier()
; #define PG8_SCHED __builtin_amdgcn_sched_barrier(0)
; template <class Epi, class Sched, bool ALIGN_EPI = false, bool SP2 = false>
; __device__ __forceinline__ void gemm_phase(PG8_LAS unsigned char* lds, const Gemm g, const Sched& S, const Epi& E) {
;     ...
;             PG8_WAIT_V(8); PG8_WAIT_L(0); PG8_BAR; PG8_MMA(1, 0, At, B0); PG8_MMA(1, 1, At, B1); PG8_BAR; PG8_SCHED;
;             PG8_LDB(B0, 1, 0); PG8_LDB(B1, 1, 1); PG8_SCHED; PG8_LDA(At, 1, 0); PG8_STAGE(PG8_SA(0, 1), a2 + hstep, voffA);
;             PG8_WAIT_V(8); PG8_WAIT_L(0); PG8_BAR; PG8_MMA(0, 0, At, B0); PG8_MMA(0, 1, At, B1); PG8_BAR; PG8_SCHED;
	v_mfma_f32_16x16x32_bf16 v[64:67], v[116:119], v[174:177], 0
	v_mfma_f32_16x16x32_bf16 v[60:63], v[124:127], v[174:177], 0
	v_mfma_f32_16x16x32_bf16 v[48:51], v[116:119], v[186:189], 0
	v_mfma_f32_16x16x32_bf16 v[44:47], v[124:127], v[186:189], 0
	v_mfma_f32_16x16x32_bf16 v[32:35], v[116:119], v[194:197], 0
	v_mfma_f32_16x16x32_bf16 v[28:31], v[124:127], v[194:197], 0
	v_mfma_f32_16x16x32_bf16 v[16:19], v[116:119], v[202:205], 0
	v_mfma_f32_16x16x32_bf16 v[12:15], v[124:127], v[202:205], 0
	v_mfma_f32_16x16x32_bf16 v[64:67], v[120:123], v[182:185], v[64:67]
	v_mfma_f32_16x16x32_bf16 v[60:63], v[128:131], v[182:185], v[60:63]
	v_mfma_f32_16x16x32_bf16 v[48:51], v[120:123], v[190:193], v[48:51]
	v_mfma_f32_16x16x32_bf16 v[44:47], v[128:131], v[190:193], v[44:47]
	v_mfma_f32_16x16x32_bf16 v[32:35], v[120:123], v[198:201], v[32:35]
	v_mfma_f32_16x16x32_bf16 v[28:31], v[128:131], v[198:201], v[28:31]
	v_mfma_f32_16x16x32_bf16 v[16:19], v[120:123], v[206:209], v[16:19]
	v_mfma_f32_16x16x32_bf16 v[12:15], v[128:131], v[206:209], v[12:15]
	s_setprio 0
	s_setprio 1
	v_mfma_f32_16x16x32_bf16 v[56:59], v[132:135], v[174:177], 0
	v_mfma_f32_16x16x32_bf16 v[52:55], v[166:169], v[174:177], 0
	v_mfma_f32_16x16x32_bf16 v[40:43], v[132:135], v[186:189], 0
	v_mfma_f32_16x16x32_bf16 v[36:39], v[166:169], v[186:189], 0
	v_mfma_f32_16x16x32_bf16 v[24:27], v[132:135], v[194:197], 0
	v_mfma_f32_16x16x32_bf16 v[20:23], v[166:169], v[194:197], 0
	v_mfma_f32_16x16x32_bf16 v[8:11], v[132:135], v[202:205], 0
	v_mfma_f32_16x16x32_bf16 v[4:7], v[166:169], v[202:205], 0
	v_mfma_f32_16x16x32_bf16 v[56:59], v[136:139], v[182:185], v[56:59]
	v_mfma_f32_16x16x32_bf16 v[52:55], v[170:173], v[182:185], v[52:55]
	v_mfma_f32_16x16x32_bf16 v[40:43], v[136:139], v[190:193], v[40:43]
	v_mfma_f32_16x16x32_bf16 v[36:39], v[170:173], v[190:193], v[36:39]
	v_mfma_f32_16x16x32_bf16 v[24:27], v[136:139], v[198:201], v[24:27]
	v_mfma_f32_16x16x32_bf16 v[20:23], v[170:173], v[198:201], v[20:23]
	v_mfma_f32_16x16x32_bf16 v[8:11], v[136:139], v[206:209], v[8:11]
	v_mfma_f32_16x16x32_bf16 v[4:7], v[170:173], v[206:209], v[4:7]
	s_barrier
	s_setprio 0
	s_add_i32 s26, 0, 0x18000
	s_add_i32 s31, 0, 0x1c000
	v_add_u32_e32 v128, s26, v178
	v_add_u32_e32 v170, s31, v178
	ds_read_b128 v[116:119], v128
	ds_read_b128 v[120:123], v128 offset:1024
	ds_read_b128 v[124:127], v128 offset:2048
	ds_read_b128 v[128:131], v128 offset:3072
	ds_read_b128 v[132:135], v170
	ds_read_b128 v[136:139], v170 offset:1024
	ds_read_b128 v[166:169], v170 offset:2048
	ds_read_b128 v[170:173], v170 offset:3072
	s_add_u32 s44, s44, 0x80000
	s_addc_u32 s45, s45, 0
	s_mov_b32 m0, s51
	v_lshl_add_u64 v[218:219], s[44:45], 0, v[160:161]
	ds_read_b128 v[174:177], v181 offset:32768
	ds_read_b128 v[182:185], v181 offset:33792
	ds_read_b128 v[186:189], v181 offset:34816
	ds_read_b128 v[190:193], v181 offset:35840
	ds_read_b128 v[194:197], v181 offset:36864
	ds_read_b128 v[198:201], v181 offset:37888
	ds_read_b128 v[202:205], v181 offset:38912
	ds_read_b128 v[206:209], v181 offset:39936
	global_load_lds_dwordx4 v[218:219], off
	v_lshl_add_u64 v[218:219], s[44:45], 0, v[158:159]
	s_mov_b32 m0, s52
	s_nop 0
	global_load_lds_dwordx4 v[218:219], off
	s_waitcnt vmcnt(8)
	s_waitcnt lgkmcnt(0)
	s_setprio 3
	s_barrier
	v_mfma_f32_16x16x32_bf16 v[152:155], v[116:119], v[174:177], v[152:155]
	v_mfma_f32_16x16x32_bf16 v[148:151], v[124:127], v[174:177], v[148:151]
	v_mfma_f32_16x16x32_bf16 v[112:115], v[116:119], v[186:189], v[112:115]
	v_mfma_f32_16x16x32_bf16 v[108:111], v[124:127], v[186:189], v[108:111]
	v_mfma_f32_16x16x32_bf16 v[96:99], v[116:119], v[194:197], v[96:99]
	v_mfma_f32_16x16x32_bf16 v[92:95], v[124:127], v[194:197], v[92:95]
	v_mfma_f32_16x16x32_bf16 v[80:83], v[116:119], v[202:205], v[80:83]
	v_mfma_f32_16x16x32_bf16 v[76:79], v[124:127], v[202:205], v[76:79]
	v_mfma_f32_16x16x32_bf16 v[152:155], v[120:123], v[182:185], v[152:155]
	v_mfma_f32_16x16x32_bf16 v[148:151], v[128:131], v[182:185], v[148:151]
	v_mfma_f32_16x16x32_bf16 v[112:115], v[120:123], v[190:193], v[112:115]
	v_mfma_f32_16x16x32_bf16 v[108:111], v[128:131], v[190:193], v[108:111]
	v_mfma_f32_16x16x32_bf16 v[96:99], v[120:123], v[198:201], v[96:99]
	v_mfma_f32_16x16x32_bf16 v[92:95], v[128:131], v[198:201], v[92:95]
	v_mfma_f32_16x16x32_bf16 v[80:83], v[120:123], v[206:209], v[80:83]
	v_mfma_f32_16x16x32_bf16 v[76:79], v[128:131], v[206:209], v[76:79]
	s_setprio 0
	s_setprio 1
	v_mfma_f32_16x16x32_bf16 v[144:147], v[132:135], v[174:177], v[144:147]
	v_mfma_f32_16x16x32_bf16 v[140:143], v[166:169], v[174:177], v[140:143]
	v_mfma_f32_16x16x32_bf16 v[104:107], v[132:135], v[186:189], v[104:107]
	v_mfma_f32_16x16x32_bf16 v[100:103], v[166:169], v[186:189], v[100:103]
	v_mfma_f32_16x16x32_bf16 v[88:91], v[132:135], v[194:197], v[88:91]
	v_mfma_f32_16x16x32_bf16 v[84:87], v[166:169], v[194:197], v[84:87]
	v_mfma_f32_16x16x32_bf16 v[72:75], v[132:135], v[202:205], v[72:75]
	v_mfma_f32_16x16x32_bf16 v[68:71], v[166:169], v[202:205], v[68:71]
	v_mfma_f32_16x16x32_bf16 v[144:147], v[136:139], v[182:185], v[144:147]
	v_mfma_f32_16x16x32_bf16 v[140:143], v[170:173], v[182:185], v[140:143]
	v_mfma_f32_16x16x32_bf16 v[104:107], v[136:139], v[190:193], v[104:107]
	v_mfma_f32_16x16x32_bf16 v[100:103], v[170:173], v[190:193], v[100:103]
	v_mfma_f32_16x16x32_bf16 v[88:91], v[136:139], v[198:201], v[88:91]
	v_mfma_f32_16x16x32_bf16 v[84:87], v[170:173], v[198:201], v[84:87]
	v_mfma_f32_16x16x32_bf16 v[72:75], v[136:139], v[206:209], v[72:75]
	v_mfma_f32_16x16x32_bf16 v[68:71], v[170:173], v[206:209], v[68:71]
	s_barrier
; #define PG8_STAGE(bufoff, gbase, voff) do { _Pragma("unroll") for (int _i = 0; _i < 2; ++_i) \
;         __builtin_amdgcn_global_load_lds((const unsigned*)((const char*)(gbase) + (voff)[_i]), (PG8_LAS unsigned*)(lds + (bufoff) + ldsw + _i * 8192), 16, 0, 0); } while (0)
; #define PG8_LDA(dst, b, h) do { _Pragma("unroll") for (int m = 0; m < 4; ++m) _Pragma("unroll") for (int k = 0; k < 2; ++k) dst[m][k] = *(const PG8_LAS bf16x8*)(lds + PG8_SA(b, h) + aoff + m * 2048 + k * 1024); } while (0)
; #define PG8_LDB(dst, b, h) do { _Pragma("unroll") for (int n = 0; n < 2; ++n) _Pragma("unroll") for (int k = 0; k < 2; ++k) dst[n][k] = *(const PG8_LAS bf16x8*)(lds + PG8_SB(b, h) + boff + n * 2048 + k * 1024); } while (0)
; #define PG8_BAR __builtin_amdgcn_s_barrier()
; template <class Epi, class Sched, bool ALIGN_EPI = false, bool SP2 = false>
; __device__ __forceinline__ void gemm_phase(PG8_LAS unsigned char* lds, const Gemm g, const Sched& S, const Epi& E) {
;     ...
;             const bool last = (t == nt - 2);
;             const char* a1 = cA + (size_t)(t + 1) * kstep;
;             const char* a2 = last ? nA : cA + (size_t)(t + 2) * kstep; const char* b2 = last ? nB : cB + (size_t)(t + 2) * kstep;
;             const char* a3 = a2 + kstep; const char* b3 = b2 + kstep;
;             if (last && has_next) S.a_ready(nxt);
;             if constexpr (SP2) {
;             PG8_LDB(B0, 0, 0); PG8_LDB(B1, 0, 1); PG8_SCHED; PG8_LDA(At, 0, 0); PG8_STAGE(PG8_SA(1, 1), a1 + hstep, voffA);
;             PG8_WAIT_V(8); PG8_WAIT_L(0); PG8_BAR; PG8_MMA(0, 0, At, B0); PG8_MMA(0, 1, At, B1); PG8_BAR; PG8_SCHED;
;             PG8_LDA(At, 0, 1); PG8_STAGE(PG8_SB(0, 0), b2, voffB); PG8_STAGE(PG8_SB(0, 1), b2 + hstep, voffB); PG8_STAGE(PG8_SA(0, 0), a2, voffA);
;             PG8_WAIT_V(8); PG8_WAIT_L(0); PG8_BAR; PG8_MMA(1, 0, At, B0); PG8_MMA(1, 1, At, B1); PG8_BAR; PG8_SCHED;
;             PG8_LDB(B0, 1, 0); PG8_LDB(B1, 1, 1); PG8_SCHED; PG8_LDA(At, 1, 0); PG8_STAGE(PG8_SA(0, 1), a2 + hstep, voffA);
;             PG8_WAIT_V(8); PG8_WAIT_L(0); PG8_BAR; PG8_MMA(0, 0, At, B0); PG8_MMA(0, 1, At, B1); PG8_BAR; PG8_SCHED;
;             PG8_LDA(At, 1, 1); PG8_STAGE(PG8_SB(1, 0), b3, voffB); PG8_STAGE(PG8_SB(1, 1), b3 + hstep, voffB); PG8_STAGE(PG8_SA(1, 0), a3, voffA);
;             PG8_WAIT_V(8); PG8_WAIT_L(0); PG8_BAR; PG8_MMA(1, 0, At, B0); PG8_MMA(1, 1, At, B1); PG8_BAR; PG8_SCHED;
	s_setprio 0
	s_add_i32 s26, s26, s46
	v_lshl_add_u64 v[210:211], v[210:211], 0, s[60:61]
	s_mov_b32 m0, s26
	ds_read_b128 v[174:177], v181 offset:49152
	ds_read_b128 v[182:185], v181 offset:50176
	ds_read_b128 v[186:189], v181 offset:51200
	ds_read_b128 v[190:193], v181 offset:52224
	ds_read_b128 v[194:197], v181 offset:53248
	ds_read_b128 v[198:201], v181 offset:54272
	ds_read_b128 v[202:205], v181 offset:55296
	ds_read_b128 v[206:209], v181 offset:56320
	global_load_lds_dwordx4 v[210:211], off
	s_add_i32 m0, s26, 0x2000
	s_add_u32 s42, s42, 0x80080
	v_lshl_add_u64 v[210:211], v[212:213], 0, s[60:61]
	s_addc_u32 s43, s43, 0
	s_add_i32 s26, s31, s46
	global_load_lds_dwordx4 v[210:211], off
	v_lshl_add_u64 v[210:211], s[42:43], 0, v[2:3]
	s_mov_b32 m0, s26
	s_nop 0
	global_load_lds_dwordx4 v[210:211], off
	v_lshl_add_u64 v[210:211], s[42:43], 0, v[156:157]
	s_add_i32 m0, s26, 0x2000
	s_nop 0
	global_load_lds_dwordx4 v[210:211], off
	v_lshl_add_u64 v[210:211], v[214:215], 0, s[60:61]
	s_mov_b32 m0, s54
	s_nop 0
	global_load_lds_dwordx4 v[210:211], off
	v_lshl_add_u64 v[210:211], v[216:217], 0, s[60:61]
	s_mov_b32 m0, s55
	s_nop 0
	global_load_lds_dwordx4 v[210:211], off
	s_waitcnt vmcnt(8)
	s_waitcnt lgkmcnt(0)
	s_setprio 3
	s_barrier
	v_mfma_f32_16x16x32_bf16 v[64:67], v[116:119], v[174:177], v[64:67]
	v_mfma_f32_16x16x32_bf16 v[60:63], v[124:127], v[174:177], v[60:63]
	v_mfma_f32_16x16x32_bf16 v[48:51], v[116:119], v[186:189], v[48:51]
	v_mfma_f32_16x16x32_bf16 v[44:47], v[124:127], v[186:189], v[44:47]
	v_mfma_f32_16x16x32_bf16 v[32:35], v[116:119], v[194:197], v[32:35]
	v_mfma_f32_16x16x32_bf16 v[28:31], v[124:127], v[194:197], v[28:31]
	v_mfma_f32_16x16x32_bf16 v[16:19], v[116:119], v[202:205], v[16:19]
	v_mfma_f32_16x16x32_bf16 v[12:15], v[124:127], v[202:205], v[12:15]
	v_mfma_f32_16x16x32_bf16 v[64:67], v[120:123], v[182:185], v[64:67]
	v_mfma_f32_16x16x32_bf16 v[60:63], v[128:131], v[182:185], v[60:63]
	v_mfma_f32_16x16x32_bf16 v[48:51], v[120:123], v[190:193], v[48:51]
	v_mfma_f32_16x16x32_bf16 v[44:47], v[128:131], v[190:193], v[44:47]
	v_mfma_f32_16x16x32_bf16 v[32:35], v[120:123], v[198:201], v[32:35]
	v_mfma_f32_16x16x32_bf16 v[28:31], v[128:131], v[198:201], v[28:31]
	v_mfma_f32_16x16x32_bf16 v[16:19], v[120:123], v[206:209], v[16:19]
	v_mfma_f32_16x16x32_bf16 v[12:15], v[128:131], v[206:209], v[12:15]
	s_setprio 0
	s_setprio 1
	v_mfma_f32_16x16x32_bf16 v[56:59], v[132:135], v[174:177], v[56:59]
	v_mfma_f32_16x16x32_bf16 v[52:55], v[166:169], v[174:177], v[52:55]
	v_mfma_f32_16x16x32_bf16 v[40:43], v[132:135], v[186:189], v[40:43]
	v_mfma_f32_16x16x32_bf16 v[36:39], v[166:169], v[186:189], v[36:39]
	v_mfma_f32_16x16x32_bf16 v[24:27], v[132:135], v[194:197], v[24:27]
	v_mfma_f32_16x16x32_bf16 v[20:23], v[166:169], v[194:197], v[20:23]
	v_mfma_f32_16x16x32_bf16 v[8:11], v[132:135], v[202:205], v[8:11]
	v_mfma_f32_16x16x32_bf16 v[4:7], v[166:169], v[202:205], v[4:7]
	v_mfma_f32_16x16x32_bf16 v[56:59], v[136:139], v[182:185], v[56:59]
	v_mfma_f32_16x16x32_bf16 v[52:55], v[170:173], v[182:185], v[52:55]
	v_mfma_f32_16x16x32_bf16 v[40:43], v[136:139], v[190:193], v[40:43]
	v_mfma_f32_16x16x32_bf16 v[36:39], v[170:173], v[190:193], v[36:39]
	v_mfma_f32_16x16x32_bf16 v[24:27], v[136:139], v[198:201], v[24:27]
	v_mfma_f32_16x16x32_bf16 v[20:23], v[170:173], v[198:201], v[20:23]
	v_mfma_f32_16x16x32_bf16 v[8:11], v[136:139], v[206:209], v[8:11]
	v_mfma_f32_16x16x32_bf16 v[4:7], v[170:173], v[206:209], v[4:7]
	s_barrier
	s_setprio 0
	s_add_i32 s66, s66, 2
	s_add_u32 s38, s38, 0x100
	s_addc_u32 s39, s39, 0
	s_add_u32 s63, s63, 0x100
	s_addc_u32 s64, s64, 0
	s_cmp_gt_u32 s66, 29
	s_cbranch_scc0 .LBB0_1961
	s_branch .Lpeel_post_p4
.LBB0_1961:
	s_add_u32 s26, s38, 0xfff80080
	s_addc_u32 s31, s39, -1
	s_add_i32 s67, 0, 0x10000
	s_cmp_eq_u32 s66, 28
	s_cselect_b32 s45, s21, s31
	s_cselect_b32 s44, s57, s26
	s_cselect_b32 s43, s19, s64
	s_cselect_b32 s42, s62, s63
	s_add_i32 s26, 0, 0x14000
	v_add_u32_e32 v128, s67, v178
	v_add_u32_e32 v170, s26, v178
	ds_read_b128 v[116:119], v128
	ds_read_b128 v[120:123], v128 offset:1024
	ds_read_b128 v[124:127], v128 offset:2048
	ds_read_b128 v[128:131], v128 offset:3072
	ds_read_b128 v[132:135], v170
	ds_read_b128 v[136:139], v170 offset:1024
	ds_read_b128 v[166:169], v170 offset:2048
	ds_read_b128 v[170:173], v170 offset:3072
	v_lshl_add_u64 v[210:211], s[38:39], 0, v[162:163]
	s_add_i32 m0, s47, 0xc000
	ds_read_b128 v[174:177], v181
	ds_read_b128 v[182:185], v181 offset:1024
	ds_read_b128 v[186:189], v181 offset:2048
	ds_read_b128 v[190:193], v181 offset:3072
	ds_read_b128 v[194:197], v181 offset:4096
	ds_read_b128 v[198:201], v181 offset:5120
	ds_read_b128 v[202:205], v181 offset:6144
	ds_read_b128 v[206:209], v181 offset:7168
	global_load_lds_dwordx4 v[210:211], off
	v_lshl_add_u64 v[210:211], s[38:39], 0, v[164:165]
	s_add_i32 m0, s47, 0xe000
	s_nop 0
	global_load_lds_dwordx4 v[210:211], off
	s_waitcnt vmcnt(8)
	s_waitcnt lgkmcnt(0)
	s_setprio 3
	s_barrier
; #define PG8_STAGE(bufoff, gbase, voff) do { _Pragma("unroll") for (int _i = 0; _i < 2; ++_i) \
;         __builtin_amdgcn_global_load_lds((const unsigned*)((const char*)(gbase) + (voff)[_i]), (PG8_LAS unsigned*)(lds + (bufoff) + ldsw + _i * 8192), 16, 0, 0); } while (0)
; #define PG8_LDA(dst, b, h) do { _Pragma("unroll") for (int m = 0; m < 4; ++m) _Pragma("unroll") for (int k = 0; k < 2; ++k) dst[m][k] = *(const PG8_LAS bf16x8*)(lds + PG8_SA(b, h) + aoff + m * 2048 + k * 1024); } while (0)
; #define PG8_MMA(ai, bj, At, Bt) do { __builtin_amdgcn_s_setprio(1); _Pragma("unroll") for (int m = 0; m < 4; ++m) _Pragma("unroll") for (int n = 0; n < 2; ++n) _Pragma("unroll") for (int k = 0; k < 2; ++k) \
;         acc[ai][bj][m][n] = __builtin_amdgcn_mfma_f32_16x16x32_bf16(Bt[n][k], At[m][k], acc[ai][bj][m][n], 0, 0, 0); __builtin_amdgcn_s_setprio(0); } while (0)
; #define PG8_WAIT_V(n) asm volatile("s_waitcnt vmcnt(" #n ")" ::: "memory")
; #define PG8_WAIT_L(n) asm volatile("s_waitcnt lgkmcnt(" #n ")" ::: "memory")
; #define PG8_BAR __builtin_amdgcn_s_barrier()
; #define PG8_SCHED __builtin_amdgcn_sched_barrier(0)
; template <class Epi, class Sched, bool ALIGN_EPI = false, bool SP2 = false>
; __device__ __forceinline__ void gemm_phase(PG8_LAS unsigned char* lds, const Gemm g, const Sched& S, const Epi& E) {
;     ...
;             PG8_WAIT_V(8); PG8_WAIT_L(0); PG8_BAR; PG8_MMA(0, 0, At, B0); PG8_MMA(0, 1, At, B1); PG8_BAR; PG8_SCHED;
;             PG8_LDA(At, 0, 1); PG8_STAGE(PG8_SB(0, 0), b2, voffB); PG8_STAGE(PG8_SB(0, 1), b2 + hstep, voffB); PG8_STAGE(PG8_SA(0, 0), a2, voffA);
;             PG8_WAIT_V(8); PG8_WAIT_L(0); PG8_BAR; PG8_MMA(1, 0, At, B0); PG8_MMA(1, 1, At, B1); PG8_BAR; PG8_SCHED;
	v_mfma_f32_16x16x32_bf16 v[152:155], v[116:119], v[174:177], v[152:155]
	v_mfma_f32_16x16x32_bf16 v[148:151], v[124:127], v[174:177], v[148:151]
	v_mfma_f32_16x16x32_bf16 v[112:115], v[116:119], v[186:189], v[112:115]
	v_mfma_f32_16x16x32_bf16 v[108:111], v[124:127], v[186:189], v[108:111]
	v_mfma_f32_16x16x32_bf16 v[96:99], v[116:119], v[194:197], v[96:99]
	v_mfma_f32_16x16x32_bf16 v[92:95], v[124:127], v[194:197], v[92:95]
	v_mfma_f32_16x16x32_bf16 v[80:83], v[116:119], v[202:205], v[80:83]
	v_mfma_f32_16x16x32_bf16 v[76:79], v[124:127], v[202:205], v[76:79]
	v_mfma_f32_16x16x32_bf16 v[152:155], v[120:123], v[182:185], v[152:155]
	v_mfma_f32_16x16x32_bf16 v[148:151], v[128:131], v[182:185], v[148:151]
	v_mfma_f32_16x16x32_bf16 v[112:115], v[120:123], v[190:193], v[112:115]
	v_mfma_f32_16x16x32_bf16 v[108:111], v[128:131], v[190:193], v[108:111]
	v_mfma_f32_16x16x32_bf16 v[96:99], v[120:123], v[198:201], v[96:99]
	v_mfma_f32_16x16x32_bf16 v[92:95], v[128:131], v[198:201], v[92:95]
	v_mfma_f32_16x16x32_bf16 v[80:83], v[120:123], v[206:209], v[80:83]
	v_mfma_f32_16x16x32_bf16 v[76:79], v[128:131], v[206:209], v[76:79]
	s_setprio 0
	s_setprio 1
	v_mfma_f32_16x16x32_bf16 v[144:147], v[132:135], v[174:177], v[144:147]
	v_mfma_f32_16x16x32_bf16 v[140:143], v[166:169], v[174:177], v[140:143]
	v_mfma_f32_16x16x32_bf16 v[104:107], v[132:135], v[186:189], v[104:107]
	v_mfma_f32_16x16x32_bf16 v[100:103], v[166:169], v[186:189], v[100:103]
	v_mfma_f32_16x16x32_bf16 v[88:91], v[132:135], v[194:197], v[88:91]
	v_mfma_f32_16x16x32_bf16 v[84:87], v[166:169], v[194:197], v[84:87]
	v_mfma_f32_16x16x32_bf16 v[72:75], v[132:135], v[202:205], v[72:75]
	v_mfma_f32_16x16x32_bf16 v[68:71], v[166:169], v[202:205], v[68:71]
	v_mfma_f32_16x16x32_bf16 v[144:147], v[136:139], v[182:185], v[144:147]
	v_mfma_f32_16x16x32_bf16 v[140:143], v[170:173], v[182:185], v[140:143]
	v_mfma_f32_16x16x32_bf16 v[104:107], v[136:139], v[190:193], v[104:107]
	v_mfma_f32_16x16x32_bf16 v[100:103], v[170:173], v[190:193], v[100:103]
	v_mfma_f32_16x16x32_bf16 v[88:91], v[136:139], v[198:201], v[88:91]
	v_mfma_f32_16x16x32_bf16 v[84:87], v[170:173], v[198:201], v[84:87]
	v_mfma_f32_16x16x32_bf16 v[72:75], v[136:139], v[206:209], v[72:75]
	v_mfma_f32_16x16x32_bf16 v[68:71], v[170:173], v[206:209], v[68:71]
	s_barrier
	s_setprio 0
	s_add_i32 s31, s67, s46
	v_lshl_add_u64 v[210:211], s[42:43], 0, v[2:3]
	s_mov_b32 m0, s31
	ds_read_b128 v[174:177], v181 offset:16384
	ds_read_b128 v[182:185], v181 offset:17408
	ds_read_b128 v[186:189], v181 offset:18432
	ds_read_b128 v[190:193], v181 offset:19456
	ds_read_b128 v[194:197], v181 offset:20480
	ds_read_b128 v[198:201], v181 offset:21504
	ds_read_b128 v[202:205], v181 offset:22528
	ds_read_b128 v[206:209], v181 offset:23552
	global_load_lds_dwordx4 v[210:211], off
	s_add_i32 m0, s31, 0x2000
	s_add_u32 s68, s42, 0x80000
	v_lshl_add_u64 v[212:213], s[42:43], 0, v[156:157]
	s_addc_u32 s69, s43, 0
	s_add_i32 s26, s26, s46
	global_load_lds_dwordx4 v[212:213], off
	v_lshl_add_u64 v[214:215], s[68:69], 0, v[2:3]
	s_mov_b32 m0, s26
	v_lshl_add_u64 v[216:217], s[44:45], 0, v[158:159]
	global_load_lds_dwordx4 v[214:215], off
	v_lshl_add_u64 v[214:215], s[68:69], 0, v[156:157]
	s_add_i32 m0, s26, 0x2000
	s_nop 0
	global_load_lds_dwordx4 v[214:215], off
	v_lshl_add_u64 v[214:215], s[44:45], 0, v[160:161]
	s_mov_b32 m0, s47
	s_nop 0
	global_load_lds_dwordx4 v[214:215], off
	s_mov_b32 m0, s50
	s_nop 0
	global_load_lds_dwordx4 v[216:217], off
	s_waitcnt vmcnt(8)
	s_waitcnt lgkmcnt(0)
	s_setprio 3
	s_barrier
	v_mfma_f32_16x16x32_bf16 v[64:67], v[116:119], v[174:177], v[64:67]
	v_mfma_f32_16x16x32_bf16 v[60:63], v[124:127], v[174:177], v[60:63]
	v_mfma_f32_16x16x32_bf16 v[48:51], v[116:119], v[186:189], v[48:51]
	v_mfma_f32_16x16x32_bf16 v[44:47], v[124:127], v[186:189], v[44:47]
	v_mfma_f32_16x16x32_bf16 v[32:35], v[116:119], v[194:197], v[32:35]
	v_mfma_f32_16x16x32_bf16 v[28:31], v[124:127], v[194:197], v[28:31]
	v_mfma_f32_16x16x32_bf16 v[16:19], v[116:119], v[202:205], v[16:19]
	v_mfma_f32_16x16x32_bf16 v[12:15], v[124:127], v[202:205], v[12:15]
	v_mfma_f32_16x16x32_bf16 v[64:67], v[120:123], v[182:185], v[64:67]
	v_mfma_f32_16x16x32_bf16 v[60:63], v[128:131], v[182:185], v[60:63]
	v_mfma_f32_16x16x32_bf16 v[48:51], v[120:123], v[190:193], v[48:51]
	v_mfma_f32_16x16x32_bf16 v[44:47], v[128:131], v[190:193], v[44:47]
	v_mfma_f32_16x16x32_bf16 v[32:35], v[120:123], v[198:201], v[32:35]
	v_mfma_f32_16x16x32_bf16 v[28:31], v[128:131], v[198:201], v[28:31]
	v_mfma_f32_16x16x32_bf16 v[16:19], v[120:123], v[206:209], v[16:19]
	v_mfma_f32_16x16x32_bf16 v[12:15], v[128:131], v[206:209], v[12:15]
	s_setprio 0
	s_setprio 1
	v_mfma_f32_16x16x32_bf16 v[56:59], v[132:135], v[174:177], v[56:59]
	v_mfma_f32_16x16x32_bf16 v[52:55], v[166:169], v[174:177], v[52:55]
	v_mfma_f32_16x16x32_bf16 v[40:43], v[132:135], v[186:189], v[40:43]
	v_mfma_f32_16x16x32_bf16 v[36:39], v[166:169], v[186:189], v[36:39]
	v_mfma_f32_16x16x32_bf16 v[24:27], v[132:135], v[194:197], v[24:27]
	v_mfma_f32_16x16x32_bf16 v[20:23], v[166:169], v[194:197], v[20:23]
	v_mfma_f32_16x16x32_bf16 v[8:11], v[132:135], v[202:205], v[8:11]
	v_mfma_f32_16x16x32_bf16 v[4:7], v[166:169], v[202:205], v[4:7]
	v_mfma_f32_16x16x32_bf16 v[56:59], v[136:139], v[182:185], v[56:59]
	v_mfma_f32_16x16x32_bf16 v[52:55], v[170:173], v[182:185], v[52:55]
	v_mfma_f32_16x16x32_bf16 v[40:43], v[136:139], v[190:193], v[40:43]
	v_mfma_f32_16x16x32_bf16 v[36:39], v[170:173], v[190:193], v[36:39]
	v_mfma_f32_16x16x32_bf16 v[24:27], v[136:139], v[198:201], v[24:27]
	v_mfma_f32_16x16x32_bf16 v[20:23], v[170:173], v[198:201], v[20:23]
	v_mfma_f32_16x16x32_bf16 v[8:11], v[136:139], v[206:209], v[8:11]
	v_mfma_f32_16x16x32_bf16 v[4:7], v[170:173], v[206:209], v[4:7]
	s_barrier
; #define PG8_STAGE(bufoff, gbase, voff) do { _Pragma("unroll") for (int _i = 0; _i < 2; ++_i) \
;         __builtin_amdgcn_global_load_lds((const unsigned*)((const char*)(gbase) + (voff)[_i]), (PG8_LAS unsigned*)(lds + (bufoff) + ldsw + _i * 8192), 16, 0, 0); } while (0)
; #define PG8_LDA(dst, b, h) do { _Pragma("unroll") for (int m = 0; m < 4; ++m) _Pragma("unroll") for (int k = 0; k < 2; ++k) dst[m][k] = *(const PG8_LAS bf16x8*)(lds + PG8_SA(b, h) + aoff + m * 2048 + k * 1024); } while (0)
; #define PG8_LDB(dst, b, h) do { _Pragma("unroll") for (int n = 0; n < 2; ++n) _Pragma("unroll") for (int k = 0; k < 2; ++k) dst[n][k] = *(const PG8_LAS bf16x8*)(lds + PG8_SB(b, h) + boff + n * 2048 + k * 1024); } while (0)
; #define PG8_MMA(ai, bj, At, Bt) do { __builtin_amdgcn_s_setprio(1); _Pragma("unroll") for (int m = 0; m < 4; ++m) _Pragma("unroll") for (int n = 0; n < 2; ++n) _Pragma("unroll") for (int k = 0; k < 2; ++k) \
;         acc[ai][bj][m][n] = __builtin_amdgcn_mfma_f32_16x16x32_bf16(Bt[n][k], At[m][k], acc[ai][bj][m][n], 0, 0, 0); __builtin_amdgcn_s_setprio(0); } while (0)
; #define PG8_WAIT_V(n) asm volatile("s_waitcnt vmcnt(" #n ")" ::: "memory")
; #define PG8_WAIT_L(n) asm volatile("s_waitcnt lgkmcnt(" #n ")" ::: "memory")
; #define PG8_BAR __builtin_amdgcn_s_barrier()
; #define PG8_SCHED __builtin_amdgcn_sched_barrier(0)
; template <class Epi, class Sched, bool ALIGN_EPI = false, bool SP2 = false>
; __device__ __forceinline__ void gemm_phase(PG8_LAS unsigned char* lds, const Gemm g, const Sched& S, const Epi& E) {
;     ...
;             PG8_LDB(B0, 1, 0); PG8_LDB(B1, 1, 1); PG8_SCHED; PG8_LDA(At, 1, 0); PG8_STAGE(PG8_SA(0, 1), a2 + hstep, voffA);
;             PG8_WAIT_V(8); PG8_WAIT_L(0); PG8_BAR; PG8_MMA(0, 0, At, B0); PG8_MMA(0, 1, At, B1); PG8_BAR; PG8_SCHED;
	s_setprio 0
	s_add_i32 s26, 0, 0x18000
	s_add_i32 s31, 0, 0x1c000
	v_add_u32_e32 v128, s26, v178
	v_add_u32_e32 v170, s31, v178
	ds_read_b128 v[116:119], v128
	ds_read_b128 v[120:123], v128 offset:1024
	ds_read_b128 v[124:127], v128 offset:2048
	ds_read_b128 v[128:131], v128 offset:3072
	ds_read_b128 v[132:135], v170
	ds_read_b128 v[136:139], v170 offset:1024
	ds_read_b128 v[166:169], v170 offset:2048
	ds_read_b128 v[170:173], v170 offset:3072
	s_add_u32 s44, s44, 0x80000
	s_addc_u32 s45, s45, 0
	s_mov_b32 m0, s51
	v_lshl_add_u64 v[218:219], s[44:45], 0, v[160:161]
	ds_read_b128 v[174:177], v181 offset:32768
	ds_read_b128 v[182:185], v181 offset:33792
	ds_read_b128 v[186:189], v181 offset:34816
	ds_read_b128 v[190:193], v181 offset:35840
	ds_read_b128 v[194:197], v181 offset:36864
	ds_read_b128 v[198:201], v181 offset:37888
	ds_read_b128 v[202:205], v181 offset:38912
	ds_read_b128 v[206:209], v181 offset:39936
	global_load_lds_dwordx4 v[218:219], off
	v_lshl_add_u64 v[218:219], s[44:45], 0, v[158:159]
	s_mov_b32 m0, s52
	s_nop 0
	global_load_lds_dwordx4 v[218:219], off
	s_waitcnt vmcnt(8)
	s_waitcnt lgkmcnt(0)
	s_setprio 3
	s_barrier
	v_mfma_f32_16x16x32_bf16 v[152:155], v[116:119], v[174:177], v[152:155]
	v_mfma_f32_16x16x32_bf16 v[148:151], v[124:127], v[174:177], v[148:151]
	v_mfma_f32_16x16x32_bf16 v[112:115], v[116:119], v[186:189], v[112:115]
	v_mfma_f32_16x16x32_bf16 v[108:111], v[124:127], v[186:189], v[108:111]
	v_mfma_f32_16x16x32_bf16 v[96:99], v[116:119], v[194:197], v[96:99]
	v_mfma_f32_16x16x32_bf16 v[92:95], v[124:127], v[194:197], v[92:95]
	v_mfma_f32_16x16x32_bf16 v[80:83], v[116:119], v[202:205], v[80:83]
	v_mfma_f32_16x16x32_bf16 v[76:79], v[124:127], v[202:205], v[76:79]
	v_mfma_f32_16x16x32_bf16 v[152:155], v[120:123], v[182:185], v[152:155]
	v_mfma_f32_16x16x32_bf16 v[148:151], v[128:131], v[182:185], v[148:151]
	v_mfma_f32_16x16x32_bf16 v[112:115], v[120:123], v[190:193], v[112:115]
	v_mfma_f32_16x16x32_bf16 v[108:111], v[128:131], v[190:193], v[108:111]
	v_mfma_f32_16x16x32_bf16 v[96:99], v[120:123], v[198:201], v[96:99]
	v_mfma_f32_16x16x32_bf16 v[92:95], v[128:131], v[198:201], v[92:95]
	v_mfma_f32_16x16x32_bf16 v[80:83], v[120:123], v[206:209], v[80:83]
	v_mfma_f32_16x16x32_bf16 v[76:79], v[128:131], v[206:209], v[76:79]
	s_setprio 0
	s_setprio 1
	v_mfma_f32_16x16x32_bf16 v[144:147], v[132:135], v[174:177], v[144:147]
	v_mfma_f32_16x16x32_bf16 v[140:143], v[166:169], v[174:177], v[140:143]
	v_mfma_f32_16x16x32_bf16 v[104:107], v[132:135], v[186:189], v[104:107]
	v_mfma_f32_16x16x32_bf16 v[100:103], v[166:169], v[186:189], v[100:103]
	v_mfma_f32_16x16x32_bf16 v[88:91], v[132:135], v[194:197], v[88:91]
	v_mfma_f32_16x16x32_bf16 v[84:87], v[166:169], v[194:197], v[84:87]
	v_mfma_f32_16x16x32_bf16 v[72:75], v[132:135], v[202:205], v[72:75]
	v_mfma_f32_16x16x32_bf16 v[68:71], v[166:169], v[202:205], v[68:71]
	v_mfma_f32_16x16x32_bf16 v[144:147], v[136:139], v[182:185], v[144:147]
	v_mfma_f32_16x16x32_bf16 v[140:143], v[170:173], v[182:185], v[140:143]
	v_mfma_f32_16x16x32_bf16 v[104:107], v[136:139], v[190:193], v[104:107]
	v_mfma_f32_16x16x32_bf16 v[100:103], v[170:173], v[190:193], v[100:103]
	v_mfma_f32_16x16x32_bf16 v[88:91], v[136:139], v[198:201], v[88:91]
	v_mfma_f32_16x16x32_bf16 v[84:87], v[170:173], v[198:201], v[84:87]
	v_mfma_f32_16x16x32_bf16 v[72:75], v[136:139], v[206:209], v[72:75]
	v_mfma_f32_16x16x32_bf16 v[68:71], v[170:173], v[206:209], v[68:71]
	s_barrier
; #define PG8_STAGE(bufoff, gbase, voff) do { _Pragma("unroll") for (int _i = 0; _i < 2; ++_i) \
;         __builtin_amdgcn_global_load_lds((const unsigned*)((const char*)(gbase) + (voff)[_i]), (PG8_LAS unsigned*)(lds + (bufoff) + ldsw + _i * 8192), 16, 0, 0); } while (0)
; #define PG8_LDA(dst, b, h) do { _Pragma("unroll") for (int m = 0; m < 4; ++m) _Pragma("unroll") for (int k = 0; k < 2; ++k) dst[m][k] = *(const PG8_LAS bf16x8*)(lds + PG8_SA(b, h) + aoff + m * 2048 + k * 1024); } while (0)
; #define PG8_MMA(ai, bj, At, Bt) do { __builtin_amdgcn_s_setprio(1); _Pragma("unroll") for (int m = 0; m < 4; ++m) _Pragma("unroll") for (int n = 0; n < 2; ++n) _Pragma("unroll") for (int k = 0; k < 2; ++k) \
;         acc[ai][bj][m][n] = __builtin_amdgcn_mfma_f32_16x16x32_bf16(Bt[n][k], At[m][k], acc[ai][bj][m][n], 0, 0, 0); __builtin_amdgcn_s_setprio(0); } while (0)
; #define PG8_WAIT_V(n) asm volatile("s_waitcnt vmcnt(" #n ")" ::: "memory")
; #define PG8_WAIT_L(n) asm volatile("s_waitcnt lgkmcnt(" #n ")" ::: "memory")
; #define PG8_BAR __builtin_amdgcn_s_barrier()
; #define PG8_SCHED __builtin_amdgcn_sched_barrier(0)
; template <class Epi, class Sched, bool ALIGN_EPI = false, bool SP2 = false>
; __device__ __forceinline__ void gemm_phase(PG8_LAS unsigned char* lds, const Gemm g, const Sched& S, const Epi& E) {
;     ...
;             PG8_LDA(At, 1, 1); PG8_STAGE(PG8_SB(1, 0), b3, voffB); PG8_STAGE(PG8_SB(1, 1), b3 + hstep, voffB); PG8_STAGE(PG8_SA(1, 0), a3, voffA);
;             PG8_WAIT_V(8); PG8_WAIT_L(0); PG8_BAR; PG8_MMA(1, 0, At, B0); PG8_MMA(1, 1, At, B1); PG8_BAR; PG8_SCHED;
	s_setprio 0
	s_add_i32 s26, s26, s46
	v_lshl_add_u64 v[210:211], v[210:211], 0, s[60:61]
	s_mov_b32 m0, s26
	ds_read_b128 v[174:177], v181 offset:49152
	ds_read_b128 v[182:185], v181 offset:50176
	ds_read_b128 v[186:189], v181 offset:51200
	ds_read_b128 v[190:193], v181 offset:52224
	ds_read_b128 v[194:197], v181 offset:53248
	ds_read_b128 v[198:201], v181 offset:54272
	ds_read_b128 v[202:205], v181 offset:55296
	ds_read_b128 v[206:209], v181 offset:56320
	global_load_lds_dwordx4 v[210:211], off
	s_add_i32 m0, s26, 0x2000
	s_add_u32 s42, s42, 0x80080
	v_lshl_add_u64 v[210:211], v[212:213], 0, s[60:61]
	s_addc_u32 s43, s43, 0
	s_add_i32 s26, s31, s46
	global_load_lds_dwordx4 v[210:211], off
	v_lshl_add_u64 v[210:211], s[42:43], 0, v[2:3]
	s_mov_b32 m0, s26
	s_nop 0
	global_load_lds_dwordx4 v[210:211], off
	v_lshl_add_u64 v[210:211], s[42:43], 0, v[156:157]
	s_add_i32 m0, s26, 0x2000
	s_nop 0
	global_load_lds_dwordx4 v[210:211], off
	v_lshl_add_u64 v[210:211], v[214:215], 0, s[60:61]
	s_mov_b32 m0, s54
	s_nop 0
	global_load_lds_dwordx4 v[210:211], off
	v_lshl_add_u64 v[210:211], v[216:217], 0, s[60:61]
	s_mov_b32 m0, s55
	s_nop 0
	global_load_lds_dwordx4 v[210:211], off
	s_waitcnt vmcnt(8)
	s_waitcnt lgkmcnt(0)
	s_setprio 3
	s_barrier
	v_mfma_f32_16x16x32_bf16 v[64:67], v[116:119], v[174:177], v[64:67]
	v_mfma_f32_16x16x32_bf16 v[60:63], v[124:127], v[174:177], v[60:63]
	v_mfma_f32_16x16x32_bf16 v[48:51], v[116:119], v[186:189], v[48:51]
	v_mfma_f32_16x16x32_bf16 v[44:47], v[124:127], v[186:189], v[44:47]
	v_mfma_f32_16x16x32_bf16 v[32:35], v[116:119], v[194:197], v[32:35]
	v_mfma_f32_16x16x32_bf16 v[28:31], v[124:127], v[194:197], v[28:31]
	v_mfma_f32_16x16x32_bf16 v[16:19], v[116:119], v[202:205], v[16:19]
	v_mfma_f32_16x16x32_bf16 v[12:15], v[124:127], v[202:205], v[12:15]
	v_mfma_f32_16x16x32_bf16 v[64:67], v[120:123], v[182:185], v[64:67]
	v_mfma_f32_16x16x32_bf16 v[60:63], v[128:131], v[182:185], v[60:63]
	v_mfma_f32_16x16x32_bf16 v[48:51], v[120:123], v[190:193], v[48:51]
	v_mfma_f32_16x16x32_bf16 v[44:47], v[128:131], v[190:193], v[44:47]
	v_mfma_f32_16x16x32_bf16 v[32:35], v[120:123], v[198:201], v[32:35]
	v_mfma_f32_16x16x32_bf16 v[28:31], v[128:131], v[198:201], v[28:31]
	v_mfma_f32_16x16x32_bf16 v[16:19], v[120:123], v[206:209], v[16:19]
	v_mfma_f32_16x16x32_bf16 v[12:15], v[128:131], v[206:209], v[12:15]
	s_setprio 0
	s_setprio 1
	v_mfma_f32_16x16x32_bf16 v[56:59], v[132:135], v[174:177], v[56:59]
	v_mfma_f32_16x16x32_bf16 v[52:55], v[166:169], v[174:177], v[52:55]
	v_mfma_f32_16x16x32_bf16 v[40:43], v[132:135], v[186:189], v[40:43]
	v_mfma_f32_16x16x32_bf16 v[36:39], v[166:169], v[186:189], v[36:39]
	v_mfma_f32_16x16x32_bf16 v[24:27], v[132:135], v[194:197], v[24:27]
	v_mfma_f32_16x16x32_bf16 v[20:23], v[166:169], v[194:197], v[20:23]
	v_mfma_f32_16x16x32_bf16 v[8:11], v[132:135], v[202:205], v[8:11]
	v_mfma_f32_16x16x32_bf16 v[4:7], v[166:169], v[202:205], v[4:7]
	v_mfma_f32_16x16x32_bf16 v[56:59], v[136:139], v[182:185], v[56:59]
	v_mfma_f32_16x16x32_bf16 v[52:55], v[170:173], v[182:185], v[52:55]
	v_mfma_f32_16x16x32_bf16 v[40:43], v[136:139], v[190:193], v[40:43]
	v_mfma_f32_16x16x32_bf16 v[36:39], v[170:173], v[190:193], v[36:39]
	v_mfma_f32_16x16x32_bf16 v[24:27], v[136:139], v[198:201], v[24:27]
	v_mfma_f32_16x16x32_bf16 v[20:23], v[170:173], v[198:201], v[20:23]
	v_mfma_f32_16x16x32_bf16 v[8:11], v[136:139], v[206:209], v[8:11]
	v_mfma_f32_16x16x32_bf16 v[4:7], v[170:173], v[206:209], v[4:7]
	s_barrier
	s_setprio 0
	s_add_i32 s66, s66, 2
	s_add_u32 s38, s38, 0x100
	s_addc_u32 s39, s39, 0
	s_add_u32 s63, s63, 0x100
	s_addc_u32 s64, s64, 0
	s_cmp_gt_u32 s66, 29
	s_cbranch_scc0 .LBB0_1961

; #define PG8_STAGE(bufoff, gbase, voff) do { _Pragma("unroll") for (int _i = 0; _i < 2; ++_i) \
;         __builtin_amdgcn_global_load_lds((const unsigned*)((const char*)(gbase) + (voff)[_i]), (PG8_LAS unsigned*)(lds + (bufoff) + ldsw + _i * 8192), 16, 0, 0); } while (0)
; #define PG8_LDA(dst, b, h) do { _Pragma("unroll") for (int m = 0; m < 4; ++m) _Pragma("unroll") for (int k = 0; k < 2; ++k) dst[m][k] = *(const PG8_LAS bf16x8*)(lds + PG8_SA(b, h) + aoff + m * 2048 + k * 1024); } while (0)
; #define PG8_LDB(dst, b, h) do { _Pragma("unroll") for (int n = 0; n < 2; ++n) _Pragma("unroll") for (int k = 0; k < 2; ++k) dst[n][k] = *(const PG8_LAS bf16x8*)(lds + PG8_SB(b, h) + boff + n * 2048 + k * 1024); } while (0)
; #define PG8_WAIT_V(n) asm volatile("s_waitcnt vmcnt(" #n ")" ::: "memory")
; #define PG8_WAIT_L(n) asm volatile("s_waitcnt lgkmcnt(" #n ")" ::: "memory")
; #define PG8_BAR __builtin_amdgcn_s_barrier()
; #define PG8_SCHED __builtin_amdgcn_sched_barrier(0)
; template <class Epi, class Sched, bool ALIGN_EPI = false, bool SP2 = false>
; __device__ __forceinline__ void gemm_phase(PG8_LAS unsigned char* lds, const Gemm g, const Sched& S, const Epi& E) {
;     ...
;         const bool has_next = S.next(ui + 1, nxt);
;         const char* nA = has_next ? (const char*)g.A + (size_t)nxt.pm * tstep : cA; const char* nB = has_next ? (const char*)g.Bt + (size_t)nxt.pn * tstep : cB;
;         for (int t = 0; t < nt; t += 2) {
;             const bool last = (t == nt - 2);
;             const char* a1 = cA + (size_t)(t + 1) * kstep;
;             const char* a2 = last ? nA : cA + (size_t)(t + 2) * kstep; const char* b2 = last ? nB : cB + (size_t)(t + 2) * kstep;
;             const char* a3 = a2 + kstep; const char* b3 = b2 + kstep;
;             if (last && has_next) S.a_ready(nxt);
;             if constexpr (SP2) {
;             PG8_LDB(B0, 0, 0); PG8_LDB(B1, 0, 1); PG8_SCHED; PG8_LDA(At, 0, 0); PG8_STAGE(PG8_SA(1, 1), a1 + hstep, voffA);
;             PG8_WAIT_V(8); PG8_WAIT_L(0); PG8_BAR; PG8_MMA(0, 0, At, B0); PG8_MMA(0, 1, At, B1); PG8_BAR; PG8_SCHED;
;             PG8_LDA(At, 0, 1); PG8_STAGE(PG8_SB(0, 0), b2, voffB); PG8_STAGE(PG8_SB(0, 1), b2 + hstep, voffB); PG8_STAGE(PG8_SA(0, 0), a2, voffA);
;             PG8_WAIT_V(8); PG8_WAIT_L(0); PG8_BAR; PG8_MMA(1, 0, At, B0); PG8_MMA(1, 1, At, B1); PG8_BAR; PG8_SCHED;
.LBB0_2103:
	s_ashr_i32 s17, s16, 31
	s_lshl_b64 s[18:19], s[16:17], 20
	s_add_u32 s18, s2, s18
	s_addc_u32 s19, s3, s19
	s_and_b64 s[20:21], s[4:5], exec
	s_cselect_b32 s17, s19, s35
	s_cselect_b32 s52, s18, s34
	s_ashr_i32 s15, s14, 31
	s_lshl_b64 s[20:21], s[14:15], 20
	s_add_u32 s20, s29, s20
	s_addc_u32 s21, s40, s21
	s_and_b64 s[38:39], s[4:5], exec
	s_cselect_b32 s15, s21, s37
	s_cselect_b32 s53, s20, s36
	s_add_u32 s34, s34, 0x80080
	s_addc_u32 s35, s35, 0
	s_add_u32 s54, s36, 0x100
	s_addc_u32 s55, s37, 0
	s_mov_b32 s56, -2
	s_add_u32 s26, s34, 0xfff80080
	s_addc_u32 s31, s35, -1
	s_add_i32 s57, 0, 0x10000
	s_cmp_eq_u32 s56, 28
	s_cselect_b32 s39, s17, s31
	s_cselect_b32 s38, s52, s26
	v_add_u32_e32 v149, s57, v146
	s_cselect_b32 s37, s15, s55
	s_cselect_b32 s36, s53, s54
	s_add_i32 s26, 0, 0x14000
	ds_read_b128 v[142:145], v149
	ds_read_b128 v[150:153], v149 offset:1024
	ds_read_b128 v[154:157], v149 offset:2048
	ds_read_b128 v[158:161], v149 offset:3072
	v_add_u32_e32 v149, s26, v146
	ds_read_b128 v[162:165], v149
	ds_read_b128 v[166:169], v149 offset:1024
	ds_read_b128 v[170:173], v149 offset:2048
	ds_read_b128 v[174:177], v149 offset:3072
	v_lshl_add_u64 v[178:179], s[34:35], 0, v[138:139]
	s_add_i32 m0, s43, 0xc000
	ds_read_b128 v[182:185], v148
	ds_read_b128 v[186:189], v148 offset:1024
	ds_read_b128 v[190:193], v148 offset:2048
	ds_read_b128 v[194:197], v148 offset:3072
	ds_read_b128 v[198:201], v148 offset:4096
	ds_read_b128 v[202:205], v148 offset:5120
	ds_read_b128 v[206:209], v148 offset:6144
	ds_read_b128 v[210:213], v148 offset:7168
	global_load_lds_dwordx4 v[178:179], off
	v_lshl_add_u64 v[178:179], s[34:35], 0, v[140:141]
	s_add_i32 m0, s43, 0xe000
	s_nop 0
	global_load_lds_dwordx4 v[178:179], off
	s_waitcnt vmcnt(8)
	s_waitcnt lgkmcnt(0)
	s_setprio 3
	s_barrier
	v_mfma_f32_16x16x32_bf16 v[128:131], v[142:145], v[182:185], 0
	v_mfma_f32_16x16x32_bf16 v[124:127], v[154:157], v[182:185], 0
	v_mfma_f32_16x16x32_bf16 v[112:115], v[142:145], v[190:193], 0
	v_mfma_f32_16x16x32_bf16 v[108:111], v[154:157], v[190:193], 0
	v_mfma_f32_16x16x32_bf16 v[96:99], v[142:145], v[198:201], 0
	v_mfma_f32_16x16x32_bf16 v[92:95], v[154:157], v[198:201], 0
	v_mfma_f32_16x16x32_bf16 v[80:83], v[142:145], v[206:209], 0
	v_mfma_f32_16x16x32_bf16 v[76:79], v[154:157], v[206:209], 0
	v_mfma_f32_16x16x32_bf16 v[128:131], v[150:153], v[186:189], v[128:131]
	v_mfma_f32_16x16x32_bf16 v[124:127], v[158:161], v[186:189], v[124:127]
	v_mfma_f32_16x16x32_bf16 v[112:115], v[150:153], v[194:197], v[112:115]
	v_mfma_f32_16x16x32_bf16 v[108:111], v[158:161], v[194:197], v[108:111]
	v_mfma_f32_16x16x32_bf16 v[96:99], v[150:153], v[202:205], v[96:99]
	v_mfma_f32_16x16x32_bf16 v[92:95], v[158:161], v[202:205], v[92:95]
	v_mfma_f32_16x16x32_bf16 v[80:83], v[150:153], v[210:213], v[80:83]
	v_mfma_f32_16x16x32_bf16 v[76:79], v[158:161], v[210:213], v[76:79]
	s_setprio 0
	s_setprio 1
	v_mfma_f32_16x16x32_bf16 v[120:123], v[162:165], v[182:185], 0
	v_mfma_f32_16x16x32_bf16 v[116:119], v[170:173], v[182:185], 0
	v_mfma_f32_16x16x32_bf16 v[104:107], v[162:165], v[190:193], 0
	v_mfma_f32_16x16x32_bf16 v[100:103], v[170:173], v[190:193], 0
	v_mfma_f32_16x16x32_bf16 v[88:91], v[162:165], v[198:201], 0
	v_mfma_f32_16x16x32_bf16 v[84:87], v[170:173], v[198:201], 0
	v_mfma_f32_16x16x32_bf16 v[72:75], v[162:165], v[206:209], 0
	v_mfma_f32_16x16x32_bf16 v[68:71], v[170:173], v[206:209], 0
	v_mfma_f32_16x16x32_bf16 v[120:123], v[166:169], v[186:189], v[120:123]
	v_mfma_f32_16x16x32_bf16 v[116:119], v[174:177], v[186:189], v[116:119]
	v_mfma_f32_16x16x32_bf16 v[104:107], v[166:169], v[194:197], v[104:107]
	v_mfma_f32_16x16x32_bf16 v[100:103], v[174:177], v[194:197], v[100:103]
	v_mfma_f32_16x16x32_bf16 v[88:91], v[166:169], v[202:205], v[88:91]
	v_mfma_f32_16x16x32_bf16 v[84:87], v[174:177], v[202:205], v[84:87]
	v_mfma_f32_16x16x32_bf16 v[72:75], v[166:169], v[210:213], v[72:75]
	v_mfma_f32_16x16x32_bf16 v[68:71], v[174:177], v[210:213], v[68:71]
	s_barrier
	s_setprio 0
	s_add_i32 s31, s57, s42
	v_lshl_add_u64 v[178:179], s[36:37], 0, v[2:3]
	s_mov_b32 m0, s31
	ds_read_b128 v[182:185], v148 offset:16384
	ds_read_b128 v[186:189], v148 offset:17408
	ds_read_b128 v[190:193], v148 offset:18432
	ds_read_b128 v[194:197], v148 offset:19456
	ds_read_b128 v[198:201], v148 offset:20480
	ds_read_b128 v[202:205], v148 offset:21504
	ds_read_b128 v[206:209], v148 offset:22528
	ds_read_b128 v[210:213], v148 offset:23552
	global_load_lds_dwordx4 v[178:179], off
	s_add_i32 m0, s31, 0x2000
	s_add_u32 s62, s36, 0x80000
	v_lshl_add_u64 v[214:215], s[36:37], 0, v[132:133]
	s_addc_u32 s63, s37, 0
	s_add_i32 s26, s26, s42
	global_load_lds_dwordx4 v[214:215], off
	v_lshl_add_u64 v[216:217], s[62:63], 0, v[2:3]
	s_mov_b32 m0, s26
	v_lshl_add_u64 v[218:219], s[38:39], 0, v[134:135]
	global_load_lds_dwordx4 v[216:217], off
	v_lshl_add_u64 v[216:217], s[62:63], 0, v[132:133]
	s_add_i32 m0, s26, 0x2000
	s_nop 0
	global_load_lds_dwordx4 v[216:217], off
	v_lshl_add_u64 v[216:217], s[38:39], 0, v[136:137]
	s_mov_b32 m0, s43
	s_nop 0
	global_load_lds_dwordx4 v[216:217], off
	s_mov_b32 m0, s44
	s_nop 0
	global_load_lds_dwordx4 v[218:219], off
	s_waitcnt vmcnt(8)
	s_waitcnt lgkmcnt(0)
	s_setprio 3
	s_barrier
; #define PG8_STAGE(bufoff, gbase, voff) do { _Pragma("unroll") for (int _i = 0; _i < 2; ++_i) \
;         __builtin_amdgcn_global_load_lds((const unsigned*)((const char*)(gbase) + (voff)[_i]), (PG8_LAS unsigned*)(lds + (bufoff) + ldsw + _i * 8192), 16, 0, 0); } while (0)
; #define PG8_LDA(dst, b, h) do { _Pragma("unroll") for (int m = 0; m < 4; ++m) _Pragma("unroll") for (int k = 0; k < 2; ++k) dst[m][k] = *(const PG8_LAS bf16x8*)(lds + PG8_SA(b, h) + aoff + m * 2048 + k * 1024); } while (0)
; #define PG8_LDB(dst, b, h) do { _Pragma("unroll") for (int n = 0; n < 2; ++n) _Pragma("unroll") for (int k = 0; k < 2; ++k) dst[n][k] = *(const PG8_LAS bf16x8*)(lds + PG8_SB(b, h) + boff + n * 2048 + k * 1024); } while (0)
; #define PG8_MMA(ai, bj, At, Bt) do { __builtin_amdgcn_s_setprio(1); _Pragma("unroll") for (int m = 0; m < 4; ++m) _Pragma("unroll") for (int n = 0; n < 2; ++n) _Pragma("unroll") for (int k = 0; k < 2; ++k) \
;         acc[ai][bj][m][n] = __builtin_amdgcn_mfma_f32_16x16x32_bf16(Bt[n][k], At[m][k], acc[ai][bj][m][n], 0, 0, 0); __builtin_amdgcn_s_setprio(0); } while (0)
; #define PG8_WAIT_V(n) asm volatile("s_waitcnt vmcnt(" #n ")" ::: "memory")
; #define PG8_WAIT_L(n) asm volatile("s_waitcnt lgkmcnt(" #n ")" ::: "memory")
; #define PG8_BAR __builtin_amdgcn_s_barrier()
; #define PG8_SCHED __builtin_amdgcn_sched_barrier(0)
; template <class Epi, class Sched, bool ALIGN_EPI = false, bool SP2 = false>
; __device__ __forceinline__ void gemm_phase(PG8_LAS unsigned char* lds, const Gemm g, const Sched& S, const Epi& E) {
;     ...
;             PG8_WAIT_V(8); PG8_WAIT_L(0); PG8_BAR; PG8_MMA(1, 0, At, B0); PG8_MMA(1, 1, At, B1); PG8_BAR; PG8_SCHED;
;             PG8_LDB(B0, 1, 0); PG8_LDB(B1, 1, 1); PG8_SCHED; PG8_LDA(At, 1, 0); PG8_STAGE(PG8_SA(0, 1), a2 + hstep, voffA);
;             PG8_WAIT_V(8); PG8_WAIT_L(0); PG8_BAR; PG8_MMA(0, 0, At, B0); PG8_MMA(0, 1, At, B1); PG8_BAR; PG8_SCHED;
	v_mfma_f32_16x16x32_bf16 v[64:67], v[142:145], v[182:185], 0
	v_mfma_f32_16x16x32_bf16 v[60:63], v[154:157], v[182:185], 0
	v_mfma_f32_16x16x32_bf16 v[48:51], v[142:145], v[190:193], 0
	v_mfma_f32_16x16x32_bf16 v[44:47], v[154:157], v[190:193], 0
	v_mfma_f32_16x16x32_bf16 v[32:35], v[142:145], v[198:201], 0
	v_mfma_f32_16x16x32_bf16 v[28:31], v[154:157], v[198:201], 0
	v_mfma_f32_16x16x32_bf16 v[16:19], v[142:145], v[206:209], 0
	v_mfma_f32_16x16x32_bf16 v[12:15], v[154:157], v[206:209], 0
	v_mfma_f32_16x16x32_bf16 v[64:67], v[150:153], v[186:189], v[64:67]
	v_mfma_f32_16x16x32_bf16 v[60:63], v[158:161], v[186:189], v[60:63]
	v_mfma_f32_16x16x32_bf16 v[48:51], v[150:153], v[194:197], v[48:51]
	v_mfma_f32_16x16x32_bf16 v[44:47], v[158:161], v[194:197], v[44:47]
	v_mfma_f32_16x16x32_bf16 v[32:35], v[150:153], v[202:205], v[32:35]
	v_mfma_f32_16x16x32_bf16 v[28:31], v[158:161], v[202:205], v[28:31]
	v_mfma_f32_16x16x32_bf16 v[16:19], v[150:153], v[210:213], v[16:19]
	v_mfma_f32_16x16x32_bf16 v[12:15], v[158:161], v[210:213], v[12:15]
	s_setprio 0
	s_setprio 1
	v_mfma_f32_16x16x32_bf16 v[56:59], v[162:165], v[182:185], 0
	v_mfma_f32_16x16x32_bf16 v[52:55], v[170:173], v[182:185], 0
	v_mfma_f32_16x16x32_bf16 v[40:43], v[162:165], v[190:193], 0
	v_mfma_f32_16x16x32_bf16 v[36:39], v[170:173], v[190:193], 0
	v_mfma_f32_16x16x32_bf16 v[24:27], v[162:165], v[198:201], 0
	v_mfma_f32_16x16x32_bf16 v[20:23], v[170:173], v[198:201], 0
	v_mfma_f32_16x16x32_bf16 v[8:11], v[162:165], v[206:209], 0
	v_mfma_f32_16x16x32_bf16 v[4:7], v[170:173], v[206:209], 0
	v_mfma_f32_16x16x32_bf16 v[56:59], v[166:169], v[186:189], v[56:59]
	v_mfma_f32_16x16x32_bf16 v[52:55], v[174:177], v[186:189], v[52:55]
	v_mfma_f32_16x16x32_bf16 v[40:43], v[166:169], v[194:197], v[40:43]
	v_mfma_f32_16x16x32_bf16 v[36:39], v[174:177], v[194:197], v[36:39]
	v_mfma_f32_16x16x32_bf16 v[24:27], v[166:169], v[202:205], v[24:27]
	v_mfma_f32_16x16x32_bf16 v[20:23], v[174:177], v[202:205], v[20:23]
	v_mfma_f32_16x16x32_bf16 v[8:11], v[166:169], v[210:213], v[8:11]
	v_mfma_f32_16x16x32_bf16 v[4:7], v[174:177], v[210:213], v[4:7]
	s_barrier
	s_setprio 0
	s_add_i32 s26, 0, 0x18000
	v_add_u32_e32 v149, s26, v146
	s_add_i32 s31, 0, 0x1c000
	ds_read_b128 v[142:145], v149
	ds_read_b128 v[150:153], v149 offset:1024
	ds_read_b128 v[154:157], v149 offset:2048
	ds_read_b128 v[158:161], v149 offset:3072
	v_add_u32_e32 v149, s31, v146
	ds_read_b128 v[162:165], v149
	ds_read_b128 v[166:169], v149 offset:1024
	ds_read_b128 v[170:173], v149 offset:2048
	ds_read_b128 v[174:177], v149 offset:3072
	s_add_u32 s38, s38, 0x80000
	s_addc_u32 s39, s39, 0
	s_mov_b32 m0, s45
	v_lshl_add_u64 v[220:221], s[38:39], 0, v[136:137]
	ds_read_b128 v[182:185], v148 offset:32768
	ds_read_b128 v[186:189], v148 offset:33792
	ds_read_b128 v[190:193], v148 offset:34816
	ds_read_b128 v[194:197], v148 offset:35840
	ds_read_b128 v[198:201], v148 offset:36864
	ds_read_b128 v[202:205], v148 offset:37888
	ds_read_b128 v[206:209], v148 offset:38912
	ds_read_b128 v[210:213], v148 offset:39936
	global_load_lds_dwordx4 v[220:221], off
	v_lshl_add_u64 v[220:221], s[38:39], 0, v[134:135]
	s_mov_b32 m0, s46
	s_nop 0
	global_load_lds_dwordx4 v[220:221], off
	s_waitcnt vmcnt(8)
	s_waitcnt lgkmcnt(0)
	s_setprio 3
	s_barrier
	v_mfma_f32_16x16x32_bf16 v[128:131], v[142:145], v[182:185], v[128:131]
	v_mfma_f32_16x16x32_bf16 v[124:127], v[154:157], v[182:185], v[124:127]
	v_mfma_f32_16x16x32_bf16 v[112:115], v[142:145], v[190:193], v[112:115]
	v_mfma_f32_16x16x32_bf16 v[108:111], v[154:157], v[190:193], v[108:111]
	v_mfma_f32_16x16x32_bf16 v[96:99], v[142:145], v[198:201], v[96:99]
	v_mfma_f32_16x16x32_bf16 v[92:95], v[154:157], v[198:201], v[92:95]
	v_mfma_f32_16x16x32_bf16 v[80:83], v[142:145], v[206:209], v[80:83]
	v_mfma_f32_16x16x32_bf16 v[76:79], v[154:157], v[206:209], v[76:79]
	v_mfma_f32_16x16x32_bf16 v[128:131], v[150:153], v[186:189], v[128:131]
	v_mfma_f32_16x16x32_bf16 v[124:127], v[158:161], v[186:189], v[124:127]
	v_mfma_f32_16x16x32_bf16 v[112:115], v[150:153], v[194:197], v[112:115]
	v_mfma_f32_16x16x32_bf16 v[108:111], v[158:161], v[194:197], v[108:111]
	v_mfma_f32_16x16x32_bf16 v[96:99], v[150:153], v[202:205], v[96:99]
	v_mfma_f32_16x16x32_bf16 v[92:95], v[158:161], v[202:205], v[92:95]
	v_mfma_f32_16x16x32_bf16 v[80:83], v[150:153], v[210:213], v[80:83]
	v_mfma_f32_16x16x32_bf16 v[76:79], v[158:161], v[210:213], v[76:79]
	s_setprio 0
	s_setprio 1
	v_mfma_f32_16x16x32_bf16 v[120:123], v[162:165], v[182:185], v[120:123]
	v_mfma_f32_16x16x32_bf16 v[116:119], v[170:173], v[182:185], v[116:119]
	v_mfma_f32_16x16x32_bf16 v[104:107], v[162:165], v[190:193], v[104:107]
	v_mfma_f32_16x16x32_bf16 v[100:103], v[170:173], v[190:193], v[100:103]
	v_mfma_f32_16x16x32_bf16 v[88:91], v[162:165], v[198:201], v[88:91]
	v_mfma_f32_16x16x32_bf16 v[84:87], v[170:173], v[198:201], v[84:87]
	v_mfma_f32_16x16x32_bf16 v[72:75], v[162:165], v[206:209], v[72:75]
	v_mfma_f32_16x16x32_bf16 v[68:71], v[170:173], v[206:209], v[68:71]
	v_mfma_f32_16x16x32_bf16 v[120:123], v[166:169], v[186:189], v[120:123]
	v_mfma_f32_16x16x32_bf16 v[116:119], v[174:177], v[186:189], v[116:119]
	v_mfma_f32_16x16x32_bf16 v[104:107], v[166:169], v[194:197], v[104:107]
	v_mfma_f32_16x16x32_bf16 v[100:103], v[174:177], v[194:197], v[100:103]
	v_mfma_f32_16x16x32_bf16 v[88:91], v[166:169], v[202:205], v[88:91]
	v_mfma_f32_16x16x32_bf16 v[84:87], v[174:177], v[202:205], v[84:87]
	v_mfma_f32_16x16x32_bf16 v[72:75], v[166:169], v[210:213], v[72:75]
	v_mfma_f32_16x16x32_bf16 v[68:71], v[174:177], v[210:213], v[68:71]
	s_barrier
; #define PG8_STAGE(bufoff, gbase, voff) do { _Pragma("unroll") for (int _i = 0; _i < 2; ++_i) \
;         __builtin_amdgcn_global_load_lds((const unsigned*)((const char*)(gbase) + (voff)[_i]), (PG8_LAS unsigned*)(lds + (bufoff) + ldsw + _i * 8192), 16, 0, 0); } while (0)
; #define PG8_LDA(dst, b, h) do { _Pragma("unroll") for (int m = 0; m < 4; ++m) _Pragma("unroll") for (int k = 0; k < 2; ++k) dst[m][k] = *(const PG8_LAS bf16x8*)(lds + PG8_SA(b, h) + aoff + m * 2048 + k * 1024); } while (0)
; #define PG8_LDB(dst, b, h) do { _Pragma("unroll") for (int n = 0; n < 2; ++n) _Pragma("unroll") for (int k = 0; k < 2; ++k) dst[n][k] = *(const PG8_LAS bf16x8*)(lds + PG8_SB(b, h) + boff + n * 2048 + k * 1024); } while (0)
; #define PG8_BAR __builtin_amdgcn_s_barrier()
; template <class Epi, class Sched, bool ALIGN_EPI = false, bool SP2 = false>
; __device__ __forceinline__ void gemm_phase(PG8_LAS unsigned char* lds, const Gemm g, const Sched& S, const Epi& E) {
;     ...
;             const bool last = (t == nt - 2);
;             const char* a1 = cA + (size_t)(t + 1) * kstep;
;             const char* a2 = last ? nA : cA + (size_t)(t + 2) * kstep; const char* b2 = last ? nB : cB + (size_t)(t + 2) * kstep;
;             const char* a3 = a2 + kstep; const char* b3 = b2 + kstep;
;             if (last && has_next) S.a_ready(nxt);
;             if constexpr (SP2) {
;             PG8_LDB(B0, 0, 0); PG8_LDB(B1, 0, 1); PG8_SCHED; PG8_LDA(At, 0, 0); PG8_STAGE(PG8_SA(1, 1), a1 + hstep, voffA);
;             PG8_WAIT_V(8); PG8_WAIT_L(0); PG8_BAR; PG8_MMA(0, 0, At, B0); PG8_MMA(0, 1, At, B1); PG8_BAR; PG8_SCHED;
;             PG8_LDA(At, 0, 1); PG8_STAGE(PG8_SB(0, 0), b2, voffB); PG8_STAGE(PG8_SB(0, 1), b2 + hstep, voffB); PG8_STAGE(PG8_SA(0, 0), a2, voffA);
;             PG8_WAIT_V(8); PG8_WAIT_L(0); PG8_BAR; PG8_MMA(1, 0, At, B0); PG8_MMA(1, 1, At, B1); PG8_BAR; PG8_SCHED;
;             PG8_LDB(B0, 1, 0); PG8_LDB(B1, 1, 1); PG8_SCHED; PG8_LDA(At, 1, 0); PG8_STAGE(PG8_SA(0, 1), a2 + hstep, voffA);
;             PG8_WAIT_V(8); PG8_WAIT_L(0); PG8_BAR; PG8_MMA(0, 0, At, B0); PG8_MMA(0, 1, At, B1); PG8_BAR; PG8_SCHED;
;             PG8_LDA(At, 1, 1); PG8_STAGE(PG8_SB(1, 0), b3, voffB); PG8_STAGE(PG8_SB(1, 1), b3 + hstep, voffB); PG8_STAGE(PG8_SA(1, 0), a3, voffA);
;             PG8_WAIT_V(8); PG8_WAIT_L(0); PG8_BAR; PG8_MMA(1, 0, At, B0); PG8_MMA(1, 1, At, B1); PG8_BAR; PG8_SCHED;
	s_setprio 0
	s_add_i32 s26, s26, s42
	v_lshl_add_u64 v[178:179], v[178:179], 0, s[60:61]
	s_mov_b32 m0, s26
	ds_read_b128 v[182:185], v148 offset:49152
	ds_read_b128 v[186:189], v148 offset:50176
	ds_read_b128 v[190:193], v148 offset:51200
	ds_read_b128 v[194:197], v148 offset:52224
	ds_read_b128 v[198:201], v148 offset:53248
	ds_read_b128 v[202:205], v148 offset:54272
	ds_read_b128 v[206:209], v148 offset:55296
	ds_read_b128 v[210:213], v148 offset:56320
	global_load_lds_dwordx4 v[178:179], off
	s_add_i32 m0, s26, 0x2000
	s_add_u32 s36, s36, 0x80080
	v_lshl_add_u64 v[178:179], v[214:215], 0, s[60:61]
	s_addc_u32 s37, s37, 0
	s_add_i32 s26, s31, s42
	global_load_lds_dwordx4 v[178:179], off
	v_lshl_add_u64 v[178:179], s[36:37], 0, v[2:3]
	s_mov_b32 m0, s26
	s_nop 0
	global_load_lds_dwordx4 v[178:179], off
	v_lshl_add_u64 v[178:179], s[36:37], 0, v[132:133]
	s_add_i32 m0, s26, 0x2000
	s_nop 0
	global_load_lds_dwordx4 v[178:179], off
	v_lshl_add_u64 v[178:179], v[216:217], 0, s[60:61]
	s_mov_b32 m0, s47
	s_nop 0
	global_load_lds_dwordx4 v[178:179], off
	v_lshl_add_u64 v[178:179], v[218:219], 0, s[60:61]
	s_mov_b32 m0, s50
	s_nop 0
	global_load_lds_dwordx4 v[178:179], off
	s_waitcnt vmcnt(8)
	s_waitcnt lgkmcnt(0)
	s_setprio 3
	s_barrier
	v_mfma_f32_16x16x32_bf16 v[64:67], v[142:145], v[182:185], v[64:67]
	v_mfma_f32_16x16x32_bf16 v[60:63], v[154:157], v[182:185], v[60:63]
	v_mfma_f32_16x16x32_bf16 v[48:51], v[142:145], v[190:193], v[48:51]
	v_mfma_f32_16x16x32_bf16 v[44:47], v[154:157], v[190:193], v[44:47]
	v_mfma_f32_16x16x32_bf16 v[32:35], v[142:145], v[198:201], v[32:35]
	v_mfma_f32_16x16x32_bf16 v[28:31], v[154:157], v[198:201], v[28:31]
	v_mfma_f32_16x16x32_bf16 v[16:19], v[142:145], v[206:209], v[16:19]
	v_mfma_f32_16x16x32_bf16 v[12:15], v[154:157], v[206:209], v[12:15]
	v_mfma_f32_16x16x32_bf16 v[64:67], v[150:153], v[186:189], v[64:67]
	v_mfma_f32_16x16x32_bf16 v[60:63], v[158:161], v[186:189], v[60:63]
	v_mfma_f32_16x16x32_bf16 v[48:51], v[150:153], v[194:197], v[48:51]
	v_mfma_f32_16x16x32_bf16 v[44:47], v[158:161], v[194:197], v[44:47]
	v_mfma_f32_16x16x32_bf16 v[32:35], v[150:153], v[202:205], v[32:35]
	v_mfma_f32_16x16x32_bf16 v[28:31], v[158:161], v[202:205], v[28:31]
	v_mfma_f32_16x16x32_bf16 v[16:19], v[150:153], v[210:213], v[16:19]
	v_mfma_f32_16x16x32_bf16 v[12:15], v[158:161], v[210:213], v[12:15]
	s_setprio 0
	s_setprio 1
	v_mfma_f32_16x16x32_bf16 v[56:59], v[162:165], v[182:185], v[56:59]
	v_mfma_f32_16x16x32_bf16 v[52:55], v[170:173], v[182:185], v[52:55]
	v_mfma_f32_16x16x32_bf16 v[40:43], v[162:165], v[190:193], v[40:43]
	v_mfma_f32_16x16x32_bf16 v[36:39], v[170:173], v[190:193], v[36:39]
	v_mfma_f32_16x16x32_bf16 v[24:27], v[162:165], v[198:201], v[24:27]
	v_mfma_f32_16x16x32_bf16 v[20:23], v[170:173], v[198:201], v[20:23]
	v_mfma_f32_16x16x32_bf16 v[8:11], v[162:165], v[206:209], v[8:11]
	v_mfma_f32_16x16x32_bf16 v[4:7], v[170:173], v[206:209], v[4:7]
	v_mfma_f32_16x16x32_bf16 v[56:59], v[166:169], v[186:189], v[56:59]
	v_mfma_f32_16x16x32_bf16 v[52:55], v[174:177], v[186:189], v[52:55]
	v_mfma_f32_16x16x32_bf16 v[40:43], v[166:169], v[194:197], v[40:43]
	v_mfma_f32_16x16x32_bf16 v[36:39], v[174:177], v[194:197], v[36:39]
	v_mfma_f32_16x16x32_bf16 v[24:27], v[166:169], v[202:205], v[24:27]
	v_mfma_f32_16x16x32_bf16 v[20:23], v[174:177], v[202:205], v[20:23]
	v_mfma_f32_16x16x32_bf16 v[8:11], v[166:169], v[210:213], v[8:11]
	v_mfma_f32_16x16x32_bf16 v[4:7], v[174:177], v[210:213], v[4:7]
	s_barrier
	s_setprio 0
	s_add_i32 s56, s56, 2
	s_add_u32 s34, s34, 0x100
	s_addc_u32 s35, s35, 0
	s_add_u32 s54, s54, 0x100
	s_addc_u32 s55, s55, 0
	s_cmp_gt_u32 s56, 29
	s_cbranch_scc0 .LBB0_2104
	s_branch .Lpeel_post_p6
.LBB0_2104:
	s_add_u32 s26, s34, 0xfff80080
	s_addc_u32 s31, s35, -1
	s_add_i32 s57, 0, 0x10000
	s_cmp_eq_u32 s56, 28
	s_cselect_b32 s39, s17, s31
	s_cselect_b32 s38, s52, s26
	v_add_u32_e32 v149, s57, v146
	s_cselect_b32 s37, s15, s55
	s_cselect_b32 s36, s53, s54
	s_add_i32 s26, 0, 0x14000
	ds_read_b128 v[142:145], v149
	ds_read_b128 v[150:153], v149 offset:1024
	ds_read_b128 v[154:157], v149 offset:2048
	ds_read_b128 v[158:161], v149 offset:3072
	v_add_u32_e32 v149, s26, v146
	ds_read_b128 v[162:165], v149
	ds_read_b128 v[166:169], v149 offset:1024
	ds_read_b128 v[170:173], v149 offset:2048
	ds_read_b128 v[174:177], v149 offset:3072
	v_lshl_add_u64 v[178:179], s[34:35], 0, v[138:139]
	s_add_i32 m0, s43, 0xc000
	ds_read_b128 v[182:185], v148
	ds_read_b128 v[186:189], v148 offset:1024
	ds_read_b128 v[190:193], v148 offset:2048
	ds_read_b128 v[194:197], v148 offset:3072
	ds_read_b128 v[198:201], v148 offset:4096
	ds_read_b128 v[202:205], v148 offset:5120
	ds_read_b128 v[206:209], v148 offset:6144
	ds_read_b128 v[210:213], v148 offset:7168
	global_load_lds_dwordx4 v[178:179], off
	v_lshl_add_u64 v[178:179], s[34:35], 0, v[140:141]
	s_add_i32 m0, s43, 0xe000
	s_nop 0
	global_load_lds_dwordx4 v[178:179], off
	s_waitcnt vmcnt(8)
	s_waitcnt lgkmcnt(0)
	s_setprio 3
	s_barrier
; #define PG8_STAGE(bufoff, gbase, voff) do { _Pragma("unroll") for (int _i = 0; _i < 2; ++_i) \
;         __builtin_amdgcn_global_load_lds((const unsigned*)((const char*)(gbase) + (voff)[_i]), (PG8_LAS unsigned*)(lds + (bufoff) + ldsw + _i * 8192), 16, 0, 0); } while (0)
; #define PG8_LDA(dst, b, h) do { _Pragma("unroll") for (int m = 0; m < 4; ++m) _Pragma("unroll") for (int k = 0; k < 2; ++k) dst[m][k] = *(const PG8_LAS bf16x8*)(lds + PG8_SA(b, h) + aoff + m * 2048 + k * 1024); } while (0)
; #define PG8_MMA(ai, bj, At, Bt) do { __builtin_amdgcn_s_setprio(1); _Pragma("unroll") for (int m = 0; m < 4; ++m) _Pragma("unroll") for (int n = 0; n < 2; ++n) _Pragma("unroll") for (int k = 0; k < 2; ++k) \
;         acc[ai][bj][m][n] = __builtin_amdgcn_mfma_f32_16x16x32_bf16(Bt[n][k], At[m][k], acc[ai][bj][m][n], 0, 0, 0); __builtin_amdgcn_s_setprio(0); } while (0)
; #define PG8_WAIT_V(n) asm volatile("s_waitcnt vmcnt(" #n ")" ::: "memory")
; #define PG8_WAIT_L(n) asm volatile("s_waitcnt lgkmcnt(" #n ")" ::: "memory")
; #define PG8_BAR __builtin_amdgcn_s_barrier()
; #define PG8_SCHED __builtin_amdgcn_sched_barrier(0)
; template <class Epi, class Sched, bool ALIGN_EPI = false, bool SP2 = false>
; __device__ __forceinline__ void gemm_phase(PG8_LAS unsigned char* lds, const Gemm g, const Sched& S, const Epi& E) {
;     ...
;             PG8_WAIT_V(8); PG8_WAIT_L(0); PG8_BAR; PG8_MMA(0, 0, At, B0); PG8_MMA(0, 1, At, B1); PG8_BAR; PG8_SCHED;
;             PG8_LDA(At, 0, 1); PG8_STAGE(PG8_SB(0, 0), b2, voffB); PG8_STAGE(PG8_SB(0, 1), b2 + hstep, voffB); PG8_STAGE(PG8_SA(0, 0), a2, voffA);
;             PG8_WAIT_V(8); PG8_WAIT_L(0); PG8_BAR; PG8_MMA(1, 0, At, B0); PG8_MMA(1, 1, At, B1); PG8_BAR; PG8_SCHED;
	v_mfma_f32_16x16x32_bf16 v[128:131], v[142:145], v[182:185], v[128:131]
	v_mfma_f32_16x16x32_bf16 v[124:127], v[154:157], v[182:185], v[124:127]
	v_mfma_f32_16x16x32_bf16 v[112:115], v[142:145], v[190:193], v[112:115]
	v_mfma_f32_16x16x32_bf16 v[108:111], v[154:157], v[190:193], v[108:111]
	v_mfma_f32_16x16x32_bf16 v[96:99], v[142:145], v[198:201], v[96:99]
	v_mfma_f32_16x16x32_bf16 v[92:95], v[154:157], v[198:201], v[92:95]
	v_mfma_f32_16x16x32_bf16 v[80:83], v[142:145], v[206:209], v[80:83]
	v_mfma_f32_16x16x32_bf16 v[76:79], v[154:157], v[206:209], v[76:79]
	v_mfma_f32_16x16x32_bf16 v[128:131], v[150:153], v[186:189], v[128:131]
	v_mfma_f32_16x16x32_bf16 v[124:127], v[158:161], v[186:189], v[124:127]
	v_mfma_f32_16x16x32_bf16 v[112:115], v[150:153], v[194:197], v[112:115]
	v_mfma_f32_16x16x32_bf16 v[108:111], v[158:161], v[194:197], v[108:111]
	v_mfma_f32_16x16x32_bf16 v[96:99], v[150:153], v[202:205], v[96:99]
	v_mfma_f32_16x16x32_bf16 v[92:95], v[158:161], v[202:205], v[92:95]
	v_mfma_f32_16x16x32_bf16 v[80:83], v[150:153], v[210:213], v[80:83]
	v_mfma_f32_16x16x32_bf16 v[76:79], v[158:161], v[210:213], v[76:79]
	s_setprio 0
	s_setprio 1
	v_mfma_f32_16x16x32_bf16 v[120:123], v[162:165], v[182:185], v[120:123]
	v_mfma_f32_16x16x32_bf16 v[116:119], v[170:173], v[182:185], v[116:119]
	v_mfma_f32_16x16x32_bf16 v[104:107], v[162:165], v[190:193], v[104:107]
	v_mfma_f32_16x16x32_bf16 v[100:103], v[170:173], v[190:193], v[100:103]
	v_mfma_f32_16x16x32_bf16 v[88:91], v[162:165], v[198:201], v[88:91]
	v_mfma_f32_16x16x32_bf16 v[84:87], v[170:173], v[198:201], v[84:87]
	v_mfma_f32_16x16x32_bf16 v[72:75], v[162:165], v[206:209], v[72:75]
	v_mfma_f32_16x16x32_bf16 v[68:71], v[170:173], v[206:209], v[68:71]
	v_mfma_f32_16x16x32_bf16 v[120:123], v[166:169], v[186:189], v[120:123]
	v_mfma_f32_16x16x32_bf16 v[116:119], v[174:177], v[186:189], v[116:119]
	v_mfma_f32_16x16x32_bf16 v[104:107], v[166:169], v[194:197], v[104:107]
	v_mfma_f32_16x16x32_bf16 v[100:103], v[174:177], v[194:197], v[100:103]
	v_mfma_f32_16x16x32_bf16 v[88:91], v[166:169], v[202:205], v[88:91]
	v_mfma_f32_16x16x32_bf16 v[84:87], v[174:177], v[202:205], v[84:87]
	v_mfma_f32_16x16x32_bf16 v[72:75], v[166:169], v[210:213], v[72:75]
	v_mfma_f32_16x16x32_bf16 v[68:71], v[174:177], v[210:213], v[68:71]
	s_barrier
	s_setprio 0
	s_add_i32 s31, s57, s42
	v_lshl_add_u64 v[178:179], s[36:37], 0, v[2:3]
	s_mov_b32 m0, s31
	ds_read_b128 v[182:185], v148 offset:16384
	ds_read_b128 v[186:189], v148 offset:17408
	ds_read_b128 v[190:193], v148 offset:18432
	ds_read_b128 v[194:197], v148 offset:19456
	ds_read_b128 v[198:201], v148 offset:20480
	ds_read_b128 v[202:205], v148 offset:21504
	ds_read_b128 v[206:209], v148 offset:22528
	ds_read_b128 v[210:213], v148 offset:23552
	global_load_lds_dwordx4 v[178:179], off
	s_add_i32 m0, s31, 0x2000
	s_add_u32 s62, s36, 0x80000
	v_lshl_add_u64 v[214:215], s[36:37], 0, v[132:133]
	s_addc_u32 s63, s37, 0
	s_add_i32 s26, s26, s42
	global_load_lds_dwordx4 v[214:215], off
	v_lshl_add_u64 v[216:217], s[62:63], 0, v[2:3]
	s_mov_b32 m0, s26
	v_lshl_add_u64 v[218:219], s[38:39], 0, v[134:135]
	global_load_lds_dwordx4 v[216:217], off
	v_lshl_add_u64 v[216:217], s[62:63], 0, v[132:133]
	s_add_i32 m0, s26, 0x2000
	s_nop 0
	global_load_lds_dwordx4 v[216:217], off
	v_lshl_add_u64 v[216:217], s[38:39], 0, v[136:137]
	s_mov_b32 m0, s43
	s_nop 0
	global_load_lds_dwordx4 v[216:217], off
	s_mov_b32 m0, s44
	s_nop 0
	global_load_lds_dwordx4 v[218:219], off
	s_waitcnt vmcnt(8)
	s_waitcnt lgkmcnt(0)
	s_setprio 3
	s_barrier
	v_mfma_f32_16x16x32_bf16 v[64:67], v[142:145], v[182:185], v[64:67]
	v_mfma_f32_16x16x32_bf16 v[60:63], v[154:157], v[182:185], v[60:63]
	v_mfma_f32_16x16x32_bf16 v[48:51], v[142:145], v[190:193], v[48:51]
	v_mfma_f32_16x16x32_bf16 v[44:47], v[154:157], v[190:193], v[44:47]
	v_mfma_f32_16x16x32_bf16 v[32:35], v[142:145], v[198:201], v[32:35]
	v_mfma_f32_16x16x32_bf16 v[28:31], v[154:157], v[198:201], v[28:31]
	v_mfma_f32_16x16x32_bf16 v[16:19], v[142:145], v[206:209], v[16:19]
	v_mfma_f32_16x16x32_bf16 v[12:15], v[154:157], v[206:209], v[12:15]
	v_mfma_f32_16x16x32_bf16 v[64:67], v[150:153], v[186:189], v[64:67]
	v_mfma_f32_16x16x32_bf16 v[60:63], v[158:161], v[186:189], v[60:63]
	v_mfma_f32_16x16x32_bf16 v[48:51], v[150:153], v[194:197], v[48:51]
	v_mfma_f32_16x16x32_bf16 v[44:47], v[158:161], v[194:197], v[44:47]
	v_mfma_f32_16x16x32_bf16 v[32:35], v[150:153], v[202:205], v[32:35]
	v_mfma_f32_16x16x32_bf16 v[28:31], v[158:161], v[202:205], v[28:31]
	v_mfma_f32_16x16x32_bf16 v[16:19], v[150:153], v[210:213], v[16:19]
	v_mfma_f32_16x16x32_bf16 v[12:15], v[158:161], v[210:213], v[12:15]
	s_setprio 0
	s_setprio 1
	v_mfma_f32_16x16x32_bf16 v[56:59], v[162:165], v[182:185], v[56:59]
	v_mfma_f32_16x16x32_bf16 v[52:55], v[170:173], v[182:185], v[52:55]
	v_mfma_f32_16x16x32_bf16 v[40:43], v[162:165], v[190:193], v[40:43]
	v_mfma_f32_16x16x32_bf16 v[36:39], v[170:173], v[190:193], v[36:39]
	v_mfma_f32_16x16x32_bf16 v[24:27], v[162:165], v[198:201], v[24:27]
	v_mfma_f32_16x16x32_bf16 v[20:23], v[170:173], v[198:201], v[20:23]
	v_mfma_f32_16x16x32_bf16 v[8:11], v[162:165], v[206:209], v[8:11]
	v_mfma_f32_16x16x32_bf16 v[4:7], v[170:173], v[206:209], v[4:7]
	v_mfma_f32_16x16x32_bf16 v[56:59], v[166:169], v[186:189], v[56:59]
	v_mfma_f32_16x16x32_bf16 v[52:55], v[174:177], v[186:189], v[52:55]
	v_mfma_f32_16x16x32_bf16 v[40:43], v[166:169], v[194:197], v[40:43]
	v_mfma_f32_16x16x32_bf16 v[36:39], v[174:177], v[194:197], v[36:39]
	v_mfma_f32_16x16x32_bf16 v[24:27], v[166:169], v[202:205], v[24:27]
	v_mfma_f32_16x16x32_bf16 v[20:23], v[174:177], v[202:205], v[20:23]
	v_mfma_f32_16x16x32_bf16 v[8:11], v[166:169], v[210:213], v[8:11]
	v_mfma_f32_16x16x32_bf16 v[4:7], v[174:177], v[210:213], v[4:7]
	s_barrier
; #define PG8_STAGE(bufoff, gbase, voff) do { _Pragma("unroll") for (int _i = 0; _i < 2; ++_i) \
;         __builtin_amdgcn_global_load_lds((const unsigned*)((const char*)(gbase) + (voff)[_i]), (PG8_LAS unsigned*)(lds + (bufoff) + ldsw + _i * 8192), 16, 0, 0); } while (0)
; #define PG8_LDA(dst, b, h) do { _Pragma("unroll") for (int m = 0; m < 4; ++m) _Pragma("unroll") for (int k = 0; k < 2; ++k) dst[m][k] = *(const PG8_LAS bf16x8*)(lds + PG8_SA(b, h) + aoff + m * 2048 + k * 1024); } while (0)
; #define PG8_LDB(dst, b, h) do { _Pragma("unroll") for (int n = 0; n < 2; ++n) _Pragma("unroll") for (int k = 0; k < 2; ++k) dst[n][k] = *(const PG8_LAS bf16x8*)(lds + PG8_SB(b, h) + boff + n * 2048 + k * 1024); } while (0)
; #define PG8_MMA(ai, bj, At, Bt) do { __builtin_amdgcn_s_setprio(1); _Pragma("unroll") for (int m = 0; m < 4; ++m) _Pragma("unroll") for (int n = 0; n < 2; ++n) _Pragma("unroll") for (int k = 0; k < 2; ++k) \
;         acc[ai][bj][m][n] = __builtin_amdgcn_mfma_f32_16x16x32_bf16(Bt[n][k], At[m][k], acc[ai][bj][m][n], 0, 0, 0); __builtin_amdgcn_s_setprio(0); } while (0)
; #define PG8_WAIT_V(n) asm volatile("s_waitcnt vmcnt(" #n ")" ::: "memory")
; #define PG8_WAIT_L(n) asm volatile("s_waitcnt lgkmcnt(" #n ")" ::: "memory")
; #define PG8_BAR __builtin_amdgcn_s_barrier()
; #define PG8_SCHED __builtin_amdgcn_sched_barrier(0)
; template <class Epi, class Sched, bool ALIGN_EPI = false, bool SP2 = false>
; __device__ __forceinline__ void gemm_phase(PG8_LAS unsigned char* lds, const Gemm g, const Sched& S, const Epi& E) {
;     ...
;             PG8_LDB(B0, 1, 0); PG8_LDB(B1, 1, 1); PG8_SCHED; PG8_LDA(At, 1, 0); PG8_STAGE(PG8_SA(0, 1), a2 + hstep, voffA);
;             PG8_WAIT_V(8); PG8_WAIT_L(0); PG8_BAR; PG8_MMA(0, 0, At, B0); PG8_MMA(0, 1, At, B1); PG8_BAR; PG8_SCHED;
	s_setprio 0
	s_add_i32 s26, 0, 0x18000
	v_add_u32_e32 v149, s26, v146
	s_add_i32 s31, 0, 0x1c000
	ds_read_b128 v[142:145], v149
	ds_read_b128 v[150:153], v149 offset:1024
	ds_read_b128 v[154:157], v149 offset:2048
	ds_read_b128 v[158:161], v149 offset:3072
	v_add_u32_e32 v149, s31, v146
	ds_read_b128 v[162:165], v149
	ds_read_b128 v[166:169], v149 offset:1024
	ds_read_b128 v[170:173], v149 offset:2048
	ds_read_b128 v[174:177], v149 offset:3072
	s_add_u32 s38, s38, 0x80000
	s_addc_u32 s39, s39, 0
	s_mov_b32 m0, s45
	v_lshl_add_u64 v[220:221], s[38:39], 0, v[136:137]
	ds_read_b128 v[182:185], v148 offset:32768
	ds_read_b128 v[186:189], v148 offset:33792
	ds_read_b128 v[190:193], v148 offset:34816
	ds_read_b128 v[194:197], v148 offset:35840
	ds_read_b128 v[198:201], v148 offset:36864
	ds_read_b128 v[202:205], v148 offset:37888
	ds_read_b128 v[206:209], v148 offset:38912
	ds_read_b128 v[210:213], v148 offset:39936
	global_load_lds_dwordx4 v[220:221], off
	v_lshl_add_u64 v[220:221], s[38:39], 0, v[134:135]
	s_mov_b32 m0, s46
	s_nop 0
	global_load_lds_dwordx4 v[220:221], off
	s_waitcnt vmcnt(8)
	s_waitcnt lgkmcnt(0)
	s_setprio 3
	s_barrier
	v_mfma_f32_16x16x32_bf16 v[128:131], v[142:145], v[182:185], v[128:131]
	v_mfma_f32_16x16x32_bf16 v[124:127], v[154:157], v[182:185], v[124:127]
	v_mfma_f32_16x16x32_bf16 v[112:115], v[142:145], v[190:193], v[112:115]
	v_mfma_f32_16x16x32_bf16 v[108:111], v[154:157], v[190:193], v[108:111]
	v_mfma_f32_16x16x32_bf16 v[96:99], v[142:145], v[198:201], v[96:99]
	v_mfma_f32_16x16x32_bf16 v[92:95], v[154:157], v[198:201], v[92:95]
	v_mfma_f32_16x16x32_bf16 v[80:83], v[142:145], v[206:209], v[80:83]
	v_mfma_f32_16x16x32_bf16 v[76:79], v[154:157], v[206:209], v[76:79]
	v_mfma_f32_16x16x32_bf16 v[128:131], v[150:153], v[186:189], v[128:131]
	v_mfma_f32_16x16x32_bf16 v[124:127], v[158:161], v[186:189], v[124:127]
	v_mfma_f32_16x16x32_bf16 v[112:115], v[150:153], v[194:197], v[112:115]
	v_mfma_f32_16x16x32_bf16 v[108:111], v[158:161], v[194:197], v[108:111]
	v_mfma_f32_16x16x32_bf16 v[96:99], v[150:153], v[202:205], v[96:99]
	v_mfma_f32_16x16x32_bf16 v[92:95], v[158:161], v[202:205], v[92:95]
	v_mfma_f32_16x16x32_bf16 v[80:83], v[150:153], v[210:213], v[80:83]
	v_mfma_f32_16x16x32_bf16 v[76:79], v[158:161], v[210:213], v[76:79]
	s_setprio 0
	s_setprio 1
	v_mfma_f32_16x16x32_bf16 v[120:123], v[162:165], v[182:185], v[120:123]
	v_mfma_f32_16x16x32_bf16 v[116:119], v[170:173], v[182:185], v[116:119]
	v_mfma_f32_16x16x32_bf16 v[104:107], v[162:165], v[190:193], v[104:107]
	v_mfma_f32_16x16x32_bf16 v[100:103], v[170:173], v[190:193], v[100:103]
	v_mfma_f32_16x16x32_bf16 v[88:91], v[162:165], v[198:201], v[88:91]
	v_mfma_f32_16x16x32_bf16 v[84:87], v[170:173], v[198:201], v[84:87]
	v_mfma_f32_16x16x32_bf16 v[72:75], v[162:165], v[206:209], v[72:75]
	v_mfma_f32_16x16x32_bf16 v[68:71], v[170:173], v[206:209], v[68:71]
	v_mfma_f32_16x16x32_bf16 v[120:123], v[166:169], v[186:189], v[120:123]
	v_mfma_f32_16x16x32_bf16 v[116:119], v[174:177], v[186:189], v[116:119]
	v_mfma_f32_16x16x32_bf16 v[104:107], v[166:169], v[194:197], v[104:107]
	v_mfma_f32_16x16x32_bf16 v[100:103], v[174:177], v[194:197], v[100:103]
	v_mfma_f32_16x16x32_bf16 v[88:91], v[166:169], v[202:205], v[88:91]
	v_mfma_f32_16x16x32_bf16 v[84:87], v[174:177], v[202:205], v[84:87]
	v_mfma_f32_16x16x32_bf16 v[72:75], v[166:169], v[210:213], v[72:75]
	v_mfma_f32_16x16x32_bf16 v[68:71], v[174:177], v[210:213], v[68:71]
	s_barrier
; #define PG8_STAGE(bufoff, gbase, voff) do { _Pragma("unroll") for (int _i = 0; _i < 2; ++_i) \
;         __builtin_amdgcn_global_load_lds((const unsigned*)((const char*)(gbase) + (voff)[_i]), (PG8_LAS unsigned*)(lds + (bufoff) + ldsw + _i * 8192), 16, 0, 0); } while (0)
; #define PG8_LDA(dst, b, h) do { _Pragma("unroll") for (int m = 0; m < 4; ++m) _Pragma("unroll") for (int k = 0; k < 2; ++k) dst[m][k] = *(const PG8_LAS bf16x8*)(lds + PG8_SA(b, h) + aoff + m * 2048 + k * 1024); } while (0)
; #define PG8_MMA(ai, bj, At, Bt) do { __builtin_amdgcn_s_setprio(1); _Pragma("unroll") for (int m = 0; m < 4; ++m) _Pragma("unroll") for (int n = 0; n < 2; ++n) _Pragma("unroll") for (int k = 0; k < 2; ++k) \
;         acc[ai][bj][m][n] = __builtin_amdgcn_mfma_f32_16x16x32_bf16(Bt[n][k], At[m][k], acc[ai][bj][m][n], 0, 0, 0); __builtin_amdgcn_s_setprio(0); } while (0)
; #define PG8_WAIT_V(n) asm volatile("s_waitcnt vmcnt(" #n ")" ::: "memory")
; #define PG8_WAIT_L(n) asm volatile("s_waitcnt lgkmcnt(" #n ")" ::: "memory")
; #define PG8_BAR __builtin_amdgcn_s_barrier()
; #define PG8_SCHED __builtin_amdgcn_sched_barrier(0)
; template <class Epi, class Sched, bool ALIGN_EPI = false, bool SP2 = false>
; __device__ __forceinline__ void gemm_phase(PG8_LAS unsigned char* lds, const Gemm g, const Sched& S, const Epi& E) {
;     ...
;             PG8_LDA(At, 1, 1); PG8_STAGE(PG8_SB(1, 0), b3, voffB); PG8_STAGE(PG8_SB(1, 1), b3 + hstep, voffB); PG8_STAGE(PG8_SA(1, 0), a3, voffA);
;             PG8_WAIT_V(8); PG8_WAIT_L(0); PG8_BAR; PG8_MMA(1, 0, At, B0); PG8_MMA(1, 1, At, B1); PG8_BAR; PG8_SCHED;
	s_setprio 0
	s_add_i32 s26, s26, s42
	v_lshl_add_u64 v[178:179], v[178:179], 0, s[60:61]
	s_mov_b32 m0, s26
	ds_read_b128 v[182:185], v148 offset:49152
	ds_read_b128 v[186:189], v148 offset:50176
	ds_read_b128 v[190:193], v148 offset:51200
	ds_read_b128 v[194:197], v148 offset:52224
	ds_read_b128 v[198:201], v148 offset:53248
	ds_read_b128 v[202:205], v148 offset:54272
	ds_read_b128 v[206:209], v148 offset:55296
	ds_read_b128 v[210:213], v148 offset:56320
	global_load_lds_dwordx4 v[178:179], off
	s_add_i32 m0, s26, 0x2000
	s_add_u32 s36, s36, 0x80080
	v_lshl_add_u64 v[178:179], v[214:215], 0, s[60:61]
	s_addc_u32 s37, s37, 0
	s_add_i32 s26, s31, s42
	global_load_lds_dwordx4 v[178:179], off
	v_lshl_add_u64 v[178:179], s[36:37], 0, v[2:3]
	s_mov_b32 m0, s26
	s_nop 0
	global_load_lds_dwordx4 v[178:179], off
	v_lshl_add_u64 v[178:179], s[36:37], 0, v[132:133]
	s_add_i32 m0, s26, 0x2000
	s_nop 0
	global_load_lds_dwordx4 v[178:179], off
	v_lshl_add_u64 v[178:179], v[216:217], 0, s[60:61]
	s_mov_b32 m0, s47
	s_nop 0
	global_load_lds_dwordx4 v[178:179], off
	v_lshl_add_u64 v[178:179], v[218:219], 0, s[60:61]
	s_mov_b32 m0, s50
	s_nop 0
	global_load_lds_dwordx4 v[178:179], off
	s_waitcnt vmcnt(8)
	s_waitcnt lgkmcnt(0)
	s_setprio 3
	s_barrier
	v_mfma_f32_16x16x32_bf16 v[64:67], v[142:145], v[182:185], v[64:67]
	v_mfma_f32_16x16x32_bf16 v[60:63], v[154:157], v[182:185], v[60:63]
	v_mfma_f32_16x16x32_bf16 v[48:51], v[142:145], v[190:193], v[48:51]
	v_mfma_f32_16x16x32_bf16 v[44:47], v[154:157], v[190:193], v[44:47]
	v_mfma_f32_16x16x32_bf16 v[32:35], v[142:145], v[198:201], v[32:35]
	v_mfma_f32_16x16x32_bf16 v[28:31], v[154:157], v[198:201], v[28:31]
	v_mfma_f32_16x16x32_bf16 v[16:19], v[142:145], v[206:209], v[16:19]
	v_mfma_f32_16x16x32_bf16 v[12:15], v[154:157], v[206:209], v[12:15]
	v_mfma_f32_16x16x32_bf16 v[64:67], v[150:153], v[186:189], v[64:67]
	v_mfma_f32_16x16x32_bf16 v[60:63], v[158:161], v[186:189], v[60:63]
	v_mfma_f32_16x16x32_bf16 v[48:51], v[150:153], v[194:197], v[48:51]
	v_mfma_f32_16x16x32_bf16 v[44:47], v[158:161], v[194:197], v[44:47]
	v_mfma_f32_16x16x32_bf16 v[32:35], v[150:153], v[202:205], v[32:35]
	v_mfma_f32_16x16x32_bf16 v[28:31], v[158:161], v[202:205], v[28:31]
	v_mfma_f32_16x16x32_bf16 v[16:19], v[150:153], v[210:213], v[16:19]
	v_mfma_f32_16x16x32_bf16 v[12:15], v[158:161], v[210:213], v[12:15]
	s_setprio 0
	s_setprio 1
	v_mfma_f32_16x16x32_bf16 v[56:59], v[162:165], v[182:185], v[56:59]
	v_mfma_f32_16x16x32_bf16 v[52:55], v[170:173], v[182:185], v[52:55]
	v_mfma_f32_16x16x32_bf16 v[40:43], v[162:165], v[190:193], v[40:43]
	v_mfma_f32_16x16x32_bf16 v[36:39], v[170:173], v[190:193], v[36:39]
	v_mfma_f32_16x16x32_bf16 v[24:27], v[162:165], v[198:201], v[24:27]
	v_mfma_f32_16x16x32_bf16 v[20:23], v[170:173], v[198:201], v[20:23]
	v_mfma_f32_16x16x32_bf16 v[8:11], v[162:165], v[206:209], v[8:11]
	v_mfma_f32_16x16x32_bf16 v[4:7], v[170:173], v[206:209], v[4:7]
	v_mfma_f32_16x16x32_bf16 v[56:59], v[166:169], v[186:189], v[56:59]
	v_mfma_f32_16x16x32_bf16 v[52:55], v[174:177], v[186:189], v[52:55]
	v_mfma_f32_16x16x32_bf16 v[40:43], v[166:169], v[194:197], v[40:43]
	v_mfma_f32_16x16x32_bf16 v[36:39], v[174:177], v[194:197], v[36:39]
	v_mfma_f32_16x16x32_bf16 v[24:27], v[166:169], v[202:205], v[24:27]
	v_mfma_f32_16x16x32_bf16 v[20:23], v[174:177], v[202:205], v[20:23]
	v_mfma_f32_16x16x32_bf16 v[8:11], v[166:169], v[210:213], v[8:11]
	v_mfma_f32_16x16x32_bf16 v[4:7], v[174:177], v[210:213], v[4:7]
	s_barrier
	s_setprio 0
	s_add_i32 s56, s56, 2
	s_add_u32 s34, s34, 0x100
	s_addc_u32 s35, s35, 0
	s_add_u32 s54, s54, 0x100
	s_addc_u32 s55, s55, 0
	s_cmp_gt_u32 s56, 29
	s_cbranch_scc0 .LBB0_2104

; #define PG8_STAGE(bufoff, gbase, voff) do { _Pragma("unroll") for (int _i = 0; _i < 2; ++_i) \
;         __builtin_amdgcn_global_load_lds((const unsigned*)((const char*)(gbase) + (voff)[_i]), (PG8_LAS unsigned*)(lds + (bufoff) + ldsw + _i * 8192), 16, 0, 0); } while (0)
; #define PG8_LDA(dst, b, h) do { _Pragma("unroll") for (int m = 0; m < 4; ++m) _Pragma("unroll") for (int k = 0; k < 2; ++k) dst[m][k] = *(const PG8_LAS bf16x8*)(lds + PG8_SA(b, h) + aoff + m * 2048 + k * 1024); } while (0)
; #define PG8_LDB(dst, b, h) do { _Pragma("unroll") for (int n = 0; n < 2; ++n) _Pragma("unroll") for (int k = 0; k < 2; ++k) dst[n][k] = *(const PG8_LAS bf16x8*)(lds + PG8_SB(b, h) + boff + n * 2048 + k * 1024); } while (0)
; #define PG8_WAIT_V(n) asm volatile("s_waitcnt vmcnt(" #n ")" ::: "memory")
; #define PG8_WAIT_L(n) asm volatile("s_waitcnt lgkmcnt(" #n ")" ::: "memory")
; #define PG8_BAR __builtin_amdgcn_s_barrier()
; #define PG8_SCHED __builtin_amdgcn_sched_barrier(0)
; template <class Epi, class Sched, bool ALIGN_EPI = false, bool SP2 = false>
; __device__ __forceinline__ void gemm_phase(PG8_LAS unsigned char* lds, const Gemm g, const Sched& S, const Epi& E) {
;     ...
;         const bool has_next = S.next(ui + 1, nxt);
;         const char* nA = has_next ? (const char*)g.A + (size_t)nxt.pm * tstep : cA; const char* nB = has_next ? (const char*)g.Bt + (size_t)nxt.pn * tstep : cB;
;         for (int t = 0; t < nt; t += 2) {
;             const bool last = (t == nt - 2);
;             const char* a1 = cA + (size_t)(t + 1) * kstep;
;             const char* a2 = last ? nA : cA + (size_t)(t + 2) * kstep; const char* b2 = last ? nB : cB + (size_t)(t + 2) * kstep;
;             const char* a3 = a2 + kstep; const char* b3 = b2 + kstep;
;             if (last && has_next) S.a_ready(nxt);
;             if constexpr (SP2) {
;             PG8_LDB(B0, 0, 0); PG8_LDB(B1, 0, 1); PG8_SCHED; PG8_LDA(At, 0, 0); PG8_STAGE(PG8_SA(1, 1), a1 + hstep, voffA);
;             PG8_WAIT_V(8); PG8_WAIT_L(0); PG8_BAR; PG8_MMA(0, 0, At, B0); PG8_MMA(0, 1, At, B1); PG8_BAR; PG8_SCHED;
;             PG8_LDA(At, 0, 1); PG8_STAGE(PG8_SB(0, 0), b2, voffB); PG8_STAGE(PG8_SB(0, 1), b2 + hstep, voffB); PG8_STAGE(PG8_SA(0, 0), a2, voffA);
;             PG8_WAIT_V(8); PG8_WAIT_L(0); PG8_BAR; PG8_MMA(1, 0, At, B0); PG8_MMA(1, 1, At, B1); PG8_BAR; PG8_SCHED;
.LBB0_2175:
	s_ashr_i32 s37, s36, 31
	s_lshl_b64 s[38:39], s[36:37], 22
	s_add_u32 s38, s2, s38
	s_addc_u32 s39, s3, s39
	s_and_b64 s[42:43], s[4:5], exec
	s_cselect_b32 s30, s39, s7
	s_cselect_b32 s37, s38, s6
	s_ashr_i32 s35, s34, 31
	s_lshl_b64 s[42:43], s[34:35], 22
	s_add_u32 s42, s29, s42
	s_addc_u32 s43, s40, s43
	s_and_b64 s[46:47], s[4:5], exec
	s_cselect_b32 s35, s43, s45
	s_cselect_b32 s64, s42, s44
	s_add_u32 s6, s6, 0x200080
	s_addc_u32 s7, s7, 0
	s_add_u32 s66, s44, 0x100
	s_addc_u32 s70, s45, 0
	s_mov_b32 s74, -2
	s_waitcnt lgkmcnt(0)
	s_add_u32 s26, s6, 0xffe00080
	s_addc_u32 s31, s7, -1
	s_add_i32 s67, 0, 0x10000
	s_cmpk_eq_i32 s74, 0x7c
	s_cselect_b32 s47, s30, s31
	s_cselect_b32 s46, s37, s26
	s_cselect_b32 s45, s35, s70
	s_cselect_b32 s44, s64, s66
	s_add_i32 s26, 0, 0x14000
	v_add_u32_e32 v144, s67, v181
	v_add_u32_e32 v170, s26, v181
	ds_read_b128 v[124:127], v144
	ds_read_b128 v[136:139], v144 offset:1024
	ds_read_b128 v[140:143], v144 offset:2048
	ds_read_b128 v[144:147], v144 offset:3072
	ds_read_b128 v[148:151], v170
	ds_read_b128 v[152:155], v170 offset:1024
	ds_read_b128 v[156:159], v170 offset:2048
	ds_read_b128 v[170:173], v170 offset:3072
	v_lshl_add_u64 v[178:179], s[6:7], 0, v[166:167]
	s_add_i32 m0, s51, 0xc000
	ds_read_b128 v[174:177], v183
	ds_read_b128 v[184:187], v183 offset:1024
	ds_read_b128 v[188:191], v183 offset:2048
	ds_read_b128 v[192:195], v183 offset:3072
	ds_read_b128 v[196:199], v183 offset:4096
	ds_read_b128 v[200:203], v183 offset:5120
	ds_read_b128 v[204:207], v183 offset:6144
	ds_read_b128 v[208:211], v183 offset:7168
	global_load_lds_dwordx4 v[178:179], off
	v_lshl_add_u64 v[178:179], s[6:7], 0, v[168:169]
	s_add_i32 m0, s51, 0xe000
	s_nop 0
	global_load_lds_dwordx4 v[178:179], off
	s_waitcnt vmcnt(8)
	s_waitcnt lgkmcnt(0)
	s_setprio 3
	s_barrier
	v_mfma_f32_16x16x32_bf16 v[132:135], v[124:127], v[174:177], 0
	v_mfma_f32_16x16x32_bf16 v[128:131], v[140:143], v[174:177], 0
	v_mfma_f32_16x16x32_bf16 v[112:115], v[124:127], v[188:191], 0
	v_mfma_f32_16x16x32_bf16 v[108:111], v[140:143], v[188:191], 0
	v_mfma_f32_16x16x32_bf16 v[96:99], v[124:127], v[196:199], 0
	v_mfma_f32_16x16x32_bf16 v[92:95], v[140:143], v[196:199], 0
	v_mfma_f32_16x16x32_bf16 v[80:83], v[124:127], v[204:207], 0
	v_mfma_f32_16x16x32_bf16 v[76:79], v[140:143], v[204:207], 0
	v_mfma_f32_16x16x32_bf16 v[132:135], v[136:139], v[184:187], v[132:135]
	v_mfma_f32_16x16x32_bf16 v[128:131], v[144:147], v[184:187], v[128:131]
	v_mfma_f32_16x16x32_bf16 v[112:115], v[136:139], v[192:195], v[112:115]
	v_mfma_f32_16x16x32_bf16 v[108:111], v[144:147], v[192:195], v[108:111]
	v_mfma_f32_16x16x32_bf16 v[96:99], v[136:139], v[200:203], v[96:99]
	v_mfma_f32_16x16x32_bf16 v[92:95], v[144:147], v[200:203], v[92:95]
	v_mfma_f32_16x16x32_bf16 v[80:83], v[136:139], v[208:211], v[80:83]
	v_mfma_f32_16x16x32_bf16 v[76:79], v[144:147], v[208:211], v[76:79]
	s_setprio 0
	s_setprio 1
	v_mfma_f32_16x16x32_bf16 v[120:123], v[148:151], v[174:177], 0
	v_mfma_f32_16x16x32_bf16 v[116:119], v[156:159], v[174:177], 0
	v_mfma_f32_16x16x32_bf16 v[104:107], v[148:151], v[188:191], 0
	v_mfma_f32_16x16x32_bf16 v[100:103], v[156:159], v[188:191], 0
	v_mfma_f32_16x16x32_bf16 v[88:91], v[148:151], v[196:199], 0
	v_mfma_f32_16x16x32_bf16 v[84:87], v[156:159], v[196:199], 0
	v_mfma_f32_16x16x32_bf16 v[72:75], v[148:151], v[204:207], 0
	v_mfma_f32_16x16x32_bf16 v[68:71], v[156:159], v[204:207], 0
	v_mfma_f32_16x16x32_bf16 v[120:123], v[152:155], v[184:187], v[120:123]
	v_mfma_f32_16x16x32_bf16 v[116:119], v[170:173], v[184:187], v[116:119]
	v_mfma_f32_16x16x32_bf16 v[104:107], v[152:155], v[192:195], v[104:107]
	v_mfma_f32_16x16x32_bf16 v[100:103], v[170:173], v[192:195], v[100:103]
	v_mfma_f32_16x16x32_bf16 v[88:91], v[152:155], v[200:203], v[88:91]
	v_mfma_f32_16x16x32_bf16 v[84:87], v[170:173], v[200:203], v[84:87]
	v_mfma_f32_16x16x32_bf16 v[72:75], v[152:155], v[208:211], v[72:75]
	v_mfma_f32_16x16x32_bf16 v[68:71], v[170:173], v[208:211], v[68:71]
	s_barrier
	s_setprio 0
	s_add_i32 s31, s67, s50
	v_lshl_add_u64 v[178:179], s[44:45], 0, v[2:3]
	s_mov_b32 m0, s31
	ds_read_b128 v[174:177], v183 offset:16384
	ds_read_b128 v[184:187], v183 offset:17408
	ds_read_b128 v[188:191], v183 offset:18432
	ds_read_b128 v[192:195], v183 offset:19456
	ds_read_b128 v[196:199], v183 offset:20480
	ds_read_b128 v[200:203], v183 offset:21504
	ds_read_b128 v[204:207], v183 offset:22528
	ds_read_b128 v[208:211], v183 offset:23552
	global_load_lds_dwordx4 v[178:179], off
	s_add_i32 m0, s31, 0x2000
	s_add_u32 s68, s44, 0x200000
	v_lshl_add_u64 v[212:213], s[44:45], 0, v[160:161]
	s_addc_u32 s69, s45, 0
	s_add_i32 s26, s26, s50
	global_load_lds_dwordx4 v[212:213], off
	v_lshl_add_u64 v[214:215], s[68:69], 0, v[2:3]
	s_mov_b32 m0, s26
	v_lshl_add_u64 v[216:217], s[46:47], 0, v[162:163]
	global_load_lds_dwordx4 v[214:215], off
	v_lshl_add_u64 v[214:215], s[68:69], 0, v[160:161]
	s_add_i32 m0, s26, 0x2000
	s_nop 0
	global_load_lds_dwordx4 v[214:215], off
	v_lshl_add_u64 v[214:215], s[46:47], 0, v[164:165]
	s_mov_b32 m0, s51
	s_nop 0
	global_load_lds_dwordx4 v[214:215], off
	s_mov_b32 m0, s52
	s_nop 0
	global_load_lds_dwordx4 v[216:217], off
	s_waitcnt vmcnt(8)
	s_waitcnt lgkmcnt(0)
	s_setprio 3
	s_barrier
; #define PG8_STAGE(bufoff, gbase, voff) do { _Pragma("unroll") for (int _i = 0; _i < 2; ++_i) \
;         __builtin_amdgcn_global_load_lds((const unsigned*)((const char*)(gbase) + (voff)[_i]), (PG8_LAS unsigned*)(lds + (bufoff) + ldsw + _i * 8192), 16, 0, 0); } while (0)
; #define PG8_LDA(dst, b, h) do { _Pragma("unroll") for (int m = 0; m < 4; ++m) _Pragma("unroll") for (int k = 0; k < 2; ++k) dst[m][k] = *(const PG8_LAS bf16x8*)(lds + PG8_SA(b, h) + aoff + m * 2048 + k * 1024); } while (0)
; #define PG8_LDB(dst, b, h) do { _Pragma("unroll") for (int n = 0; n < 2; ++n) _Pragma("unroll") for (int k = 0; k < 2; ++k) dst[n][k] = *(const PG8_LAS bf16x8*)(lds + PG8_SB(b, h) + boff + n * 2048 + k * 1024); } while (0)
; #define PG8_MMA(ai, bj, At, Bt) do { __builtin_amdgcn_s_setprio(1); _Pragma("unroll") for (int m = 0; m < 4; ++m) _Pragma("unroll") for (int n = 0; n < 2; ++n) _Pragma("unroll") for (int k = 0; k < 2; ++k) \
;         acc[ai][bj][m][n] = __builtin_amdgcn_mfma_f32_16x16x32_bf16(Bt[n][k], At[m][k], acc[ai][bj][m][n], 0, 0, 0); __builtin_amdgcn_s_setprio(0); } while (0)
; #define PG8_WAIT_V(n) asm volatile("s_waitcnt vmcnt(" #n ")" ::: "memory")
; #define PG8_WAIT_L(n) asm volatile("s_waitcnt lgkmcnt(" #n ")" ::: "memory")
; #define PG8_BAR __builtin_amdgcn_s_barrier()
; #define PG8_SCHED __builtin_amdgcn_sched_barrier(0)
; template <class Epi, class Sched, bool ALIGN_EPI = false, bool SP2 = false>
; __device__ __forceinline__ void gemm_phase(PG8_LAS unsigned char* lds, const Gemm g, const Sched& S, const Epi& E) {
;     ...
;             PG8_WAIT_V(8); PG8_WAIT_L(0); PG8_BAR; PG8_MMA(1, 0, At, B0); PG8_MMA(1, 1, At, B1); PG8_BAR; PG8_SCHED;
;             PG8_LDB(B0, 1, 0); PG8_LDB(B1, 1, 1); PG8_SCHED; PG8_LDA(At, 1, 0); PG8_STAGE(PG8_SA(0, 1), a2 + hstep, voffA);
;             PG8_WAIT_V(8); PG8_WAIT_L(0); PG8_BAR; PG8_MMA(0, 0, At, B0); PG8_MMA(0, 1, At, B1); PG8_BAR; PG8_SCHED;
	v_mfma_f32_16x16x32_bf16 v[64:67], v[124:127], v[174:177], 0
	v_mfma_f32_16x16x32_bf16 v[60:63], v[140:143], v[174:177], 0
	v_mfma_f32_16x16x32_bf16 v[48:51], v[124:127], v[188:191], 0
	v_mfma_f32_16x16x32_bf16 v[44:47], v[140:143], v[188:191], 0
	v_mfma_f32_16x16x32_bf16 v[32:35], v[124:127], v[196:199], 0
	v_mfma_f32_16x16x32_bf16 v[28:31], v[140:143], v[196:199], 0
	v_mfma_f32_16x16x32_bf16 v[16:19], v[124:127], v[204:207], 0
	v_mfma_f32_16x16x32_bf16 v[12:15], v[140:143], v[204:207], 0
	v_mfma_f32_16x16x32_bf16 v[64:67], v[136:139], v[184:187], v[64:67]
	v_mfma_f32_16x16x32_bf16 v[60:63], v[144:147], v[184:187], v[60:63]
	v_mfma_f32_16x16x32_bf16 v[48:51], v[136:139], v[192:195], v[48:51]
	v_mfma_f32_16x16x32_bf16 v[44:47], v[144:147], v[192:195], v[44:47]
	v_mfma_f32_16x16x32_bf16 v[32:35], v[136:139], v[200:203], v[32:35]
	v_mfma_f32_16x16x32_bf16 v[28:31], v[144:147], v[200:203], v[28:31]
	v_mfma_f32_16x16x32_bf16 v[16:19], v[136:139], v[208:211], v[16:19]
	v_mfma_f32_16x16x32_bf16 v[12:15], v[144:147], v[208:211], v[12:15]
	s_setprio 0
	s_setprio 1
	v_mfma_f32_16x16x32_bf16 v[56:59], v[148:151], v[174:177], 0
	v_mfma_f32_16x16x32_bf16 v[52:55], v[156:159], v[174:177], 0
	v_mfma_f32_16x16x32_bf16 v[40:43], v[148:151], v[188:191], 0
	v_mfma_f32_16x16x32_bf16 v[36:39], v[156:159], v[188:191], 0
	v_mfma_f32_16x16x32_bf16 v[24:27], v[148:151], v[196:199], 0
	v_mfma_f32_16x16x32_bf16 v[20:23], v[156:159], v[196:199], 0
	v_mfma_f32_16x16x32_bf16 v[8:11], v[148:151], v[204:207], 0
	v_mfma_f32_16x16x32_bf16 v[4:7], v[156:159], v[204:207], 0
	v_mfma_f32_16x16x32_bf16 v[56:59], v[152:155], v[184:187], v[56:59]
	v_mfma_f32_16x16x32_bf16 v[52:55], v[170:173], v[184:187], v[52:55]
	v_mfma_f32_16x16x32_bf16 v[40:43], v[152:155], v[192:195], v[40:43]
	v_mfma_f32_16x16x32_bf16 v[36:39], v[170:173], v[192:195], v[36:39]
	v_mfma_f32_16x16x32_bf16 v[24:27], v[152:155], v[200:203], v[24:27]
	v_mfma_f32_16x16x32_bf16 v[20:23], v[170:173], v[200:203], v[20:23]
	v_mfma_f32_16x16x32_bf16 v[8:11], v[152:155], v[208:211], v[8:11]
	v_mfma_f32_16x16x32_bf16 v[4:7], v[170:173], v[208:211], v[4:7]
	s_barrier
	s_setprio 0
	s_add_i32 s26, 0, 0x18000
	s_add_i32 s31, 0, 0x1c000
	v_add_u32_e32 v144, s26, v181
	v_add_u32_e32 v170, s31, v181
	ds_read_b128 v[124:127], v144
	ds_read_b128 v[136:139], v144 offset:1024
	ds_read_b128 v[140:143], v144 offset:2048
	ds_read_b128 v[144:147], v144 offset:3072
	ds_read_b128 v[148:151], v170
	ds_read_b128 v[152:155], v170 offset:1024
	ds_read_b128 v[156:159], v170 offset:2048
	ds_read_b128 v[170:173], v170 offset:3072
	s_add_u32 s46, s46, 0x200000
	s_addc_u32 s47, s47, 0
	s_mov_b32 m0, s53
	v_lshl_add_u64 v[218:219], s[46:47], 0, v[164:165]
	ds_read_b128 v[174:177], v183 offset:32768
	ds_read_b128 v[184:187], v183 offset:33792
	ds_read_b128 v[188:191], v183 offset:34816
	ds_read_b128 v[192:195], v183 offset:35840
	ds_read_b128 v[196:199], v183 offset:36864
	ds_read_b128 v[200:203], v183 offset:37888
	ds_read_b128 v[204:207], v183 offset:38912
	ds_read_b128 v[208:211], v183 offset:39936
	global_load_lds_dwordx4 v[218:219], off
	v_lshl_add_u64 v[218:219], s[46:47], 0, v[162:163]
	s_mov_b32 m0, s54
	s_nop 0
	global_load_lds_dwordx4 v[218:219], off
	s_waitcnt vmcnt(8)
	s_waitcnt lgkmcnt(0)
	s_setprio 3
	s_barrier
	v_mfma_f32_16x16x32_bf16 v[132:135], v[124:127], v[174:177], v[132:135]
	v_mfma_f32_16x16x32_bf16 v[128:131], v[140:143], v[174:177], v[128:131]
	v_mfma_f32_16x16x32_bf16 v[112:115], v[124:127], v[188:191], v[112:115]
	v_mfma_f32_16x16x32_bf16 v[108:111], v[140:143], v[188:191], v[108:111]
	v_mfma_f32_16x16x32_bf16 v[96:99], v[124:127], v[196:199], v[96:99]
	v_mfma_f32_16x16x32_bf16 v[92:95], v[140:143], v[196:199], v[92:95]
	v_mfma_f32_16x16x32_bf16 v[80:83], v[124:127], v[204:207], v[80:83]
	v_mfma_f32_16x16x32_bf16 v[76:79], v[140:143], v[204:207], v[76:79]
	v_mfma_f32_16x16x32_bf16 v[132:135], v[136:139], v[184:187], v[132:135]
	v_mfma_f32_16x16x32_bf16 v[128:131], v[144:147], v[184:187], v[128:131]
	v_mfma_f32_16x16x32_bf16 v[112:115], v[136:139], v[192:195], v[112:115]
	v_mfma_f32_16x16x32_bf16 v[108:111], v[144:147], v[192:195], v[108:111]
	v_mfma_f32_16x16x32_bf16 v[96:99], v[136:139], v[200:203], v[96:99]
	v_mfma_f32_16x16x32_bf16 v[92:95], v[144:147], v[200:203], v[92:95]
	v_mfma_f32_16x16x32_bf16 v[80:83], v[136:139], v[208:211], v[80:83]
	v_mfma_f32_16x16x32_bf16 v[76:79], v[144:147], v[208:211], v[76:79]
	s_setprio 0
	s_setprio 1
	v_mfma_f32_16x16x32_bf16 v[120:123], v[148:151], v[174:177], v[120:123]
	v_mfma_f32_16x16x32_bf16 v[116:119], v[156:159], v[174:177], v[116:119]
	v_mfma_f32_16x16x32_bf16 v[104:107], v[148:151], v[188:191], v[104:107]
	v_mfma_f32_16x16x32_bf16 v[100:103], v[156:159], v[188:191], v[100:103]
	v_mfma_f32_16x16x32_bf16 v[88:91], v[148:151], v[196:199], v[88:91]
	v_mfma_f32_16x16x32_bf16 v[84:87], v[156:159], v[196:199], v[84:87]
	v_mfma_f32_16x16x32_bf16 v[72:75], v[148:151], v[204:207], v[72:75]
	v_mfma_f32_16x16x32_bf16 v[68:71], v[156:159], v[204:207], v[68:71]
	v_mfma_f32_16x16x32_bf16 v[120:123], v[152:155], v[184:187], v[120:123]
	v_mfma_f32_16x16x32_bf16 v[116:119], v[170:173], v[184:187], v[116:119]
	v_mfma_f32_16x16x32_bf16 v[104:107], v[152:155], v[192:195], v[104:107]
	v_mfma_f32_16x16x32_bf16 v[100:103], v[170:173], v[192:195], v[100:103]
	v_mfma_f32_16x16x32_bf16 v[88:91], v[152:155], v[200:203], v[88:91]
	v_mfma_f32_16x16x32_bf16 v[84:87], v[170:173], v[200:203], v[84:87]
	v_mfma_f32_16x16x32_bf16 v[72:75], v[152:155], v[208:211], v[72:75]
	v_mfma_f32_16x16x32_bf16 v[68:71], v[170:173], v[208:211], v[68:71]
	s_barrier
; #define PG8_STAGE(bufoff, gbase, voff) do { _Pragma("unroll") for (int _i = 0; _i < 2; ++_i) \
;         __builtin_amdgcn_global_load_lds((const unsigned*)((const char*)(gbase) + (voff)[_i]), (PG8_LAS unsigned*)(lds + (bufoff) + ldsw + _i * 8192), 16, 0, 0); } while (0)
; #define PG8_LDA(dst, b, h) do { _Pragma("unroll") for (int m = 0; m < 4; ++m) _Pragma("unroll") for (int k = 0; k < 2; ++k) dst[m][k] = *(const PG8_LAS bf16x8*)(lds + PG8_SA(b, h) + aoff + m * 2048 + k * 1024); } while (0)
; #define PG8_LDB(dst, b, h) do { _Pragma("unroll") for (int n = 0; n < 2; ++n) _Pragma("unroll") for (int k = 0; k < 2; ++k) dst[n][k] = *(const PG8_LAS bf16x8*)(lds + PG8_SB(b, h) + boff + n * 2048 + k * 1024); } while (0)
; #define PG8_BAR __builtin_amdgcn_s_barrier()
; template <class Epi, class Sched, bool ALIGN_EPI = false, bool SP2 = false>
; __device__ __forceinline__ void gemm_phase(PG8_LAS unsigned char* lds, const Gemm g, const Sched& S, const Epi& E) {
;     ...
;             const bool last = (t == nt - 2);
;             const char* a1 = cA + (size_t)(t + 1) * kstep;
;             const char* a2 = last ? nA : cA + (size_t)(t + 2) * kstep; const char* b2 = last ? nB : cB + (size_t)(t + 2) * kstep;
;             const char* a3 = a2 + kstep; const char* b3 = b2 + kstep;
;             if (last && has_next) S.a_ready(nxt);
;             if constexpr (SP2) {
;             PG8_LDB(B0, 0, 0); PG8_LDB(B1, 0, 1); PG8_SCHED; PG8_LDA(At, 0, 0); PG8_STAGE(PG8_SA(1, 1), a1 + hstep, voffA);
;             PG8_WAIT_V(8); PG8_WAIT_L(0); PG8_BAR; PG8_MMA(0, 0, At, B0); PG8_MMA(0, 1, At, B1); PG8_BAR; PG8_SCHED;
;             PG8_LDA(At, 0, 1); PG8_STAGE(PG8_SB(0, 0), b2, voffB); PG8_STAGE(PG8_SB(0, 1), b2 + hstep, voffB); PG8_STAGE(PG8_SA(0, 0), a2, voffA);
;             PG8_WAIT_V(8); PG8_WAIT_L(0); PG8_BAR; PG8_MMA(1, 0, At, B0); PG8_MMA(1, 1, At, B1); PG8_BAR; PG8_SCHED;
;             PG8_LDB(B0, 1, 0); PG8_LDB(B1, 1, 1); PG8_SCHED; PG8_LDA(At, 1, 0); PG8_STAGE(PG8_SA(0, 1), a2 + hstep, voffA);
;             PG8_WAIT_V(8); PG8_WAIT_L(0); PG8_BAR; PG8_MMA(0, 0, At, B0); PG8_MMA(0, 1, At, B1); PG8_BAR; PG8_SCHED;
;             PG8_LDA(At, 1, 1); PG8_STAGE(PG8_SB(1, 0), b3, voffB); PG8_STAGE(PG8_SB(1, 1), b3 + hstep, voffB); PG8_STAGE(PG8_SA(1, 0), a3, voffA);
;             PG8_WAIT_V(8); PG8_WAIT_L(0); PG8_BAR; PG8_MMA(1, 0, At, B0); PG8_MMA(1, 1, At, B1); PG8_BAR; PG8_SCHED;
	s_setprio 0
	s_add_i32 s26, s26, s50
	v_lshl_add_u64 v[178:179], v[178:179], 0, s[60:61]
	s_mov_b32 m0, s26
	ds_read_b128 v[174:177], v183 offset:49152
	ds_read_b128 v[184:187], v183 offset:50176
	ds_read_b128 v[188:191], v183 offset:51200
	ds_read_b128 v[192:195], v183 offset:52224
	ds_read_b128 v[196:199], v183 offset:53248
	ds_read_b128 v[200:203], v183 offset:54272
	ds_read_b128 v[204:207], v183 offset:55296
	ds_read_b128 v[208:211], v183 offset:56320
	global_load_lds_dwordx4 v[178:179], off
	s_add_i32 m0, s26, 0x2000
	s_add_u32 s44, s44, 0x200080
	v_lshl_add_u64 v[178:179], v[212:213], 0, s[60:61]
	s_addc_u32 s45, s45, 0
	s_add_i32 s26, s31, s50
	global_load_lds_dwordx4 v[178:179], off
	v_lshl_add_u64 v[178:179], s[44:45], 0, v[2:3]
	s_mov_b32 m0, s26
	s_nop 0
	global_load_lds_dwordx4 v[178:179], off
	v_lshl_add_u64 v[178:179], s[44:45], 0, v[160:161]
	s_add_i32 m0, s26, 0x2000
	s_nop 0
	global_load_lds_dwordx4 v[178:179], off
	v_lshl_add_u64 v[178:179], v[214:215], 0, s[60:61]
	s_mov_b32 m0, s56
	s_nop 0
	global_load_lds_dwordx4 v[178:179], off
	v_lshl_add_u64 v[178:179], v[216:217], 0, s[60:61]
	s_mov_b32 m0, s57
	s_nop 0
	global_load_lds_dwordx4 v[178:179], off
	s_waitcnt vmcnt(8)
	s_waitcnt lgkmcnt(0)
	s_setprio 3
	s_barrier
	v_mfma_f32_16x16x32_bf16 v[64:67], v[124:127], v[174:177], v[64:67]
	v_mfma_f32_16x16x32_bf16 v[60:63], v[140:143], v[174:177], v[60:63]
	v_mfma_f32_16x16x32_bf16 v[48:51], v[124:127], v[188:191], v[48:51]
	v_mfma_f32_16x16x32_bf16 v[44:47], v[140:143], v[188:191], v[44:47]
	v_mfma_f32_16x16x32_bf16 v[32:35], v[124:127], v[196:199], v[32:35]
	v_mfma_f32_16x16x32_bf16 v[28:31], v[140:143], v[196:199], v[28:31]
	v_mfma_f32_16x16x32_bf16 v[16:19], v[124:127], v[204:207], v[16:19]
	v_mfma_f32_16x16x32_bf16 v[12:15], v[140:143], v[204:207], v[12:15]
	v_mfma_f32_16x16x32_bf16 v[64:67], v[136:139], v[184:187], v[64:67]
	v_mfma_f32_16x16x32_bf16 v[60:63], v[144:147], v[184:187], v[60:63]
	v_mfma_f32_16x16x32_bf16 v[48:51], v[136:139], v[192:195], v[48:51]
	v_mfma_f32_16x16x32_bf16 v[44:47], v[144:147], v[192:195], v[44:47]
	v_mfma_f32_16x16x32_bf16 v[32:35], v[136:139], v[200:203], v[32:35]
	v_mfma_f32_16x16x32_bf16 v[28:31], v[144:147], v[200:203], v[28:31]
	v_mfma_f32_16x16x32_bf16 v[16:19], v[136:139], v[208:211], v[16:19]
	v_mfma_f32_16x16x32_bf16 v[12:15], v[144:147], v[208:211], v[12:15]
	s_setprio 0
	s_setprio 1
	v_mfma_f32_16x16x32_bf16 v[56:59], v[148:151], v[174:177], v[56:59]
	v_mfma_f32_16x16x32_bf16 v[52:55], v[156:159], v[174:177], v[52:55]
	v_mfma_f32_16x16x32_bf16 v[40:43], v[148:151], v[188:191], v[40:43]
	v_mfma_f32_16x16x32_bf16 v[36:39], v[156:159], v[188:191], v[36:39]
	v_mfma_f32_16x16x32_bf16 v[24:27], v[148:151], v[196:199], v[24:27]
	v_mfma_f32_16x16x32_bf16 v[20:23], v[156:159], v[196:199], v[20:23]
	v_mfma_f32_16x16x32_bf16 v[8:11], v[148:151], v[204:207], v[8:11]
	v_mfma_f32_16x16x32_bf16 v[4:7], v[156:159], v[204:207], v[4:7]
	v_mfma_f32_16x16x32_bf16 v[56:59], v[152:155], v[184:187], v[56:59]
	v_mfma_f32_16x16x32_bf16 v[52:55], v[170:173], v[184:187], v[52:55]
	v_mfma_f32_16x16x32_bf16 v[40:43], v[152:155], v[192:195], v[40:43]
	v_mfma_f32_16x16x32_bf16 v[36:39], v[170:173], v[192:195], v[36:39]
	v_mfma_f32_16x16x32_bf16 v[24:27], v[152:155], v[200:203], v[24:27]
	v_mfma_f32_16x16x32_bf16 v[20:23], v[170:173], v[200:203], v[20:23]
	v_mfma_f32_16x16x32_bf16 v[8:11], v[152:155], v[208:211], v[8:11]
	v_mfma_f32_16x16x32_bf16 v[4:7], v[170:173], v[208:211], v[4:7]
	s_barrier
	s_setprio 0
	s_add_i32 s74, s74, 2
	s_add_u32 s6, s6, 0x100
	s_addc_u32 s7, s7, 0
	s_add_u32 s66, s66, 0x100
	s_addc_u32 s70, s70, 0
	s_cmpk_gt_u32 s74, 0x7d
	s_cbranch_scc0 .LBB0_2176
	s_branch .Lpeel_post_p7
.LBB0_2176:
	s_add_u32 s26, s6, 0xffe00080
	s_addc_u32 s31, s7, -1
	s_add_i32 s67, 0, 0x10000
	s_cmpk_eq_i32 s74, 0x7c
	s_cselect_b32 s47, s30, s31
	s_cselect_b32 s46, s37, s26
	s_cselect_b32 s45, s35, s70
	s_cselect_b32 s44, s64, s66
	s_add_i32 s26, 0, 0x14000
	v_add_u32_e32 v144, s67, v181
	v_add_u32_e32 v170, s26, v181
	ds_read_b128 v[124:127], v144
	ds_read_b128 v[136:139], v144 offset:1024
	ds_read_b128 v[140:143], v144 offset:2048
	ds_read_b128 v[144:147], v144 offset:3072
	ds_read_b128 v[148:151], v170
	ds_read_b128 v[152:155], v170 offset:1024
	ds_read_b128 v[156:159], v170 offset:2048
	ds_read_b128 v[170:173], v170 offset:3072
	v_lshl_add_u64 v[178:179], s[6:7], 0, v[166:167]
	s_add_i32 m0, s51, 0xc000
	ds_read_b128 v[174:177], v183
	ds_read_b128 v[184:187], v183 offset:1024
	ds_read_b128 v[188:191], v183 offset:2048
	ds_read_b128 v[192:195], v183 offset:3072
	ds_read_b128 v[196:199], v183 offset:4096
	ds_read_b128 v[200:203], v183 offset:5120
	ds_read_b128 v[204:207], v183 offset:6144
	ds_read_b128 v[208:211], v183 offset:7168
	global_load_lds_dwordx4 v[178:179], off
	v_lshl_add_u64 v[178:179], s[6:7], 0, v[168:169]
	s_add_i32 m0, s51, 0xe000
	s_nop 0
	global_load_lds_dwordx4 v[178:179], off
	s_waitcnt vmcnt(8)
	s_waitcnt lgkmcnt(0)
	s_setprio 3
	s_barrier
; #define PG8_STAGE(bufoff, gbase, voff) do { _Pragma("unroll") for (int _i = 0; _i < 2; ++_i) \
;         __builtin_amdgcn_global_load_lds((const unsigned*)((const char*)(gbase) + (voff)[_i]), (PG8_LAS unsigned*)(lds + (bufoff) + ldsw + _i * 8192), 16, 0, 0); } while (0)
; #define PG8_LDA(dst, b, h) do { _Pragma("unroll") for (int m = 0; m < 4; ++m) _Pragma("unroll") for (int k = 0; k < 2; ++k) dst[m][k] = *(const PG8_LAS bf16x8*)(lds + PG8_SA(b, h) + aoff + m * 2048 + k * 1024); } while (0)
; #define PG8_MMA(ai, bj, At, Bt) do { __builtin_amdgcn_s_setprio(1); _Pragma("unroll") for (int m = 0; m < 4; ++m) _Pragma("unroll") for (int n = 0; n < 2; ++n) _Pragma("unroll") for (int k = 0; k < 2; ++k) \
;         acc[ai][bj][m][n] = __builtin_amdgcn_mfma_f32_16x16x32_bf16(Bt[n][k], At[m][k], acc[ai][bj][m][n], 0, 0, 0); __builtin_amdgcn_s_setprio(0); } while (0)
; #define PG8_WAIT_V(n) asm volatile("s_waitcnt vmcnt(" #n ")" ::: "memory")
; #define PG8_WAIT_L(n) asm volatile("s_waitcnt lgkmcnt(" #n ")" ::: "memory")
; #define PG8_BAR __builtin_amdgcn_s_barrier()
; #define PG8_SCHED __builtin_amdgcn_sched_barrier(0)
; template <class Epi, class Sched, bool ALIGN_EPI = false, bool SP2 = false>
; __device__ __forceinline__ void gemm_phase(PG8_LAS unsigned char* lds, const Gemm g, const Sched& S, const Epi& E) {
;     ...
;             PG8_WAIT_V(8); PG8_WAIT_L(0); PG8_BAR; PG8_MMA(0, 0, At, B0); PG8_MMA(0, 1, At, B1); PG8_BAR; PG8_SCHED;
;             PG8_LDA(At, 0, 1); PG8_STAGE(PG8_SB(0, 0), b2, voffB); PG8_STAGE(PG8_SB(0, 1), b2 + hstep, voffB); PG8_STAGE(PG8_SA(0, 0), a2, voffA);
;             PG8_WAIT_V(8); PG8_WAIT_L(0); PG8_BAR; PG8_MMA(1, 0, At, B0); PG8_MMA(1, 1, At, B1); PG8_BAR; PG8_SCHED;
	v_mfma_f32_16x16x32_bf16 v[132:135], v[124:127], v[174:177], v[132:135]
	v_mfma_f32_16x16x32_bf16 v[128:131], v[140:143], v[174:177], v[128:131]
	v_mfma_f32_16x16x32_bf16 v[112:115], v[124:127], v[188:191], v[112:115]
	v_mfma_f32_16x16x32_bf16 v[108:111], v[140:143], v[188:191], v[108:111]
	v_mfma_f32_16x16x32_bf16 v[96:99], v[124:127], v[196:199], v[96:99]
	v_mfma_f32_16x16x32_bf16 v[92:95], v[140:143], v[196:199], v[92:95]
	v_mfma_f32_16x16x32_bf16 v[80:83], v[124:127], v[204:207], v[80:83]
	v_mfma_f32_16x16x32_bf16 v[76:79], v[140:143], v[204:207], v[76:79]
	v_mfma_f32_16x16x32_bf16 v[132:135], v[136:139], v[184:187], v[132:135]
	v_mfma_f32_16x16x32_bf16 v[128:131], v[144:147], v[184:187], v[128:131]
	v_mfma_f32_16x16x32_bf16 v[112:115], v[136:139], v[192:195], v[112:115]
	v_mfma_f32_16x16x32_bf16 v[108:111], v[144:147], v[192:195], v[108:111]
	v_mfma_f32_16x16x32_bf16 v[96:99], v[136:139], v[200:203], v[96:99]
	v_mfma_f32_16x16x32_bf16 v[92:95], v[144:147], v[200:203], v[92:95]
	v_mfma_f32_16x16x32_bf16 v[80:83], v[136:139], v[208:211], v[80:83]
	v_mfma_f32_16x16x32_bf16 v[76:79], v[144:147], v[208:211], v[76:79]
	s_setprio 0
	s_setprio 1
	v_mfma_f32_16x16x32_bf16 v[120:123], v[148:151], v[174:177], v[120:123]
	v_mfma_f32_16x16x32_bf16 v[116:119], v[156:159], v[174:177], v[116:119]
	v_mfma_f32_16x16x32_bf16 v[104:107], v[148:151], v[188:191], v[104:107]
	v_mfma_f32_16x16x32_bf16 v[100:103], v[156:159], v[188:191], v[100:103]
	v_mfma_f32_16x16x32_bf16 v[88:91], v[148:151], v[196:199], v[88:91]
	v_mfma_f32_16x16x32_bf16 v[84:87], v[156:159], v[196:199], v[84:87]
	v_mfma_f32_16x16x32_bf16 v[72:75], v[148:151], v[204:207], v[72:75]
	v_mfma_f32_16x16x32_bf16 v[68:71], v[156:159], v[204:207], v[68:71]
	v_mfma_f32_16x16x32_bf16 v[120:123], v[152:155], v[184:187], v[120:123]
	v_mfma_f32_16x16x32_bf16 v[116:119], v[170:173], v[184:187], v[116:119]
	v_mfma_f32_16x16x32_bf16 v[104:107], v[152:155], v[192:195], v[104:107]
	v_mfma_f32_16x16x32_bf16 v[100:103], v[170:173], v[192:195], v[100:103]
	v_mfma_f32_16x16x32_bf16 v[88:91], v[152:155], v[200:203], v[88:91]
	v_mfma_f32_16x16x32_bf16 v[84:87], v[170:173], v[200:203], v[84:87]
	v_mfma_f32_16x16x32_bf16 v[72:75], v[152:155], v[208:211], v[72:75]
	v_mfma_f32_16x16x32_bf16 v[68:71], v[170:173], v[208:211], v[68:71]
	s_barrier
	s_setprio 0
	s_add_i32 s31, s67, s50
	v_lshl_add_u64 v[178:179], s[44:45], 0, v[2:3]
	s_mov_b32 m0, s31
	ds_read_b128 v[174:177], v183 offset:16384
	ds_read_b128 v[184:187], v183 offset:17408
	ds_read_b128 v[188:191], v183 offset:18432
	ds_read_b128 v[192:195], v183 offset:19456
	ds_read_b128 v[196:199], v183 offset:20480
	ds_read_b128 v[200:203], v183 offset:21504
	ds_read_b128 v[204:207], v183 offset:22528
	ds_read_b128 v[208:211], v183 offset:23552
	global_load_lds_dwordx4 v[178:179], off
	s_add_i32 m0, s31, 0x2000
	s_add_u32 s68, s44, 0x200000
	v_lshl_add_u64 v[212:213], s[44:45], 0, v[160:161]
	s_addc_u32 s69, s45, 0
	s_add_i32 s26, s26, s50
	global_load_lds_dwordx4 v[212:213], off
	v_lshl_add_u64 v[214:215], s[68:69], 0, v[2:3]
	s_mov_b32 m0, s26
	v_lshl_add_u64 v[216:217], s[46:47], 0, v[162:163]
	global_load_lds_dwordx4 v[214:215], off
	v_lshl_add_u64 v[214:215], s[68:69], 0, v[160:161]
	s_add_i32 m0, s26, 0x2000
	s_nop 0
	global_load_lds_dwordx4 v[214:215], off
	v_lshl_add_u64 v[214:215], s[46:47], 0, v[164:165]
	s_mov_b32 m0, s51
	s_nop 0
	global_load_lds_dwordx4 v[214:215], off
	s_mov_b32 m0, s52
	s_nop 0
	global_load_lds_dwordx4 v[216:217], off
	s_waitcnt vmcnt(8)
	s_waitcnt lgkmcnt(0)
	s_setprio 3
	s_barrier
	v_mfma_f32_16x16x32_bf16 v[64:67], v[124:127], v[174:177], v[64:67]
	v_mfma_f32_16x16x32_bf16 v[60:63], v[140:143], v[174:177], v[60:63]
	v_mfma_f32_16x16x32_bf16 v[48:51], v[124:127], v[188:191], v[48:51]
	v_mfma_f32_16x16x32_bf16 v[44:47], v[140:143], v[188:191], v[44:47]
	v_mfma_f32_16x16x32_bf16 v[32:35], v[124:127], v[196:199], v[32:35]
	v_mfma_f32_16x16x32_bf16 v[28:31], v[140:143], v[196:199], v[28:31]
	v_mfma_f32_16x16x32_bf16 v[16:19], v[124:127], v[204:207], v[16:19]
	v_mfma_f32_16x16x32_bf16 v[12:15], v[140:143], v[204:207], v[12:15]
	v_mfma_f32_16x16x32_bf16 v[64:67], v[136:139], v[184:187], v[64:67]
	v_mfma_f32_16x16x32_bf16 v[60:63], v[144:147], v[184:187], v[60:63]
	v_mfma_f32_16x16x32_bf16 v[48:51], v[136:139], v[192:195], v[48:51]
	v_mfma_f32_16x16x32_bf16 v[44:47], v[144:147], v[192:195], v[44:47]
	v_mfma_f32_16x16x32_bf16 v[32:35], v[136:139], v[200:203], v[32:35]
	v_mfma_f32_16x16x32_bf16 v[28:31], v[144:147], v[200:203], v[28:31]
	v_mfma_f32_16x16x32_bf16 v[16:19], v[136:139], v[208:211], v[16:19]
	v_mfma_f32_16x16x32_bf16 v[12:15], v[144:147], v[208:211], v[12:15]
	s_setprio 0
	s_setprio 1
	v_mfma_f32_16x16x32_bf16 v[56:59], v[148:151], v[174:177], v[56:59]
	v_mfma_f32_16x16x32_bf16 v[52:55], v[156:159], v[174:177], v[52:55]
	v_mfma_f32_16x16x32_bf16 v[40:43], v[148:151], v[188:191], v[40:43]
	v_mfma_f32_16x16x32_bf16 v[36:39], v[156:159], v[188:191], v[36:39]
	v_mfma_f32_16x16x32_bf16 v[24:27], v[148:151], v[196:199], v[24:27]
	v_mfma_f32_16x16x32_bf16 v[20:23], v[156:159], v[196:199], v[20:23]
	v_mfma_f32_16x16x32_bf16 v[8:11], v[148:151], v[204:207], v[8:11]
	v_mfma_f32_16x16x32_bf16 v[4:7], v[156:159], v[204:207], v[4:7]
	v_mfma_f32_16x16x32_bf16 v[56:59], v[152:155], v[184:187], v[56:59]
	v_mfma_f32_16x16x32_bf16 v[52:55], v[170:173], v[184:187], v[52:55]
	v_mfma_f32_16x16x32_bf16 v[40:43], v[152:155], v[192:195], v[40:43]
	v_mfma_f32_16x16x32_bf16 v[36:39], v[170:173], v[192:195], v[36:39]
	v_mfma_f32_16x16x32_bf16 v[24:27], v[152:155], v[200:203], v[24:27]
	v_mfma_f32_16x16x32_bf16 v[20:23], v[170:173], v[200:203], v[20:23]
	v_mfma_f32_16x16x32_bf16 v[8:11], v[152:155], v[208:211], v[8:11]
	v_mfma_f32_16x16x32_bf16 v[4:7], v[170:173], v[208:211], v[4:7]
	s_barrier
; #define PG8_STAGE(bufoff, gbase, voff) do { _Pragma("unroll") for (int _i = 0; _i < 2; ++_i) \
;         __builtin_amdgcn_global_load_lds((const unsigned*)((const char*)(gbase) + (voff)[_i]), (PG8_LAS unsigned*)(lds + (bufoff) + ldsw + _i * 8192), 16, 0, 0); } while (0)
; #define PG8_LDA(dst, b, h) do { _Pragma("unroll") for (int m = 0; m < 4; ++m) _Pragma("unroll") for (int k = 0; k < 2; ++k) dst[m][k] = *(const PG8_LAS bf16x8*)(lds + PG8_SA(b, h) + aoff + m * 2048 + k * 1024); } while (0)
; #define PG8_LDB(dst, b, h) do { _Pragma("unroll") for (int n = 0; n < 2; ++n) _Pragma("unroll") for (int k = 0; k < 2; ++k) dst[n][k] = *(const PG8_LAS bf16x8*)(lds + PG8_SB(b, h) + boff + n * 2048 + k * 1024); } while (0)
; #define PG8_MMA(ai, bj, At, Bt) do { __builtin_amdgcn_s_setprio(1); _Pragma("unroll") for (int m = 0; m < 4; ++m) _Pragma("unroll") for (int n = 0; n < 2; ++n) _Pragma("unroll") for (int k = 0; k < 2; ++k) \
;         acc[ai][bj][m][n] = __builtin_amdgcn_mfma_f32_16x16x32_bf16(Bt[n][k], At[m][k], acc[ai][bj][m][n], 0, 0, 0); __builtin_amdgcn_s_setprio(0); } while (0)
; #define PG8_WAIT_V(n) asm volatile("s_waitcnt vmcnt(" #n ")" ::: "memory")
; #define PG8_WAIT_L(n) asm volatile("s_waitcnt lgkmcnt(" #n ")" ::: "memory")
; #define PG8_BAR __builtin_amdgcn_s_barrier()
; #define PG8_SCHED __builtin_amdgcn_sched_barrier(0)
; template <class Epi, class Sched, bool ALIGN_EPI = false, bool SP2 = false>
; __device__ __forceinline__ void gemm_phase(PG8_LAS unsigned char* lds, const Gemm g, const Sched& S, const Epi& E) {
;     ...
;             PG8_LDB(B0, 1, 0); PG8_LDB(B1, 1, 1); PG8_SCHED; PG8_LDA(At, 1, 0); PG8_STAGE(PG8_SA(0, 1), a2 + hstep, voffA);
;             PG8_WAIT_V(8); PG8_WAIT_L(0); PG8_BAR; PG8_MMA(0, 0, At, B0); PG8_MMA(0, 1, At, B1); PG8_BAR; PG8_SCHED;
	s_setprio 0
	s_add_i32 s26, 0, 0x18000
	s_add_i32 s31, 0, 0x1c000
	v_add_u32_e32 v144, s26, v181
	v_add_u32_e32 v170, s31, v181
	ds_read_b128 v[124:127], v144
	ds_read_b128 v[136:139], v144 offset:1024
	ds_read_b128 v[140:143], v144 offset:2048
	ds_read_b128 v[144:147], v144 offset:3072
	ds_read_b128 v[148:151], v170
	ds_read_b128 v[152:155], v170 offset:1024
	ds_read_b128 v[156:159], v170 offset:2048
	ds_read_b128 v[170:173], v170 offset:3072
	s_add_u32 s46, s46, 0x200000
	s_addc_u32 s47, s47, 0
	s_mov_b32 m0, s53
	v_lshl_add_u64 v[218:219], s[46:47], 0, v[164:165]
	ds_read_b128 v[174:177], v183 offset:32768
	ds_read_b128 v[184:187], v183 offset:33792
	ds_read_b128 v[188:191], v183 offset:34816
	ds_read_b128 v[192:195], v183 offset:35840
	ds_read_b128 v[196:199], v183 offset:36864
	ds_read_b128 v[200:203], v183 offset:37888
	ds_read_b128 v[204:207], v183 offset:38912
	ds_read_b128 v[208:211], v183 offset:39936
	global_load_lds_dwordx4 v[218:219], off
	v_lshl_add_u64 v[218:219], s[46:47], 0, v[162:163]
	s_mov_b32 m0, s54
	s_nop 0
	global_load_lds_dwordx4 v[218:219], off
	s_waitcnt vmcnt(8)
	s_waitcnt lgkmcnt(0)
	s_setprio 3
	s_barrier
	v_mfma_f32_16x16x32_bf16 v[132:135], v[124:127], v[174:177], v[132:135]
	v_mfma_f32_16x16x32_bf16 v[128:131], v[140:143], v[174:177], v[128:131]
	v_mfma_f32_16x16x32_bf16 v[112:115], v[124:127], v[188:191], v[112:115]
	v_mfma_f32_16x16x32_bf16 v[108:111], v[140:143], v[188:191], v[108:111]
	v_mfma_f32_16x16x32_bf16 v[96:99], v[124:127], v[196:199], v[96:99]
	v_mfma_f32_16x16x32_bf16 v[92:95], v[140:143], v[196:199], v[92:95]
	v_mfma_f32_16x16x32_bf16 v[80:83], v[124:127], v[204:207], v[80:83]
	v_mfma_f32_16x16x32_bf16 v[76:79], v[140:143], v[204:207], v[76:79]
	v_mfma_f32_16x16x32_bf16 v[132:135], v[136:139], v[184:187], v[132:135]
	v_mfma_f32_16x16x32_bf16 v[128:131], v[144:147], v[184:187], v[128:131]
	v_mfma_f32_16x16x32_bf16 v[112:115], v[136:139], v[192:195], v[112:115]
	v_mfma_f32_16x16x32_bf16 v[108:111], v[144:147], v[192:195], v[108:111]
	v_mfma_f32_16x16x32_bf16 v[96:99], v[136:139], v[200:203], v[96:99]
	v_mfma_f32_16x16x32_bf16 v[92:95], v[144:147], v[200:203], v[92:95]
	v_mfma_f32_16x16x32_bf16 v[80:83], v[136:139], v[208:211], v[80:83]
	v_mfma_f32_16x16x32_bf16 v[76:79], v[144:147], v[208:211], v[76:79]
	s_setprio 0
	s_setprio 1
	v_mfma_f32_16x16x32_bf16 v[120:123], v[148:151], v[174:177], v[120:123]
	v_mfma_f32_16x16x32_bf16 v[116:119], v[156:159], v[174:177], v[116:119]
	v_mfma_f32_16x16x32_bf16 v[104:107], v[148:151], v[188:191], v[104:107]
	v_mfma_f32_16x16x32_bf16 v[100:103], v[156:159], v[188:191], v[100:103]
	v_mfma_f32_16x16x32_bf16 v[88:91], v[148:151], v[196:199], v[88:91]
	v_mfma_f32_16x16x32_bf16 v[84:87], v[156:159], v[196:199], v[84:87]
	v_mfma_f32_16x16x32_bf16 v[72:75], v[148:151], v[204:207], v[72:75]
	v_mfma_f32_16x16x32_bf16 v[68:71], v[156:159], v[204:207], v[68:71]
	v_mfma_f32_16x16x32_bf16 v[120:123], v[152:155], v[184:187], v[120:123]
	v_mfma_f32_16x16x32_bf16 v[116:119], v[170:173], v[184:187], v[116:119]
	v_mfma_f32_16x16x32_bf16 v[104:107], v[152:155], v[192:195], v[104:107]
	v_mfma_f32_16x16x32_bf16 v[100:103], v[170:173], v[192:195], v[100:103]
	v_mfma_f32_16x16x32_bf16 v[88:91], v[152:155], v[200:203], v[88:91]
	v_mfma_f32_16x16x32_bf16 v[84:87], v[170:173], v[200:203], v[84:87]
	v_mfma_f32_16x16x32_bf16 v[72:75], v[152:155], v[208:211], v[72:75]
	v_mfma_f32_16x16x32_bf16 v[68:71], v[170:173], v[208:211], v[68:71]
	s_barrier
; #define PG8_STAGE(bufoff, gbase, voff) do { _Pragma("unroll") for (int _i = 0; _i < 2; ++_i) \
;         __builtin_amdgcn_global_load_lds((const unsigned*)((const char*)(gbase) + (voff)[_i]), (PG8_LAS unsigned*)(lds + (bufoff) + ldsw + _i * 8192), 16, 0, 0); } while (0)
; #define PG8_LDA(dst, b, h) do { _Pragma("unroll") for (int m = 0; m < 4; ++m) _Pragma("unroll") for (int k = 0; k < 2; ++k) dst[m][k] = *(const PG8_LAS bf16x8*)(lds + PG8_SA(b, h) + aoff + m * 2048 + k * 1024); } while (0)
; #define PG8_MMA(ai, bj, At, Bt) do { __builtin_amdgcn_s_setprio(1); _Pragma("unroll") for (int m = 0; m < 4; ++m) _Pragma("unroll") for (int n = 0; n < 2; ++n) _Pragma("unroll") for (int k = 0; k < 2; ++k) \
;         acc[ai][bj][m][n] = __builtin_amdgcn_mfma_f32_16x16x32_bf16(Bt[n][k], At[m][k], acc[ai][bj][m][n], 0, 0, 0); __builtin_amdgcn_s_setprio(0); } while (0)
; #define PG8_WAIT_V(n) asm volatile("s_waitcnt vmcnt(" #n ")" ::: "memory")
; #define PG8_WAIT_L(n) asm volatile("s_waitcnt lgkmcnt(" #n ")" ::: "memory")
; #define PG8_BAR __builtin_amdgcn_s_barrier()
; #define PG8_SCHED __builtin_amdgcn_sched_barrier(0)
; template <class Epi, class Sched, bool ALIGN_EPI = false, bool SP2 = false>
; __device__ __forceinline__ void gemm_phase(PG8_LAS unsigned char* lds, const Gemm g, const Sched& S, const Epi& E) {
;     ...
;             PG8_LDA(At, 1, 1); PG8_STAGE(PG8_SB(1, 0), b3, voffB); PG8_STAGE(PG8_SB(1, 1), b3 + hstep, voffB); PG8_STAGE(PG8_SA(1, 0), a3, voffA);
;             PG8_WAIT_V(8); PG8_WAIT_L(0); PG8_BAR; PG8_MMA(1, 0, At, B0); PG8_MMA(1, 1, At, B1); PG8_BAR; PG8_SCHED;
	s_setprio 0
	s_add_i32 s26, s26, s50
	v_lshl_add_u64 v[178:179], v[178:179], 0, s[60:61]
	s_mov_b32 m0, s26
	ds_read_b128 v[174:177], v183 offset:49152
	ds_read_b128 v[184:187], v183 offset:50176
	ds_read_b128 v[188:191], v183 offset:51200
	ds_read_b128 v[192:195], v183 offset:52224
	ds_read_b128 v[196:199], v183 offset:53248
	ds_read_b128 v[200:203], v183 offset:54272
	ds_read_b128 v[204:207], v183 offset:55296
	ds_read_b128 v[208:211], v183 offset:56320
	global_load_lds_dwordx4 v[178:179], off
	s_add_i32 m0, s26, 0x2000
	s_add_u32 s44, s44, 0x200080
	v_lshl_add_u64 v[178:179], v[212:213], 0, s[60:61]
	s_addc_u32 s45, s45, 0
	s_add_i32 s26, s31, s50
	global_load_lds_dwordx4 v[178:179], off
	v_lshl_add_u64 v[178:179], s[44:45], 0, v[2:3]
	s_mov_b32 m0, s26
	s_nop 0
	global_load_lds_dwordx4 v[178:179], off
	v_lshl_add_u64 v[178:179], s[44:45], 0, v[160:161]
	s_add_i32 m0, s26, 0x2000
	s_nop 0
	global_load_lds_dwordx4 v[178:179], off
	v_lshl_add_u64 v[178:179], v[214:215], 0, s[60:61]
	s_mov_b32 m0, s56
	s_nop 0
	global_load_lds_dwordx4 v[178:179], off
	v_lshl_add_u64 v[178:179], v[216:217], 0, s[60:61]
	s_mov_b32 m0, s57
	s_nop 0
	global_load_lds_dwordx4 v[178:179], off
	s_waitcnt vmcnt(8)
	s_waitcnt lgkmcnt(0)
	s_setprio 3
	s_barrier
	v_mfma_f32_16x16x32_bf16 v[64:67], v[124:127], v[174:177], v[64:67]
	v_mfma_f32_16x16x32_bf16 v[60:63], v[140:143], v[174:177], v[60:63]
	v_mfma_f32_16x16x32_bf16 v[48:51], v[124:127], v[188:191], v[48:51]
	v_mfma_f32_16x16x32_bf16 v[44:47], v[140:143], v[188:191], v[44:47]
	v_mfma_f32_16x16x32_bf16 v[32:35], v[124:127], v[196:199], v[32:35]
	v_mfma_f32_16x16x32_bf16 v[28:31], v[140:143], v[196:199], v[28:31]
	v_mfma_f32_16x16x32_bf16 v[16:19], v[124:127], v[204:207], v[16:19]
	v_mfma_f32_16x16x32_bf16 v[12:15], v[140:143], v[204:207], v[12:15]
	v_mfma_f32_16x16x32_bf16 v[64:67], v[136:139], v[184:187], v[64:67]
	v_mfma_f32_16x16x32_bf16 v[60:63], v[144:147], v[184:187], v[60:63]
	v_mfma_f32_16x16x32_bf16 v[48:51], v[136:139], v[192:195], v[48:51]
	v_mfma_f32_16x16x32_bf16 v[44:47], v[144:147], v[192:195], v[44:47]
	v_mfma_f32_16x16x32_bf16 v[32:35], v[136:139], v[200:203], v[32:35]
	v_mfma_f32_16x16x32_bf16 v[28:31], v[144:147], v[200:203], v[28:31]
	v_mfma_f32_16x16x32_bf16 v[16:19], v[136:139], v[208:211], v[16:19]
	v_mfma_f32_16x16x32_bf16 v[12:15], v[144:147], v[208:211], v[12:15]
	s_setprio 0
	s_setprio 1
	v_mfma_f32_16x16x32_bf16 v[56:59], v[148:151], v[174:177], v[56:59]
	v_mfma_f32_16x16x32_bf16 v[52:55], v[156:159], v[174:177], v[52:55]
	v_mfma_f32_16x16x32_bf16 v[40:43], v[148:151], v[188:191], v[40:43]
	v_mfma_f32_16x16x32_bf16 v[36:39], v[156:159], v[188:191], v[36:39]
	v_mfma_f32_16x16x32_bf16 v[24:27], v[148:151], v[196:199], v[24:27]
	v_mfma_f32_16x16x32_bf16 v[20:23], v[156:159], v[196:199], v[20:23]
	v_mfma_f32_16x16x32_bf16 v[8:11], v[148:151], v[204:207], v[8:11]
	v_mfma_f32_16x16x32_bf16 v[4:7], v[156:159], v[204:207], v[4:7]
	v_mfma_f32_16x16x32_bf16 v[56:59], v[152:155], v[184:187], v[56:59]
	v_mfma_f32_16x16x32_bf16 v[52:55], v[170:173], v[184:187], v[52:55]
	v_mfma_f32_16x16x32_bf16 v[40:43], v[152:155], v[192:195], v[40:43]
	v_mfma_f32_16x16x32_bf16 v[36:39], v[170:173], v[192:195], v[36:39]
	v_mfma_f32_16x16x32_bf16 v[24:27], v[152:155], v[200:203], v[24:27]
	v_mfma_f32_16x16x32_bf16 v[20:23], v[170:173], v[200:203], v[20:23]
	v_mfma_f32_16x16x32_bf16 v[8:11], v[152:155], v[208:211], v[8:11]
	v_mfma_f32_16x16x32_bf16 v[4:7], v[170:173], v[208:211], v[4:7]
	s_barrier
	s_setprio 0
	s_add_i32 s74, s74, 2
	s_add_u32 s6, s6, 0x100
	s_addc_u32 s7, s7, 0
	s_add_u32 s66, s66, 0x100
	s_addc_u32 s70, s70, 0
	s_cmpk_gt_u32 s74, 0x7d
	s_cbranch_scc0 .LBB0_2176
